# v15 + rcp trans->VALU wait-state slots filled with the next independent VALU instruction (314 s_nop removed in GEMM/skinny epilogues)
# baseline (speedup 1.0000x reference)
; DI float silu(float x) { return x / (1.f + __expf(-x)); }
; DI bf16x8 pack8(const f32x4& a, const f32x4& b) { v4u w; w.x = pk2(a[0], a[1]); w.y = pk2(a[2], a[3]); w.z = pk2(b[0], b[1]); w.w = pk2(b[2], b[3]); return __builtin_bit_cast(bf16x8, w); }
;     DI void operator()(const f32x4 (&acc)[2][2][4][2], const pg8::Unit& u, int wr, int wc, int fr, int fq) const {
;         const int ty = u.pn >> 3, cbase = (u.pn & 7) * 256 + wc * 32 + 8 * fq;
;         if (ty == 1) {
;             f32x4 lbv[2][2];
; #pragma unroll
;             for (int bj = 0; bj < 2; ++bj) { lbv[bj][0] = *(const f32x4*)(lb0 + cbase + bj * 128); lbv[bj][1] = *(const f32x4*)(lb0 + cbase + bj * 128 + 4); }
;             EPI_LOOP_BEGIN
; #pragma unroll
;                 for (int bj = 0; bj < 2; ++bj) { const size_t o = (size_t)row * D + cbase + bj * 128; f32x4 lg[2], kk[2];
; #pragma unroll
;                     for (int n = 0; n < 2; ++n)
; #pragma unroll
;                         for (int e = 0; e < 4; ++e) { const float f = fminf(fmaxf(acc[ai][bj][m][n][e], -30.f), 30.f), lb = lbv[bj][n][e], ef = __expf(-f), sg = 1.f / (1.f + ef), sgn = ef / (1.f + ef);
;                             lg[n][e] = __logf(lb + (1.f - lb) * sg); kk[n][e] = (1.f - lb) * sgn; }
;                     *(f32x4*)(lf + o) = lg[0]; *(f32x4*)(lf + o + 4) = lg[1]; *(bf16x8*)(zq + (size_t)T * D + o) = pack8(kk[0], kk[1]); }
;             EPI_LOOP_END
;         } else {
;             bf16* dst = zq + (size_t)ty * T * D;
;             EPI_LOOP_BEGIN
; #pragma unroll
;                 for (int bj = 0; bj < 2; ++bj) { const size_t o = (size_t)row * D + cbase + bj * 128; f32x4 a = acc[ai][bj][m][0], b = acc[ai][bj][m][1];
;                     if (ty != 2) {
; #pragma unroll
;                         for (int e = 0; e < 4; ++e) { a[e] = silu(a[e]); b[e] = silu(b[e]); } }
;                     *(bf16x8*)(dst + o) = pack8(a, b); }
.LBB0_233:
	s_ashr_i32 s52, s6, 3
	s_lshl_b32 s6, s6, 8
	s_and_b32 s6, s6, 0x700
	v_add_u32_e32 v160, s6, v177
	s_cmp_lg_u32 s52, 1
	s_mov_b64 s[6:7], -1
	s_cbranch_scc0 .LBB0_268
	s_cmp_lg_u32 s52, 2
	v_mov_b64_e32 v[76:77], v[136:137]
	v_mov_b64_e32 v[68:69], v[140:141]
	s_cselect_b64 s[10:11], -1, 0
	s_cmp_eq_u32 s52, 2
	v_mov_b64_e32 v[78:79], v[138:139]
	v_mov_b64_e32 v[70:71], v[142:143]
	s_cbranch_scc1 .LBB0_236
	v_mul_f32_e32 v70, 0xbfb8aa3b, v142
	v_mul_f32_e32 v71, 0xbfb8aa3b, v143
	v_exp_f32_e32 v70, v70
	v_exp_f32_e32 v71, v71
	v_mul_f32_e32 v69, 0xbfb8aa3b, v136
	v_mul_f32_e32 v68, 0xbfb8aa3b, v140
	v_exp_f32_e32 v76, v69
	v_pk_add_f32 v[70:71], v[70:71], 1.0 op_sel_hi:[1,0]
	v_mul_f32_e32 v69, 0xbfb8aa3b, v141
	v_exp_f32_e32 v68, v68
	v_exp_f32_e32 v69, v69
	v_mul_f32_e32 v78, 0xbfb8aa3b, v138
	v_rcp_f32_e32 v79, v71
	v_pk_add_f32 v[68:69], v[68:69], 1.0 op_sel_hi:[1,0]
	v_mul_f32_e32 v71, v143, v79
	v_rcp_f32_e32 v79, v70
	v_exp_f32_e32 v78, v78
	v_mul_f32_e32 v70, v142, v79
	v_rcp_f32_e32 v79, v69
	s_nop 0
	v_mul_f32_e32 v69, v141, v79
	v_mul_f32_e32 v79, 0xbfb8aa3b, v139
	v_exp_f32_e32 v79, v79
	s_nop 0
	v_pk_add_f32 v[78:79], v[78:79], 1.0 op_sel_hi:[1,0]
	v_rcp_f32_e32 v80, v68
	v_mul_f32_e32 v77, 0xbfb8aa3b, v137
	v_mul_f32_e32 v68, v140, v80
	v_exp_f32_e32 v77, v77
	v_rcp_f32_e32 v80, v79
	v_pk_add_f32 v[76:77], v[76:77], 1.0 op_sel_hi:[1,0]
	v_mul_f32_e32 v79, v139, v80
	v_rcp_f32_e32 v80, v78
	s_nop 0
	v_mul_f32_e32 v78, v138, v80
	v_rcp_f32_e32 v80, v77
	s_nop 0
	v_mul_f32_e32 v77, v137, v80
	v_rcp_f32_e32 v80, v76
	s_nop 0
	v_mul_f32_e32 v76, v136, v80
.LBB0_236:
	s_ashr_i32 s53, s52, 31
	s_lshl_b64 s[6:7], s[52:53], 25
	s_add_u32 s6, s60, s6
	s_addc_u32 s7, s61, s7
	s_lshl_b32 s9, s8, 8
	v_add_u32_e32 v82, s9, v175
	v_ashrrev_i32_e32 v161, 31, v160
	v_ashrrev_i32_e32 v83, 31, v82
	v_lshl_add_u64 v[80:81], v[160:161], 1, s[6:7]
	v_lshlrev_b64 v[82:83], 12, v[82:83]
	v_lshl_add_u64 v[82:83], v[80:81], 0, v[82:83]
	v_cvt_pk_bf16_f32 v68, v68, v69
	v_cvt_pk_bf16_f32 v69, v70, v71
	v_cvt_pk_bf16_f32 v70, v76, v77
	v_cvt_pk_bf16_f32 v71, v78, v79
	global_store_dwordx4 v[82:83], v[68:71], off
	v_mov_b64_e32 v[76:77], v[128:129]
	s_andn2_b64 vcc, exec, s[10:11]
	v_cndmask_b32_e64 v68, 0, 1, s[10:11]
	v_cmp_ne_u32_e64 s[6:7], 1, v68
	v_mov_b64_e32 v[68:69], v[132:133]
	v_mov_b64_e32 v[78:79], v[130:131]
	v_mov_b64_e32 v[70:71], v[134:135]
	s_cbranch_vccnz .LBB0_238
	v_mul_f32_e32 v70, 0xbfb8aa3b, v134
	v_mul_f32_e32 v71, 0xbfb8aa3b, v135
	v_exp_f32_e32 v70, v70
	v_exp_f32_e32 v71, v71
	v_mul_f32_e32 v69, 0xbfb8aa3b, v128
	v_mul_f32_e32 v68, 0xbfb8aa3b, v132
	v_exp_f32_e32 v76, v69
	v_pk_add_f32 v[70:71], v[70:71], 1.0 op_sel_hi:[1,0]
	v_mul_f32_e32 v69, 0xbfb8aa3b, v133
	v_exp_f32_e32 v68, v68
	v_exp_f32_e32 v69, v69
	v_mul_f32_e32 v78, 0xbfb8aa3b, v130
	v_rcp_f32_e32 v79, v71
	v_pk_add_f32 v[68:69], v[68:69], 1.0 op_sel_hi:[1,0]
	v_mul_f32_e32 v71, v135, v79
	v_rcp_f32_e32 v79, v70
	v_exp_f32_e32 v78, v78
	v_mul_f32_e32 v70, v134, v79
	v_rcp_f32_e32 v79, v69
	s_nop 0
	v_mul_f32_e32 v69, v133, v79
	v_mul_f32_e32 v79, 0xbfb8aa3b, v131
	v_exp_f32_e32 v79, v79
	s_nop 0
	v_pk_add_f32 v[78:79], v[78:79], 1.0 op_sel_hi:[1,0]
	v_rcp_f32_e32 v88, v68
	v_mul_f32_e32 v77, 0xbfb8aa3b, v129
	v_mul_f32_e32 v68, v132, v88
	v_exp_f32_e32 v77, v77
	v_rcp_f32_e32 v88, v79
	v_pk_add_f32 v[76:77], v[76:77], 1.0 op_sel_hi:[1,0]
	v_mul_f32_e32 v79, v131, v88
	v_rcp_f32_e32 v88, v78
	s_nop 0
	v_mul_f32_e32 v78, v130, v88
	v_rcp_f32_e32 v88, v77
	s_nop 0
	v_mul_f32_e32 v77, v129, v88
	v_rcp_f32_e32 v88, v76
	s_nop 0
	v_mul_f32_e32 v76, v128, v88
.LBB0_238:
	v_cvt_pk_bf16_f32 v68, v68, v69
	v_cvt_pk_bf16_f32 v69, v70, v71
	v_cvt_pk_bf16_f32 v70, v76, v77
	v_cvt_pk_bf16_f32 v71, v78, v79
	global_store_dwordx4 v[82:83], v[68:71], off offset:256
	v_mov_b64_e32 v[76:77], v[120:121]
	s_and_b64 vcc, exec, s[6:7]
	v_mov_b64_e32 v[68:69], v[124:125]
	v_mov_b64_e32 v[78:79], v[122:123]
	v_mov_b64_e32 v[70:71], v[126:127]
	s_cbranch_vccnz .LBB0_240
	v_mul_f32_e32 v70, 0xbfb8aa3b, v126
	v_mul_f32_e32 v71, 0xbfb8aa3b, v127
	v_exp_f32_e32 v70, v70
	v_exp_f32_e32 v71, v71
	v_mul_f32_e32 v69, 0xbfb8aa3b, v120
	v_mul_f32_e32 v68, 0xbfb8aa3b, v124
	v_exp_f32_e32 v76, v69
	v_pk_add_f32 v[70:71], v[70:71], 1.0 op_sel_hi:[1,0]
	v_mul_f32_e32 v69, 0xbfb8aa3b, v125
	v_exp_f32_e32 v68, v68
	v_exp_f32_e32 v69, v69
	v_mul_f32_e32 v78, 0xbfb8aa3b, v122
	v_rcp_f32_e32 v79, v71
	v_pk_add_f32 v[68:69], v[68:69], 1.0 op_sel_hi:[1,0]
	v_mul_f32_e32 v71, v127, v79
	v_rcp_f32_e32 v79, v70
	v_exp_f32_e32 v78, v78
	v_mul_f32_e32 v70, v126, v79
	v_rcp_f32_e32 v79, v69
	s_nop 0
	v_mul_f32_e32 v69, v125, v79
	v_mul_f32_e32 v79, 0xbfb8aa3b, v123
	v_exp_f32_e32 v79, v79
	s_nop 0
	v_pk_add_f32 v[78:79], v[78:79], 1.0 op_sel_hi:[1,0]
	v_rcp_f32_e32 v82, v68
	v_mul_f32_e32 v77, 0xbfb8aa3b, v121
	v_mul_f32_e32 v68, v124, v82
	v_exp_f32_e32 v77, v77
	v_rcp_f32_e32 v82, v79
	v_pk_add_f32 v[76:77], v[76:77], 1.0 op_sel_hi:[1,0]
	v_mul_f32_e32 v79, v123, v82
	v_rcp_f32_e32 v82, v78
	s_nop 0
	v_mul_f32_e32 v78, v122, v82
	v_rcp_f32_e32 v82, v77
	s_nop 0
	v_mul_f32_e32 v77, v121, v82
	v_rcp_f32_e32 v82, v76
	s_nop 0
	v_mul_f32_e32 v76, v120, v82
; DI bf16x8 pack8(const f32x4& a, const f32x4& b) { v4u w; w.x = pk2(a[0], a[1]); w.y = pk2(a[2], a[3]); w.z = pk2(b[0], b[1]); w.w = pk2(b[2], b[3]); return __builtin_bit_cast(bf16x8, w); }
; DI float silu(float x) { return x / (1.f + __expf(-x)); }
;     DI void operator()(const f32x4 (&acc)[2][2][4][2], const pg8::Unit& u, int wr, int wc, int fr, int fq) const {
;     ...
;             bf16* dst = zq + (size_t)ty * T * D;
;             EPI_LOOP_BEGIN
; #pragma unroll
;                 for (int bj = 0; bj < 2; ++bj) { const size_t o = (size_t)row * D + cbase + bj * 128; f32x4 a = acc[ai][bj][m][0], b = acc[ai][bj][m][1];
;                     if (ty != 2) {
; #pragma unroll
;                         for (int e = 0; e < 4; ++e) { a[e] = silu(a[e]); b[e] = silu(b[e]); } }
;                     *(bf16x8*)(dst + o) = pack8(a, b); }
.LBB0_240:
	v_add_u32_e32 v82, s9, v178
	v_ashrrev_i32_e32 v83, 31, v82
	v_lshlrev_b64 v[82:83], 12, v[82:83]
	v_lshl_add_u64 v[82:83], v[80:81], 0, v[82:83]
	v_cvt_pk_bf16_f32 v68, v68, v69
	v_cvt_pk_bf16_f32 v69, v70, v71
	v_cvt_pk_bf16_f32 v70, v76, v77
	v_cvt_pk_bf16_f32 v71, v78, v79
	global_store_dwordx4 v[82:83], v[68:71], off
	v_mov_b64_e32 v[76:77], v[112:113]
	s_and_b64 vcc, exec, s[6:7]
	v_mov_b64_e32 v[68:69], v[116:117]
	v_mov_b64_e32 v[78:79], v[114:115]
	v_mov_b64_e32 v[70:71], v[118:119]
	s_cbranch_vccnz .LBB0_242
	v_mul_f32_e32 v70, 0xbfb8aa3b, v118
	v_mul_f32_e32 v71, 0xbfb8aa3b, v119
	v_exp_f32_e32 v70, v70
	v_exp_f32_e32 v71, v71
	v_mul_f32_e32 v69, 0xbfb8aa3b, v112
	v_mul_f32_e32 v68, 0xbfb8aa3b, v116
	v_exp_f32_e32 v76, v69
	v_pk_add_f32 v[70:71], v[70:71], 1.0 op_sel_hi:[1,0]
	v_mul_f32_e32 v69, 0xbfb8aa3b, v117
	v_exp_f32_e32 v68, v68
	v_exp_f32_e32 v69, v69
	v_mul_f32_e32 v78, 0xbfb8aa3b, v114
	v_rcp_f32_e32 v79, v71
	v_pk_add_f32 v[68:69], v[68:69], 1.0 op_sel_hi:[1,0]
	v_mul_f32_e32 v71, v119, v79
	v_rcp_f32_e32 v79, v70
	v_exp_f32_e32 v78, v78
	v_mul_f32_e32 v70, v118, v79
	v_rcp_f32_e32 v79, v69
	s_nop 0
	v_mul_f32_e32 v69, v117, v79
	v_mul_f32_e32 v79, 0xbfb8aa3b, v115
	v_exp_f32_e32 v79, v79
	s_nop 0
	v_pk_add_f32 v[78:79], v[78:79], 1.0 op_sel_hi:[1,0]
	v_rcp_f32_e32 v88, v68
	v_mul_f32_e32 v77, 0xbfb8aa3b, v113
	v_mul_f32_e32 v68, v116, v88
	v_exp_f32_e32 v77, v77
	v_rcp_f32_e32 v88, v79
	v_pk_add_f32 v[76:77], v[76:77], 1.0 op_sel_hi:[1,0]
	v_mul_f32_e32 v79, v115, v88
	v_rcp_f32_e32 v88, v78
	s_nop 0
	v_mul_f32_e32 v78, v114, v88
	v_rcp_f32_e32 v88, v77
	s_nop 0
	v_mul_f32_e32 v77, v113, v88
	v_rcp_f32_e32 v88, v76
	s_nop 0
	v_mul_f32_e32 v76, v112, v88
.LBB0_242:
	v_cvt_pk_bf16_f32 v68, v68, v69
	v_cvt_pk_bf16_f32 v69, v70, v71
	v_cvt_pk_bf16_f32 v70, v76, v77
	v_cvt_pk_bf16_f32 v71, v78, v79
	global_store_dwordx4 v[82:83], v[68:71], off offset:256
	v_mov_b64_e32 v[76:77], v[104:105]
	s_and_b64 vcc, exec, s[6:7]
	v_mov_b64_e32 v[68:69], v[108:109]
	v_mov_b64_e32 v[78:79], v[106:107]
	v_mov_b64_e32 v[70:71], v[110:111]
	s_cbranch_vccnz .LBB0_244
	v_mul_f32_e32 v70, 0xbfb8aa3b, v110
	v_mul_f32_e32 v71, 0xbfb8aa3b, v111
	v_exp_f32_e32 v70, v70
	v_exp_f32_e32 v71, v71
	v_mul_f32_e32 v69, 0xbfb8aa3b, v104
	v_mul_f32_e32 v68, 0xbfb8aa3b, v108
	v_exp_f32_e32 v76, v69
	v_pk_add_f32 v[70:71], v[70:71], 1.0 op_sel_hi:[1,0]
	v_mul_f32_e32 v69, 0xbfb8aa3b, v109
	v_exp_f32_e32 v68, v68
	v_exp_f32_e32 v69, v69
	v_mul_f32_e32 v78, 0xbfb8aa3b, v106
	v_rcp_f32_e32 v79, v71
	v_pk_add_f32 v[68:69], v[68:69], 1.0 op_sel_hi:[1,0]
	v_mul_f32_e32 v71, v111, v79
	v_rcp_f32_e32 v79, v70
	v_exp_f32_e32 v78, v78
	v_mul_f32_e32 v70, v110, v79
	v_rcp_f32_e32 v79, v69
	s_nop 0
	v_mul_f32_e32 v69, v109, v79
	v_mul_f32_e32 v79, 0xbfb8aa3b, v107
	v_exp_f32_e32 v79, v79
	s_nop 0
	v_pk_add_f32 v[78:79], v[78:79], 1.0 op_sel_hi:[1,0]
	v_rcp_f32_e32 v82, v68
	v_mul_f32_e32 v77, 0xbfb8aa3b, v105
	v_mul_f32_e32 v68, v108, v82
	v_exp_f32_e32 v77, v77
	v_rcp_f32_e32 v82, v79
	v_pk_add_f32 v[76:77], v[76:77], 1.0 op_sel_hi:[1,0]
	v_mul_f32_e32 v79, v107, v82
	v_rcp_f32_e32 v82, v78
	s_nop 0
	v_mul_f32_e32 v78, v106, v82
	v_rcp_f32_e32 v82, v77
	s_nop 0
	v_mul_f32_e32 v77, v105, v82
	v_rcp_f32_e32 v82, v76
	s_nop 0
	v_mul_f32_e32 v76, v104, v82
.LBB0_244:
	v_add_u32_e32 v82, s9, v179
	v_ashrrev_i32_e32 v83, 31, v82
	v_lshlrev_b64 v[82:83], 12, v[82:83]
	v_lshl_add_u64 v[82:83], v[80:81], 0, v[82:83]
	v_cvt_pk_bf16_f32 v68, v68, v69
	v_cvt_pk_bf16_f32 v69, v70, v71
	v_cvt_pk_bf16_f32 v70, v76, v77
	v_cvt_pk_bf16_f32 v71, v78, v79
	global_store_dwordx4 v[82:83], v[68:71], off
	v_mov_b64_e32 v[76:77], v[96:97]
	s_and_b64 vcc, exec, s[6:7]
	v_mov_b64_e32 v[68:69], v[100:101]
	v_mov_b64_e32 v[78:79], v[98:99]
	v_mov_b64_e32 v[70:71], v[102:103]
	s_cbranch_vccnz .LBB0_246
	v_mul_f32_e32 v70, 0xbfb8aa3b, v102
	v_mul_f32_e32 v71, 0xbfb8aa3b, v103
	v_exp_f32_e32 v70, v70
	v_exp_f32_e32 v71, v71
	v_mul_f32_e32 v69, 0xbfb8aa3b, v96
	v_mul_f32_e32 v68, 0xbfb8aa3b, v100
	v_exp_f32_e32 v76, v69
	v_pk_add_f32 v[70:71], v[70:71], 1.0 op_sel_hi:[1,0]
	v_mul_f32_e32 v69, 0xbfb8aa3b, v101
	v_exp_f32_e32 v68, v68
	v_exp_f32_e32 v69, v69
	v_mul_f32_e32 v78, 0xbfb8aa3b, v98
	v_rcp_f32_e32 v79, v71
	v_pk_add_f32 v[68:69], v[68:69], 1.0 op_sel_hi:[1,0]
	v_mul_f32_e32 v71, v103, v79
	v_rcp_f32_e32 v79, v70
	v_exp_f32_e32 v78, v78
	v_mul_f32_e32 v70, v102, v79
	v_rcp_f32_e32 v79, v69
	s_nop 0
	v_mul_f32_e32 v69, v101, v79
	v_mul_f32_e32 v79, 0xbfb8aa3b, v99
	v_exp_f32_e32 v79, v79
	s_nop 0
	v_pk_add_f32 v[78:79], v[78:79], 1.0 op_sel_hi:[1,0]
	v_rcp_f32_e32 v88, v68
	v_mul_f32_e32 v77, 0xbfb8aa3b, v97
	v_mul_f32_e32 v68, v100, v88
	v_exp_f32_e32 v77, v77
	v_rcp_f32_e32 v88, v79
	v_pk_add_f32 v[76:77], v[76:77], 1.0 op_sel_hi:[1,0]
	v_mul_f32_e32 v79, v99, v88
	v_rcp_f32_e32 v88, v78
	s_nop 0
	v_mul_f32_e32 v78, v98, v88
	v_rcp_f32_e32 v88, v77
	s_nop 0
	v_mul_f32_e32 v77, v97, v88
	v_rcp_f32_e32 v88, v76
	s_nop 0
	v_mul_f32_e32 v76, v96, v88
; DI bf16x8 pack8(const f32x4& a, const f32x4& b) { v4u w; w.x = pk2(a[0], a[1]); w.y = pk2(a[2], a[3]); w.z = pk2(b[0], b[1]); w.w = pk2(b[2], b[3]); return __builtin_bit_cast(bf16x8, w); }
; DI float silu(float x) { return x / (1.f + __expf(-x)); }
;     DI void operator()(const f32x4 (&acc)[2][2][4][2], const pg8::Unit& u, int wr, int wc, int fr, int fq) const {
;     ...
;             bf16* dst = zq + (size_t)ty * T * D;
;             EPI_LOOP_BEGIN
; #pragma unroll
;                 for (int bj = 0; bj < 2; ++bj) { const size_t o = (size_t)row * D + cbase + bj * 128; f32x4 a = acc[ai][bj][m][0], b = acc[ai][bj][m][1];
;                     if (ty != 2) {
; #pragma unroll
;                         for (int e = 0; e < 4; ++e) { a[e] = silu(a[e]); b[e] = silu(b[e]); } }
;                     *(bf16x8*)(dst + o) = pack8(a, b); }
.LBB0_246:
	v_cvt_pk_bf16_f32 v68, v68, v69
	v_cvt_pk_bf16_f32 v69, v70, v71
	v_cvt_pk_bf16_f32 v70, v76, v77
	v_cvt_pk_bf16_f32 v71, v78, v79
	global_store_dwordx4 v[82:83], v[68:71], off offset:256
	v_mov_b64_e32 v[76:77], v[84:85]
	s_and_b64 vcc, exec, s[6:7]
	v_mov_b64_e32 v[68:69], v[92:93]
	v_mov_b64_e32 v[78:79], v[86:87]
	v_mov_b64_e32 v[70:71], v[94:95]
	s_cbranch_vccnz .LBB0_248
	v_mul_f32_e32 v70, 0xbfb8aa3b, v94
	v_mul_f32_e32 v71, 0xbfb8aa3b, v95
	v_exp_f32_e32 v70, v70
	v_exp_f32_e32 v71, v71
	v_mul_f32_e32 v69, 0xbfb8aa3b, v84
	v_mul_f32_e32 v68, 0xbfb8aa3b, v92
	v_exp_f32_e32 v76, v69
	v_pk_add_f32 v[70:71], v[70:71], 1.0 op_sel_hi:[1,0]
	v_mul_f32_e32 v69, 0xbfb8aa3b, v93
	v_exp_f32_e32 v68, v68
	v_exp_f32_e32 v69, v69
	v_mul_f32_e32 v78, 0xbfb8aa3b, v86
	v_rcp_f32_e32 v79, v71
	v_pk_add_f32 v[68:69], v[68:69], 1.0 op_sel_hi:[1,0]
	v_mul_f32_e32 v71, v95, v79
	v_rcp_f32_e32 v79, v70
	v_exp_f32_e32 v78, v78
	v_mul_f32_e32 v70, v94, v79
	v_rcp_f32_e32 v79, v69
	s_nop 0
	v_mul_f32_e32 v69, v93, v79
	v_mul_f32_e32 v79, 0xbfb8aa3b, v87
	v_exp_f32_e32 v79, v79
	s_nop 0
	v_pk_add_f32 v[78:79], v[78:79], 1.0 op_sel_hi:[1,0]
	v_rcp_f32_e32 v82, v68
	v_mul_f32_e32 v77, 0xbfb8aa3b, v85
	v_mul_f32_e32 v68, v92, v82
	v_exp_f32_e32 v77, v77
	v_rcp_f32_e32 v82, v79
	v_pk_add_f32 v[76:77], v[76:77], 1.0 op_sel_hi:[1,0]
	v_mul_f32_e32 v79, v87, v82
	v_rcp_f32_e32 v82, v78
	s_nop 0
	v_mul_f32_e32 v78, v86, v82
	v_rcp_f32_e32 v82, v77
	s_nop 0
	v_mul_f32_e32 v77, v85, v82
	v_rcp_f32_e32 v82, v76
	s_nop 0
	v_mul_f32_e32 v76, v84, v82
.LBB0_248:
	v_add_u32_e32 v82, s9, v180
	v_ashrrev_i32_e32 v83, 31, v82
	v_lshlrev_b64 v[82:83], 12, v[82:83]
	v_lshl_add_u64 v[82:83], v[80:81], 0, v[82:83]
	v_cvt_pk_bf16_f32 v68, v68, v69
	v_cvt_pk_bf16_f32 v69, v70, v71
	v_cvt_pk_bf16_f32 v70, v76, v77
	v_cvt_pk_bf16_f32 v71, v78, v79
	global_store_dwordx4 v[82:83], v[68:71], off
	v_mov_b64_e32 v[78:79], v[66:67]
	s_and_b64 vcc, exec, s[6:7]
	v_mov_b64_e32 v[68:69], v[72:73]
	v_mov_b64_e32 v[76:77], v[64:65]
	v_mov_b64_e32 v[70:71], v[74:75]
	s_cbranch_vccnz .LBB0_250
	v_mul_f32_e32 v70, 0xbfb8aa3b, v74
	v_mul_f32_e32 v71, 0xbfb8aa3b, v75
	v_exp_f32_e32 v70, v70
	v_exp_f32_e32 v71, v71
	v_mul_f32_e32 v69, 0xbfb8aa3b, v64
	v_mul_f32_e32 v68, 0xbfb8aa3b, v72
	v_exp_f32_e32 v76, v69
	v_pk_add_f32 v[70:71], v[70:71], 1.0 op_sel_hi:[1,0]
	v_mul_f32_e32 v69, 0xbfb8aa3b, v73
	v_exp_f32_e32 v68, v68
	v_exp_f32_e32 v69, v69
	v_mul_f32_e32 v78, 0xbfb8aa3b, v66
	v_rcp_f32_e32 v79, v71
	v_pk_add_f32 v[68:69], v[68:69], 1.0 op_sel_hi:[1,0]
	v_mul_f32_e32 v71, v75, v79
	v_rcp_f32_e32 v79, v70
	v_exp_f32_e32 v78, v78
	v_mul_f32_e32 v70, v74, v79
	v_rcp_f32_e32 v79, v69
	s_nop 0
	v_mul_f32_e32 v69, v73, v79
	v_mul_f32_e32 v79, 0xbfb8aa3b, v67
	v_exp_f32_e32 v79, v79
	s_nop 0
	v_pk_add_f32 v[78:79], v[78:79], 1.0 op_sel_hi:[1,0]
	v_rcp_f32_e32 v88, v68
	v_mul_f32_e32 v77, 0xbfb8aa3b, v65
	v_mul_f32_e32 v68, v72, v88
	v_exp_f32_e32 v77, v77
	v_rcp_f32_e32 v88, v79
	v_pk_add_f32 v[76:77], v[76:77], 1.0 op_sel_hi:[1,0]
	v_mul_f32_e32 v79, v67, v88
	v_rcp_f32_e32 v88, v78
	s_nop 0
	v_mul_f32_e32 v78, v66, v88
	v_rcp_f32_e32 v88, v77
	s_nop 0
	v_mul_f32_e32 v77, v65, v88
	v_rcp_f32_e32 v88, v76
	s_nop 0
	v_mul_f32_e32 v76, v64, v88
.LBB0_250:
	v_cvt_pk_bf16_f32 v68, v68, v69
	v_cvt_pk_bf16_f32 v69, v70, v71
	v_cvt_pk_bf16_f32 v70, v76, v77
	v_cvt_pk_bf16_f32 v71, v78, v79
	global_store_dwordx4 v[82:83], v[68:71], off offset:256
	v_mov_b64_e32 v[78:79], v[58:59]
	s_and_b64 vcc, exec, s[6:7]
	v_mov_b64_e32 v[70:71], v[62:63]
	v_mov_b64_e32 v[76:77], v[56:57]
	v_mov_b64_e32 v[68:69], v[60:61]
	s_cbranch_vccnz .LBB0_252
	v_mul_f32_e32 v70, 0xbfb8aa3b, v62
	v_mul_f32_e32 v71, 0xbfb8aa3b, v63
	v_exp_f32_e32 v70, v70
	v_exp_f32_e32 v71, v71
	v_mul_f32_e32 v69, 0xbfb8aa3b, v56
	v_mul_f32_e32 v68, 0xbfb8aa3b, v60
	v_exp_f32_e32 v76, v69
	v_pk_add_f32 v[70:71], v[70:71], 1.0 op_sel_hi:[1,0]
	v_mul_f32_e32 v69, 0xbfb8aa3b, v61
	v_exp_f32_e32 v68, v68
	v_exp_f32_e32 v69, v69
	v_mul_f32_e32 v78, 0xbfb8aa3b, v58
	v_rcp_f32_e32 v79, v71
	v_pk_add_f32 v[68:69], v[68:69], 1.0 op_sel_hi:[1,0]
	v_mul_f32_e32 v71, v63, v79
	v_rcp_f32_e32 v79, v70
	v_exp_f32_e32 v78, v78
	v_mul_f32_e32 v70, v62, v79
	v_rcp_f32_e32 v79, v69
	s_nop 0
	v_mul_f32_e32 v69, v61, v79
	v_mul_f32_e32 v79, 0xbfb8aa3b, v59
	v_exp_f32_e32 v79, v79
	s_nop 0
	v_pk_add_f32 v[78:79], v[78:79], 1.0 op_sel_hi:[1,0]
	v_rcp_f32_e32 v82, v68
	v_mul_f32_e32 v77, 0xbfb8aa3b, v57
	v_mul_f32_e32 v68, v60, v82
	v_exp_f32_e32 v77, v77
	v_rcp_f32_e32 v82, v79
	v_pk_add_f32 v[76:77], v[76:77], 1.0 op_sel_hi:[1,0]
	v_mul_f32_e32 v79, v59, v82
	v_rcp_f32_e32 v82, v78
	s_nop 0
	v_mul_f32_e32 v78, v58, v82
	v_rcp_f32_e32 v82, v77
	s_nop 0
	v_mul_f32_e32 v77, v57, v82
	v_rcp_f32_e32 v82, v76
	s_nop 0
	v_mul_f32_e32 v76, v56, v82
; DI bf16x8 pack8(const f32x4& a, const f32x4& b) { v4u w; w.x = pk2(a[0], a[1]); w.y = pk2(a[2], a[3]); w.z = pk2(b[0], b[1]); w.w = pk2(b[2], b[3]); return __builtin_bit_cast(bf16x8, w); }
; DI float silu(float x) { return x / (1.f + __expf(-x)); }
;     DI void operator()(const f32x4 (&acc)[2][2][4][2], const pg8::Unit& u, int wr, int wc, int fr, int fq) const {
;     ...
;             bf16* dst = zq + (size_t)ty * T * D;
;             EPI_LOOP_BEGIN
; #pragma unroll
;                 for (int bj = 0; bj < 2; ++bj) { const size_t o = (size_t)row * D + cbase + bj * 128; f32x4 a = acc[ai][bj][m][0], b = acc[ai][bj][m][1];
;                     if (ty != 2) {
; #pragma unroll
;                         for (int e = 0; e < 4; ++e) { a[e] = silu(a[e]); b[e] = silu(b[e]); } }
;                     *(bf16x8*)(dst + o) = pack8(a, b); }
.LBB0_252:
	v_add_u32_e32 v82, s9, v181
	v_ashrrev_i32_e32 v83, 31, v82
	v_lshlrev_b64 v[82:83], 12, v[82:83]
	v_lshl_add_u64 v[82:83], v[80:81], 0, v[82:83]
	v_cvt_pk_bf16_f32 v68, v68, v69
	v_cvt_pk_bf16_f32 v69, v70, v71
	v_cvt_pk_bf16_f32 v70, v76, v77
	v_cvt_pk_bf16_f32 v71, v78, v79
	global_store_dwordx4 v[82:83], v[68:71], off
	v_mov_b64_e32 v[78:79], v[50:51]
	s_and_b64 vcc, exec, s[6:7]
	v_mov_b64_e32 v[70:71], v[54:55]
	v_mov_b64_e32 v[76:77], v[48:49]
	v_mov_b64_e32 v[68:69], v[52:53]
	s_cbranch_vccnz .LBB0_254
	v_mul_f32_e32 v70, 0xbfb8aa3b, v54
	v_mul_f32_e32 v71, 0xbfb8aa3b, v55
	v_exp_f32_e32 v70, v70
	v_exp_f32_e32 v71, v71
	v_mul_f32_e32 v69, 0xbfb8aa3b, v48
	v_mul_f32_e32 v68, 0xbfb8aa3b, v52
	v_exp_f32_e32 v76, v69
	v_pk_add_f32 v[70:71], v[70:71], 1.0 op_sel_hi:[1,0]
	v_mul_f32_e32 v69, 0xbfb8aa3b, v53
	v_exp_f32_e32 v68, v68
	v_exp_f32_e32 v69, v69
	v_mul_f32_e32 v78, 0xbfb8aa3b, v50
	v_rcp_f32_e32 v79, v71
	v_pk_add_f32 v[68:69], v[68:69], 1.0 op_sel_hi:[1,0]
	v_mul_f32_e32 v71, v55, v79
	v_rcp_f32_e32 v79, v70
	v_exp_f32_e32 v78, v78
	v_mul_f32_e32 v70, v54, v79
	v_rcp_f32_e32 v79, v69
	s_nop 0
	v_mul_f32_e32 v69, v53, v79
	v_mul_f32_e32 v79, 0xbfb8aa3b, v51
	v_exp_f32_e32 v79, v79
	s_nop 0
	v_pk_add_f32 v[78:79], v[78:79], 1.0 op_sel_hi:[1,0]
	v_rcp_f32_e32 v88, v68
	v_mul_f32_e32 v77, 0xbfb8aa3b, v49
	v_mul_f32_e32 v68, v52, v88
	v_exp_f32_e32 v77, v77
	v_rcp_f32_e32 v88, v79
	v_pk_add_f32 v[76:77], v[76:77], 1.0 op_sel_hi:[1,0]
	v_mul_f32_e32 v79, v51, v88
	v_rcp_f32_e32 v88, v78
	s_nop 0
	v_mul_f32_e32 v78, v50, v88
	v_rcp_f32_e32 v88, v77
	s_nop 0
	v_mul_f32_e32 v77, v49, v88
	v_rcp_f32_e32 v88, v76
	s_nop 0
	v_mul_f32_e32 v76, v48, v88
.LBB0_254:
	v_cvt_pk_bf16_f32 v68, v68, v69
	v_cvt_pk_bf16_f32 v69, v70, v71
	v_cvt_pk_bf16_f32 v70, v76, v77
	v_cvt_pk_bf16_f32 v71, v78, v79
	global_store_dwordx4 v[82:83], v[68:71], off offset:256
	v_mov_b64_e32 v[78:79], v[42:43]
	s_and_b64 vcc, exec, s[6:7]
	v_mov_b64_e32 v[70:71], v[46:47]
	v_mov_b64_e32 v[76:77], v[40:41]
	v_mov_b64_e32 v[68:69], v[44:45]
	s_cbranch_vccnz .LBB0_256
	v_mul_f32_e32 v70, 0xbfb8aa3b, v46
	v_mul_f32_e32 v71, 0xbfb8aa3b, v47
	v_exp_f32_e32 v70, v70
	v_exp_f32_e32 v71, v71
	v_mul_f32_e32 v69, 0xbfb8aa3b, v40
	v_mul_f32_e32 v68, 0xbfb8aa3b, v44
	v_exp_f32_e32 v76, v69
	v_pk_add_f32 v[70:71], v[70:71], 1.0 op_sel_hi:[1,0]
	v_mul_f32_e32 v69, 0xbfb8aa3b, v45
	v_exp_f32_e32 v68, v68
	v_exp_f32_e32 v69, v69
	v_mul_f32_e32 v78, 0xbfb8aa3b, v42
	v_rcp_f32_e32 v79, v71
	v_pk_add_f32 v[68:69], v[68:69], 1.0 op_sel_hi:[1,0]
	v_mul_f32_e32 v71, v47, v79
	v_rcp_f32_e32 v79, v70
	v_exp_f32_e32 v78, v78
	v_mul_f32_e32 v70, v46, v79
	v_rcp_f32_e32 v79, v69
	s_nop 0
	v_mul_f32_e32 v69, v45, v79
	v_mul_f32_e32 v79, 0xbfb8aa3b, v43
	v_exp_f32_e32 v79, v79
	s_nop 0
	v_pk_add_f32 v[78:79], v[78:79], 1.0 op_sel_hi:[1,0]
	v_rcp_f32_e32 v82, v68
	v_mul_f32_e32 v77, 0xbfb8aa3b, v41
	v_mul_f32_e32 v68, v44, v82
	v_exp_f32_e32 v77, v77
	v_rcp_f32_e32 v82, v79
	v_pk_add_f32 v[76:77], v[76:77], 1.0 op_sel_hi:[1,0]
	v_mul_f32_e32 v79, v43, v82
	v_rcp_f32_e32 v82, v78
	s_nop 0
	v_mul_f32_e32 v78, v42, v82
	v_rcp_f32_e32 v82, v77
	s_nop 0
	v_mul_f32_e32 v77, v41, v82
	v_rcp_f32_e32 v82, v76
	s_nop 0
	v_mul_f32_e32 v76, v40, v82
.LBB0_256:
	v_add_u32_e32 v82, s9, v182
	v_ashrrev_i32_e32 v83, 31, v82
	v_lshlrev_b64 v[82:83], 12, v[82:83]
	v_lshl_add_u64 v[82:83], v[80:81], 0, v[82:83]
	v_cvt_pk_bf16_f32 v68, v68, v69
	v_cvt_pk_bf16_f32 v69, v70, v71
	v_cvt_pk_bf16_f32 v70, v76, v77
	v_cvt_pk_bf16_f32 v71, v78, v79
	global_store_dwordx4 v[82:83], v[68:71], off
	v_mov_b64_e32 v[78:79], v[34:35]
	s_and_b64 vcc, exec, s[6:7]
	v_mov_b64_e32 v[70:71], v[38:39]
	v_mov_b64_e32 v[76:77], v[32:33]
	v_mov_b64_e32 v[68:69], v[36:37]
	s_cbranch_vccnz .LBB0_258
	v_mul_f32_e32 v70, 0xbfb8aa3b, v38
	v_mul_f32_e32 v71, 0xbfb8aa3b, v39
	v_exp_f32_e32 v70, v70
	v_exp_f32_e32 v71, v71
	v_mul_f32_e32 v69, 0xbfb8aa3b, v32
	v_mul_f32_e32 v68, 0xbfb8aa3b, v36
	v_exp_f32_e32 v76, v69
	v_pk_add_f32 v[70:71], v[70:71], 1.0 op_sel_hi:[1,0]
	v_mul_f32_e32 v69, 0xbfb8aa3b, v37
	v_exp_f32_e32 v68, v68
	v_exp_f32_e32 v69, v69
	v_mul_f32_e32 v78, 0xbfb8aa3b, v34
	v_rcp_f32_e32 v79, v71
	v_pk_add_f32 v[68:69], v[68:69], 1.0 op_sel_hi:[1,0]
	v_mul_f32_e32 v71, v39, v79
	v_rcp_f32_e32 v79, v70
	v_exp_f32_e32 v78, v78
	v_mul_f32_e32 v70, v38, v79
	v_rcp_f32_e32 v79, v69
	s_nop 0
	v_mul_f32_e32 v69, v37, v79
	v_mul_f32_e32 v79, 0xbfb8aa3b, v35
	v_exp_f32_e32 v79, v79
	s_nop 0
	v_pk_add_f32 v[78:79], v[78:79], 1.0 op_sel_hi:[1,0]
	v_rcp_f32_e32 v88, v68
	v_mul_f32_e32 v77, 0xbfb8aa3b, v33
	v_mul_f32_e32 v68, v36, v88
	v_exp_f32_e32 v77, v77
	v_rcp_f32_e32 v88, v79
	v_pk_add_f32 v[76:77], v[76:77], 1.0 op_sel_hi:[1,0]
	v_mul_f32_e32 v79, v35, v88
	v_rcp_f32_e32 v88, v78
	s_nop 0
	v_mul_f32_e32 v78, v34, v88
	v_rcp_f32_e32 v88, v77
	s_nop 0
	v_mul_f32_e32 v77, v33, v88
	v_rcp_f32_e32 v88, v76
	s_nop 0
	v_mul_f32_e32 v76, v32, v88
; DI bf16x8 pack8(const f32x4& a, const f32x4& b) { v4u w; w.x = pk2(a[0], a[1]); w.y = pk2(a[2], a[3]); w.z = pk2(b[0], b[1]); w.w = pk2(b[2], b[3]); return __builtin_bit_cast(bf16x8, w); }
; DI float silu(float x) { return x / (1.f + __expf(-x)); }
;     DI void operator()(const f32x4 (&acc)[2][2][4][2], const pg8::Unit& u, int wr, int wc, int fr, int fq) const {
;     ...
;             bf16* dst = zq + (size_t)ty * T * D;
;             EPI_LOOP_BEGIN
; #pragma unroll
;                 for (int bj = 0; bj < 2; ++bj) { const size_t o = (size_t)row * D + cbase + bj * 128; f32x4 a = acc[ai][bj][m][0], b = acc[ai][bj][m][1];
;                     if (ty != 2) {
; #pragma unroll
;                         for (int e = 0; e < 4; ++e) { a[e] = silu(a[e]); b[e] = silu(b[e]); } }
;                     *(bf16x8*)(dst + o) = pack8(a, b); }
.LBB0_258:
	v_cvt_pk_bf16_f32 v68, v68, v69
	v_cvt_pk_bf16_f32 v69, v70, v71
	v_cvt_pk_bf16_f32 v70, v76, v77
	v_cvt_pk_bf16_f32 v71, v78, v79
	global_store_dwordx4 v[82:83], v[68:71], off offset:256
	v_mov_b64_e32 v[78:79], v[26:27]
	s_and_b64 vcc, exec, s[6:7]
	v_mov_b64_e32 v[70:71], v[30:31]
	v_mov_b64_e32 v[76:77], v[24:25]
	v_mov_b64_e32 v[68:69], v[28:29]
	s_cbranch_vccnz .LBB0_260
	v_mul_f32_e32 v70, 0xbfb8aa3b, v30
	v_mul_f32_e32 v71, 0xbfb8aa3b, v31
	v_exp_f32_e32 v70, v70
	v_exp_f32_e32 v71, v71
	v_mul_f32_e32 v69, 0xbfb8aa3b, v24
	v_mul_f32_e32 v68, 0xbfb8aa3b, v28
	v_exp_f32_e32 v76, v69
	v_pk_add_f32 v[70:71], v[70:71], 1.0 op_sel_hi:[1,0]
	v_mul_f32_e32 v69, 0xbfb8aa3b, v29
	v_exp_f32_e32 v68, v68
	v_exp_f32_e32 v69, v69
	v_mul_f32_e32 v78, 0xbfb8aa3b, v26
	v_rcp_f32_e32 v79, v71
	v_pk_add_f32 v[68:69], v[68:69], 1.0 op_sel_hi:[1,0]
	v_mul_f32_e32 v71, v31, v79
	v_rcp_f32_e32 v79, v70
	v_exp_f32_e32 v78, v78
	v_mul_f32_e32 v70, v30, v79
	v_rcp_f32_e32 v79, v69
	s_nop 0
	v_mul_f32_e32 v69, v29, v79
	v_mul_f32_e32 v79, 0xbfb8aa3b, v27
	v_exp_f32_e32 v79, v79
	s_nop 0
	v_pk_add_f32 v[78:79], v[78:79], 1.0 op_sel_hi:[1,0]
	v_rcp_f32_e32 v82, v68
	v_mul_f32_e32 v77, 0xbfb8aa3b, v25
	v_mul_f32_e32 v68, v28, v82
	v_exp_f32_e32 v77, v77
	v_rcp_f32_e32 v82, v79
	v_pk_add_f32 v[76:77], v[76:77], 1.0 op_sel_hi:[1,0]
	v_mul_f32_e32 v79, v27, v82
	v_rcp_f32_e32 v82, v78
	s_nop 0
	v_mul_f32_e32 v78, v26, v82
	v_rcp_f32_e32 v82, v77
	s_nop 0
	v_mul_f32_e32 v77, v25, v82
	v_rcp_f32_e32 v82, v76
	s_nop 0
	v_mul_f32_e32 v76, v24, v82
.LBB0_260:
	v_add_u32_e32 v82, s9, v183
	v_ashrrev_i32_e32 v83, 31, v82
	v_lshlrev_b64 v[82:83], 12, v[82:83]
	v_lshl_add_u64 v[82:83], v[80:81], 0, v[82:83]
	v_cvt_pk_bf16_f32 v68, v68, v69
	v_cvt_pk_bf16_f32 v69, v70, v71
	v_cvt_pk_bf16_f32 v70, v76, v77
	v_cvt_pk_bf16_f32 v71, v78, v79
	global_store_dwordx4 v[82:83], v[68:71], off
	v_mov_b64_e32 v[78:79], v[18:19]
	s_and_b64 vcc, exec, s[6:7]
	v_mov_b64_e32 v[70:71], v[22:23]
	v_mov_b64_e32 v[76:77], v[16:17]
	v_mov_b64_e32 v[68:69], v[20:21]
	s_cbranch_vccnz .LBB0_262
	v_mul_f32_e32 v70, 0xbfb8aa3b, v22
	v_mul_f32_e32 v71, 0xbfb8aa3b, v23
	v_exp_f32_e32 v70, v70
	v_exp_f32_e32 v71, v71
	v_mul_f32_e32 v69, 0xbfb8aa3b, v16
	v_mul_f32_e32 v68, 0xbfb8aa3b, v20
	v_exp_f32_e32 v76, v69
	v_pk_add_f32 v[70:71], v[70:71], 1.0 op_sel_hi:[1,0]
	v_mul_f32_e32 v69, 0xbfb8aa3b, v21
	v_exp_f32_e32 v68, v68
	v_exp_f32_e32 v69, v69
	v_mul_f32_e32 v78, 0xbfb8aa3b, v18
	v_rcp_f32_e32 v79, v71
	v_pk_add_f32 v[68:69], v[68:69], 1.0 op_sel_hi:[1,0]
	v_mul_f32_e32 v71, v23, v79
	v_rcp_f32_e32 v79, v70
	v_exp_f32_e32 v78, v78
	v_mul_f32_e32 v70, v22, v79
	v_rcp_f32_e32 v79, v69
	s_nop 0
	v_mul_f32_e32 v69, v21, v79
	v_mul_f32_e32 v79, 0xbfb8aa3b, v19
	v_exp_f32_e32 v79, v79
	s_nop 0
	v_pk_add_f32 v[78:79], v[78:79], 1.0 op_sel_hi:[1,0]
	v_rcp_f32_e32 v88, v68
	v_mul_f32_e32 v77, 0xbfb8aa3b, v17
	v_mul_f32_e32 v68, v20, v88
	v_exp_f32_e32 v77, v77
	v_rcp_f32_e32 v88, v79
	v_pk_add_f32 v[76:77], v[76:77], 1.0 op_sel_hi:[1,0]
	v_mul_f32_e32 v79, v19, v88
	v_rcp_f32_e32 v88, v78
	s_nop 0
	v_mul_f32_e32 v78, v18, v88
	v_rcp_f32_e32 v88, v77
	s_nop 0
	v_mul_f32_e32 v77, v17, v88
	v_rcp_f32_e32 v88, v76
	s_nop 0
	v_mul_f32_e32 v76, v16, v88
.LBB0_262:
	v_cvt_pk_bf16_f32 v68, v68, v69
	v_cvt_pk_bf16_f32 v69, v70, v71
	v_cvt_pk_bf16_f32 v70, v76, v77
	v_cvt_pk_bf16_f32 v71, v78, v79
	global_store_dwordx4 v[82:83], v[68:71], off offset:256
	v_mov_b64_e32 v[78:79], v[10:11]
	s_and_b64 vcc, exec, s[6:7]
	v_mov_b64_e32 v[70:71], v[14:15]
	v_mov_b64_e32 v[76:77], v[8:9]
	v_mov_b64_e32 v[68:69], v[12:13]
	s_cbranch_vccnz .LBB0_264
	v_mul_f32_e32 v70, 0xbfb8aa3b, v14
	v_mul_f32_e32 v71, 0xbfb8aa3b, v15
	v_exp_f32_e32 v70, v70
	v_exp_f32_e32 v71, v71
	v_mul_f32_e32 v69, 0xbfb8aa3b, v8
	v_mul_f32_e32 v68, 0xbfb8aa3b, v12
	v_exp_f32_e32 v76, v69
	v_pk_add_f32 v[70:71], v[70:71], 1.0 op_sel_hi:[1,0]
	v_mul_f32_e32 v69, 0xbfb8aa3b, v13
	v_exp_f32_e32 v68, v68
	v_exp_f32_e32 v69, v69
	v_mul_f32_e32 v78, 0xbfb8aa3b, v10
	v_rcp_f32_e32 v79, v71
	v_pk_add_f32 v[68:69], v[68:69], 1.0 op_sel_hi:[1,0]
	v_mul_f32_e32 v71, v15, v79
	v_rcp_f32_e32 v79, v70
	v_exp_f32_e32 v78, v78
	v_mul_f32_e32 v70, v14, v79
	v_rcp_f32_e32 v79, v69
	s_nop 0
	v_mul_f32_e32 v69, v13, v79
	v_mul_f32_e32 v79, 0xbfb8aa3b, v11
	v_exp_f32_e32 v79, v79
	s_nop 0
	v_pk_add_f32 v[78:79], v[78:79], 1.0 op_sel_hi:[1,0]
	v_rcp_f32_e32 v82, v68
	v_mul_f32_e32 v77, 0xbfb8aa3b, v9
	v_mul_f32_e32 v68, v12, v82
	v_exp_f32_e32 v77, v77
	v_rcp_f32_e32 v82, v79
	v_pk_add_f32 v[76:77], v[76:77], 1.0 op_sel_hi:[1,0]
	v_mul_f32_e32 v79, v11, v82
	v_rcp_f32_e32 v82, v78
	s_nop 0
	v_mul_f32_e32 v78, v10, v82
	v_rcp_f32_e32 v82, v77
	s_nop 0
	v_mul_f32_e32 v77, v9, v82
	v_rcp_f32_e32 v82, v76
	s_nop 0
	v_mul_f32_e32 v76, v8, v82
.LBB0_264:
	v_add_u32_e32 v82, s9, v184
	v_ashrrev_i32_e32 v83, 31, v82
	v_lshlrev_b64 v[82:83], 12, v[82:83]
	v_lshl_add_u64 v[80:81], v[80:81], 0, v[82:83]
	v_cvt_pk_bf16_f32 v68, v68, v69
	v_cvt_pk_bf16_f32 v69, v70, v71
	v_cvt_pk_bf16_f32 v70, v76, v77
	v_cvt_pk_bf16_f32 v71, v78, v79
	global_store_dwordx4 v[80:81], v[68:71], off
	v_mov_b64_e32 v[78:79], v[2:3]
	s_and_b64 vcc, exec, s[6:7]
	v_mov_b64_e32 v[70:71], v[6:7]
	v_mov_b64_e32 v[76:77], v[0:1]
	v_mov_b64_e32 v[68:69], v[4:5]
	s_cbranch_vccnz .LBB0_266
	v_mul_f32_e32 v70, 0xbfb8aa3b, v6
	v_mul_f32_e32 v71, 0xbfb8aa3b, v7
	v_exp_f32_e32 v70, v70
	v_exp_f32_e32 v71, v71
	v_mul_f32_e32 v69, 0xbfb8aa3b, v0
	v_mul_f32_e32 v68, 0xbfb8aa3b, v4
	v_exp_f32_e32 v76, v69
	v_pk_add_f32 v[70:71], v[70:71], 1.0 op_sel_hi:[1,0]
	v_mul_f32_e32 v69, 0xbfb8aa3b, v5
	v_exp_f32_e32 v68, v68
	v_exp_f32_e32 v69, v69
	v_mul_f32_e32 v78, 0xbfb8aa3b, v2
	v_rcp_f32_e32 v79, v71
	v_pk_add_f32 v[68:69], v[68:69], 1.0 op_sel_hi:[1,0]
	v_mul_f32_e32 v71, v7, v79
	v_rcp_f32_e32 v79, v70
	v_exp_f32_e32 v78, v78
	v_mul_f32_e32 v70, v6, v79
	v_rcp_f32_e32 v79, v69
	s_nop 0
	v_mul_f32_e32 v69, v5, v79
	v_mul_f32_e32 v79, 0xbfb8aa3b, v3
	v_exp_f32_e32 v79, v79
	s_nop 0
	v_pk_add_f32 v[78:79], v[78:79], 1.0 op_sel_hi:[1,0]
	v_rcp_f32_e32 v82, v68
	v_mul_f32_e32 v77, 0xbfb8aa3b, v1
	v_mul_f32_e32 v68, v4, v82
	v_exp_f32_e32 v77, v77
	v_rcp_f32_e32 v82, v79
	v_pk_add_f32 v[76:77], v[76:77], 1.0 op_sel_hi:[1,0]
	v_mul_f32_e32 v79, v3, v82
	v_rcp_f32_e32 v82, v78
	s_nop 0
	v_mul_f32_e32 v78, v2, v82
	v_rcp_f32_e32 v82, v77
	s_nop 0
	v_mul_f32_e32 v77, v1, v82
	v_rcp_f32_e32 v82, v76
	s_nop 0
	v_mul_f32_e32 v76, v0, v82

; DI bf16x8 pack8(const f32x4& a, const f32x4& b) { v4u w; w.x = pk2(a[0], a[1]); w.y = pk2(a[2], a[3]); w.z = pk2(b[0], b[1]); w.w = pk2(b[2], b[3]); return __builtin_bit_cast(bf16x8, w); }
;     DI void operator()(const f32x4 (&acc)[2][2][4][2], const pg8::Unit& u, int wr, int wc, int fr, int fq) const {
;     ...
;         if (ty == 1) {
;             f32x4 lbv[2][2];
; #pragma unroll
;             for (int bj = 0; bj < 2; ++bj) { lbv[bj][0] = *(const f32x4*)(lb0 + cbase + bj * 128); lbv[bj][1] = *(const f32x4*)(lb0 + cbase + bj * 128 + 4); }
;             EPI_LOOP_BEGIN
; #pragma unroll
;                 for (int bj = 0; bj < 2; ++bj) { const size_t o = (size_t)row * D + cbase + bj * 128; f32x4 lg[2], kk[2];
; #pragma unroll
;                     for (int n = 0; n < 2; ++n)
; #pragma unroll
;                         for (int e = 0; e < 4; ++e) { const float f = fminf(fmaxf(acc[ai][bj][m][n][e], -30.f), 30.f), lb = lbv[bj][n][e], ef = __expf(-f), sg = 1.f / (1.f + ef), sgn = ef / (1.f + ef);
;                             lg[n][e] = __logf(lb + (1.f - lb) * sg); kk[n][e] = (1.f - lb) * sgn; }
;                     *(f32x4*)(lf + o) = lg[0]; *(f32x4*)(lf + o + 4) = lg[1]; *(bf16x8*)(zq + (size_t)T * D + o) = pack8(kk[0], kk[1]); }
.LBB0_268:
	s_and_b64 vcc, exec, s[6:7]
	s_cbranch_vccz .LBB0_267
	v_ashrrev_i32_e32 v161, 31, v160
	v_lshl_add_u64 v[76:77], v[160:161], 2, s[22:23]
	global_load_dwordx4 v[88:91], v[76:77], off
	global_load_dwordx4 v[80:83], v[76:77], off offset:16
	v_max_f32_e32 v68, v140, v140
	v_max_f32_e32 v69, v141, v141
	v_med3_f32 v141, v68, s68, v188
	v_med3_f32 v162, v69, s68, v188
	v_mul_f32_e32 v141, 0xbfb8aa3b, v141
	v_mul_f32_e32 v163, 0xbfb8aa3b, v162
	s_lshl_b32 s45, s8, 8
	v_exp_f32_e32 v162, v141
	v_exp_f32_e32 v163, v163
	v_add_u32_e32 v140, s45, v175
	v_ashrrev_i32_e32 v141, 31, v140
	v_lshlrev_b64 v[140:141], 11, v[140:141]
	v_lshl_add_u64 v[168:169], v[140:141], 0, v[160:161]
	v_pk_add_f32 v[140:141], v[162:163], 1.0 op_sel_hi:[1,0]
	v_max_f32_e32 v142, v142, v142
	v_rcp_f32_e32 v170, v140
	v_rcp_f32_e32 v171, v141
	v_rcp_f32_e32 v164, v141
	s_nop 0
	v_mul_f32_e32 v165, v163, v164
	v_rcp_f32_e32 v141, v140
	s_nop 0
	v_mul_f32_e32 v164, v162, v141
	v_med3_f32 v142, v142, s68, v188
	v_mul_f32_e32 v142, 0xbfb8aa3b, v142
	v_max_f32_e32 v136, v136, v136
	v_med3_f32 v136, v136, s68, v188
	v_mul_f32_e32 v136, 0xbfb8aa3b, v136
	v_max_f32_e32 v138, v138, v138
	v_max_f32_e32 v139, v139, v139
	v_med3_f32 v138, v138, s68, v188
	s_waitcnt vmcnt(0)
	v_pk_add_f32 v[166:167], v[88:89], 1.0 op_sel_hi:[1,0] neg_lo:[1,0] neg_hi:[1,0]
	v_med3_f32 v139, v139, s68, v188
	v_fma_f32 v140, v170, v166, v88
	v_cmp_gt_f32_e32 vcc, s69, v140
	v_exp_f32_e32 v170, v142
	v_max_f32_e32 v142, v143, v143
	v_cndmask_b32_e64 v162, 0, 32, vcc
	v_ldexp_f32 v140, v140, v162
	v_log_f32_e32 v140, v140
	v_fma_f32 v141, v171, v167, v89
	v_med3_f32 v142, v142, s68, v188
	v_cmp_gt_f32_e64 s[6:7], s69, v141
	v_mul_f32_e32 v142, 0xbfb8aa3b, v142
	v_exp_f32_e32 v171, v142
	v_cndmask_b32_e64 v163, 0, 32, s[6:7]
	v_ldexp_f32 v141, v141, v163
	v_mul_f32_e32 v163, 0x3f317217, v140
	v_log_f32_e32 v141, v141
	v_fma_f32 v163, v140, s70, -v163
	v_fmac_f32_e32 v163, 0x3377d1cf, v140
	v_cndmask_b32_e32 v162, 0, v189, vcc
	v_fmac_f32_e32 v163, 0x3f317217, v140
	v_cmp_lt_f32_e64 vcc, |v140|, s71
	v_pk_add_f32 v[190:191], v[170:171], 1.0 op_sel_hi:[1,0]
	v_mul_f32_e32 v142, 0x3f317217, v141
	v_cndmask_b32_e32 v140, v140, v163, vcc
	v_sub_f32_e32 v140, v140, v162
	v_fma_f32 v142, v141, s70, -v142
	v_fmac_f32_e32 v142, 0x3377d1cf, v141
	v_fmac_f32_e32 v142, 0x3f317217, v141
	v_cmp_lt_f32_e64 vcc, |v141|, s71
	v_mul_f32_e32 v138, 0xbfb8aa3b, v138
	v_mul_f32_e32 v139, 0xbfb8aa3b, v139
	v_cndmask_b32_e32 v141, v141, v142, vcc
	v_rcp_f32_e32 v142, v190
	v_pk_add_f32 v[162:163], v[90:91], 1.0 op_sel_hi:[1,0] neg_lo:[1,0] neg_hi:[1,0]
	v_pk_mul_f32 v[172:173], v[164:165], v[166:167]
	v_fma_f32 v142, v142, v162, v90
	v_cmp_gt_f32_e32 vcc, s69, v142
	v_exp_f32_e32 v138, v138
	v_exp_f32_e32 v139, v139
	v_cndmask_b32_e64 v143, 0, 32, vcc
	v_ldexp_f32 v142, v142, v143
	v_log_f32_e32 v142, v142
	v_cndmask_b32_e64 v143, 0, v189, s[6:7]
	v_sub_f32_e32 v141, v141, v143
	v_mul_f32_e32 v143, 0x3f317217, v142
	v_fma_f32 v143, v142, s70, -v143
	v_fmac_f32_e32 v143, 0x3377d1cf, v142
	v_fmac_f32_e32 v143, 0x3f317217, v142
	v_cmp_lt_f32_e64 s[6:7], |v142|, s71
	global_load_dwordx4 v[68:71], v[76:77], off offset:528
	s_nop 0
	global_load_dwordx4 v[76:79], v[76:77], off offset:512
	v_cndmask_b32_e64 v142, v142, v143, s[6:7]
	v_cndmask_b32_e32 v143, 0, v189, vcc
	v_sub_f32_e32 v142, v142, v143
	v_rcp_f32_e32 v143, v191
	s_nop 0
	v_fma_f32 v143, v143, v163, v91
	v_rcp_f32_e32 v164, v191
	s_nop 0
	v_mul_f32_e32 v165, v171, v164
	v_cmp_gt_f32_e64 s[6:7], s69, v143
	v_rcp_f32_e32 v164, v190
	v_max_f32_e32 v132, v132, v132
	v_mul_f32_e32 v164, v170, v164
	v_cndmask_b32_e64 v170, 0, 32, s[6:7]
	v_ldexp_f32 v143, v143, v170
	v_exp_f32_e32 v170, v136
	v_max_f32_e32 v136, v137, v137
	v_med3_f32 v136, v136, s68, v188
	v_mul_f32_e32 v136, 0xbfb8aa3b, v136
	v_exp_f32_e32 v171, v136
	v_log_f32_e32 v143, v143
	v_med3_f32 v132, v132, s68, v188
	v_mul_f32_e32 v132, 0xbfb8aa3b, v132
	v_pk_add_f32 v[192:193], v[170:171], 1.0 op_sel_hi:[1,0]
	v_mul_f32_e32 v136, 0x3f317217, v143
	v_fma_f32 v136, v143, s70, -v136
	v_fmac_f32_e32 v136, 0x3377d1cf, v143
	v_fmac_f32_e32 v136, 0x3f317217, v143
	v_cmp_lt_f32_e64 vcc, |v143|, s71
	v_max_f32_e32 v134, v134, v134
	v_med3_f32 v134, v134, s68, v188
	v_cndmask_b32_e32 v143, v143, v136, vcc
	v_rcp_f32_e32 v190, v192
	v_pk_add_f32 v[136:137], v[80:81], 1.0 op_sel_hi:[1,0] neg_lo:[1,0] neg_hi:[1,0]
	v_pk_mul_f32 v[194:195], v[164:165], v[162:163]
	v_fma_f32 v190, v190, v136, v80
	v_cmp_gt_f32_e32 vcc, s69, v190
	v_mul_f32_e32 v134, 0xbfb8aa3b, v134
	v_max_f32_e32 v128, v128, v128
	v_cndmask_b32_e64 v191, 0, 32, vcc
	v_ldexp_f32 v190, v190, v191
	v_log_f32_e32 v190, v190
	v_cndmask_b32_e64 v191, 0, v189, s[6:7]
	v_mul_f32_e32 v164, 0x3f317217, v190
	v_sub_f32_e32 v143, v143, v191
	v_fma_f32 v164, v190, s70, -v164
	v_fmac_f32_e32 v164, 0x3377d1cf, v190
	v_fmac_f32_e32 v164, 0x3f317217, v190
	v_cmp_lt_f32_e64 s[6:7], |v190|, s71
	v_med3_f32 v128, v128, s68, v188
	v_mul_f32_e32 v128, 0xbfb8aa3b, v128
	v_cndmask_b32_e64 v164, v190, v164, s[6:7]
	v_cndmask_b32_e32 v190, 0, v189, vcc
	v_sub_f32_e32 v190, v164, v190
	v_rcp_f32_e32 v164, v193
	s_nop 0
	v_fma_f32 v164, v164, v137, v81
	v_rcp_f32_e32 v165, v193
	s_nop 0
	v_mul_f32_e32 v171, v171, v165
	v_cmp_gt_f32_e64 s[6:7], s69, v164
	v_rcp_f32_e32 v165, v192
	s_nop 0
	v_mul_f32_e32 v170, v170, v165
	v_cndmask_b32_e64 v165, 0, 32, s[6:7]
	v_ldexp_f32 v164, v164, v165
	v_log_f32_e32 v164, v164
	v_pk_add_f32 v[196:197], v[138:139], 1.0 op_sel_hi:[1,0]
	v_max_f32_e32 v130, v130, v130
	v_mul_f32_e32 v165, 0x3f317217, v164
	v_fma_f32 v165, v164, s70, -v165
; DI bf16x8 pack8(const f32x4& a, const f32x4& b) { v4u w; w.x = pk2(a[0], a[1]); w.y = pk2(a[2], a[3]); w.z = pk2(b[0], b[1]); w.w = pk2(b[2], b[3]); return __builtin_bit_cast(bf16x8, w); }
;     DI void operator()(const f32x4 (&acc)[2][2][4][2], const pg8::Unit& u, int wr, int wc, int fr, int fq) const {
;     ...
;         if (ty == 1) {
;             f32x4 lbv[2][2];
; #pragma unroll
;             for (int bj = 0; bj < 2; ++bj) { lbv[bj][0] = *(const f32x4*)(lb0 + cbase + bj * 128); lbv[bj][1] = *(const f32x4*)(lb0 + cbase + bj * 128 + 4); }
;             EPI_LOOP_BEGIN
; #pragma unroll
;                 for (int bj = 0; bj < 2; ++bj) { const size_t o = (size_t)row * D + cbase + bj * 128; f32x4 lg[2], kk[2];
; #pragma unroll
;                     for (int n = 0; n < 2; ++n)
; #pragma unroll
;                         for (int e = 0; e < 4; ++e) { const float f = fminf(fmaxf(acc[ai][bj][m][n][e], -30.f), 30.f), lb = lbv[bj][n][e], ef = __expf(-f), sg = 1.f / (1.f + ef), sgn = ef / (1.f + ef);
;                             lg[n][e] = __logf(lb + (1.f - lb) * sg); kk[n][e] = (1.f - lb) * sgn; }
;                     *(f32x4*)(lf + o) = lg[0]; *(f32x4*)(lf + o + 4) = lg[1]; *(bf16x8*)(zq + (size_t)T * D + o) = pack8(kk[0], kk[1]); }
	v_fmac_f32_e32 v165, 0x3377d1cf, v164
	v_fmac_f32_e32 v165, 0x3f317217, v164
	v_cmp_lt_f32_e64 vcc, |v164|, s71
	v_med3_f32 v130, v130, s68, v188
	v_mul_f32_e32 v130, 0xbfb8aa3b, v130
	v_cndmask_b32_e32 v193, v164, v165, vcc
	v_rcp_f32_e32 v191, v196
	v_pk_add_f32 v[164:165], v[82:83], 1.0 op_sel_hi:[1,0] neg_lo:[1,0] neg_hi:[1,0]
	v_pk_mul_f32 v[198:199], v[170:171], v[136:137]
	v_fma_f32 v191, v191, v164, v82
	v_cmp_gt_f32_e32 vcc, s69, v191
	v_max_f32_e32 v124, v124, v124
	v_med3_f32 v124, v124, s68, v188
	v_cndmask_b32_e64 v192, 0, 32, vcc
	v_ldexp_f32 v191, v191, v192
	v_log_f32_e32 v192, v191
	v_cndmask_b32_e64 v191, 0, v189, s[6:7]
	v_mul_f32_e32 v170, 0x3f317217, v192
	v_sub_f32_e32 v191, v193, v191
	v_fma_f32 v170, v192, s70, -v170
	v_fmac_f32_e32 v170, 0x3377d1cf, v192
	v_fmac_f32_e32 v170, 0x3f317217, v192
	v_cmp_lt_f32_e64 s[6:7], |v192|, s71
	v_mul_f32_e32 v124, 0xbfb8aa3b, v124
	v_max_f32_e32 v126, v126, v126
	v_cndmask_b32_e64 v170, v192, v170, s[6:7]
	v_cndmask_b32_e32 v192, 0, v189, vcc
	v_sub_f32_e32 v192, v170, v192
	v_rcp_f32_e32 v170, v197
	v_rcp_f32_e32 v171, v196
	v_mul_f32_e32 v139, v139, v170
	v_mul_f32_e32 v138, v138, v171
	v_rcp_f32_e32 v193, v197
	s_nop 0
	v_fma_f32 v193, v193, v165, v83
	v_cmp_gt_f32_e32 vcc, s69, v193
	v_pk_mul_f32 v[196:197], v[138:139], v[164:165]
	v_lshl_add_u64 v[170:171], v[168:169], 2, s[18:19]
	v_cndmask_b32_e64 v200, 0, 32, vcc
	v_ldexp_f32 v193, v193, v200
	v_log_f32_e32 v193, v193
	v_exp_f32_e32 v200, v132
	v_max_f32_e32 v132, v133, v133
	v_med3_f32 v132, v132, s68, v188
	v_mul_f32_e32 v138, 0x3f317217, v193
	v_mul_f32_e32 v132, 0xbfb8aa3b, v132
	v_fma_f32 v138, v193, s70, -v138
	v_exp_f32_e32 v201, v132
	v_fmac_f32_e32 v138, 0x3377d1cf, v193
	v_fmac_f32_e32 v138, 0x3f317217, v193
	v_cmp_lt_f32_e64 s[6:7], |v193|, s71
	v_cndmask_b32_e32 v139, 0, v189, vcc
	v_med3_f32 v126, v126, s68, v188
	v_cndmask_b32_e64 v138, v193, v138, s[6:7]
	v_sub_f32_e32 v193, v138, v139
	global_store_dwordx4 v[170:171], v[140:143], off
	global_store_dwordx4 v[170:171], v[190:193], off offset:16
	v_mul_f32_e32 v126, 0xbfb8aa3b, v126
	v_pk_add_f32 v[140:141], v[200:201], 1.0 op_sel_hi:[1,0]
	v_cvt_pk_bf16_f32 v190, v172, v173
	v_cvt_pk_bf16_f32 v191, v194, v195
	v_cvt_pk_bf16_f32 v192, v198, v199
	v_cvt_pk_bf16_f32 v193, v196, v197
	v_rcp_f32_e32 v132, v140
	s_waitcnt vmcnt(2)
	v_pk_add_f32 v[138:139], v[76:77], 1.0 op_sel_hi:[1,0] neg_lo:[1,0] neg_hi:[1,0]
	v_lshl_add_u64 v[142:143], v[168:169], 1, s[42:43]
	v_fma_f32 v132, v132, v138, v76
	v_cmp_gt_f32_e32 vcc, s69, v132
	s_nop 0
	s_nop 0
	v_cndmask_b32_e64 v133, 0, 32, vcc
	v_ldexp_f32 v132, v132, v133
	v_log_f32_e32 v132, v132
	global_store_dwordx4 v[142:143], v[190:193], off
	v_max_f32_e32 v120, v120, v120
	v_mul_f32_e32 v133, 0x3f317217, v132
	v_fma_f32 v133, v132, s70, -v133
	v_fmac_f32_e32 v133, 0x3377d1cf, v132
	v_fmac_f32_e32 v133, 0x3f317217, v132
	v_cmp_lt_f32_e64 s[6:7], |v132|, s71
	v_med3_f32 v120, v120, s68, v188
	v_mul_f32_e32 v120, 0xbfb8aa3b, v120
	v_cndmask_b32_e64 v132, v132, v133, s[6:7]
	v_cndmask_b32_e32 v133, 0, v189, vcc
	v_sub_f32_e32 v132, v132, v133
	v_rcp_f32_e32 v133, v141
	v_max_f32_e32 v122, v122, v122
	v_mul_f32_e32 v169, v201, v133
	v_max_f32_e32 v123, v123, v123
	v_exp_f32_e32 v172, v134
	v_max_f32_e32 v134, v135, v135
	v_med3_f32 v134, v134, s68, v188
	v_mul_f32_e32 v134, 0xbfb8aa3b, v134
	v_exp_f32_e32 v173, v134
	v_rcp_f32_e32 v141, v141
	s_nop 0
	v_fma_f32 v141, v141, v139, v77
	v_cmp_gt_f32_e64 s[6:7], s69, v141
	v_pk_add_f32 v[190:191], v[172:173], 1.0 op_sel_hi:[1,0]
	v_med3_f32 v122, v122, s68, v188
	v_cndmask_b32_e64 v168, 0, 32, s[6:7]
	v_ldexp_f32 v141, v141, v168
	v_rcp_f32_e32 v133, v140
	s_nop 0
	v_mul_f32_e32 v168, v200, v133
	v_log_f32_e32 v192, v141
	v_rcp_f32_e32 v134, v190
	v_pk_add_f32 v[140:141], v[78:79], 1.0 op_sel_hi:[1,0] neg_lo:[1,0] neg_hi:[1,0]
	v_mul_f32_e32 v133, 0x3f317217, v192
	v_fma_f32 v134, v134, v140, v78
	v_cmp_gt_f32_e32 vcc, s69, v134
	v_fma_f32 v133, v192, s70, -v133
	v_fmac_f32_e32 v133, 0x3377d1cf, v192
	v_cndmask_b32_e64 v135, 0, 32, vcc
	v_ldexp_f32 v134, v134, v135
	v_log_f32_e32 v134, v134
	v_fmac_f32_e32 v133, 0x3f317217, v192
	v_cmp_lt_f32_e64 s[8:9], |v192|, s71
	v_cndmask_b32_e64 v135, 0, v189, s[6:7]
	v_pk_mul_f32 v[168:169], v[168:169], v[138:139]
	v_cndmask_b32_e64 v133, v192, v133, s[8:9]
	v_sub_f32_e32 v133, v133, v135
	v_mul_f32_e32 v135, 0x3f317217, v134
	v_fma_f32 v135, v134, s70, -v135
	v_fmac_f32_e32 v135, 0x3377d1cf, v134
	v_fmac_f32_e32 v135, 0x3f317217, v134
	v_cmp_lt_f32_e64 s[6:7], |v134|, s71
	v_med3_f32 v123, v123, s68, v188
	v_mul_f32_e32 v122, 0xbfb8aa3b, v122
	v_cndmask_b32_e64 v134, v134, v135, s[6:7]
	v_cndmask_b32_e32 v135, 0, v189, vcc
	v_sub_f32_e32 v134, v134, v135
	v_rcp_f32_e32 v135, v191
	v_mul_f32_e32 v123, 0xbfb8aa3b, v123
	v_mul_f32_e32 v173, v173, v135
	v_rcp_f32_e32 v135, v190
	v_rcp_f32_e32 v191, v191
	v_mul_f32_e32 v172, v172, v135
	v_fma_f32 v191, v191, v141, v79
	v_cmp_gt_f32_e64 s[6:7], s69, v191
	v_pk_mul_f32 v[172:173], v[172:173], v[140:141]
	v_exp_f32_e32 v122, v122
	v_cndmask_b32_e64 v192, 0, 32, s[6:7]
	v_ldexp_f32 v191, v191, v192
	v_exp_f32_e32 v192, v128
	v_max_f32_e32 v128, v129, v129
	v_med3_f32 v128, v128, s68, v188
	v_mul_f32_e32 v128, 0xbfb8aa3b, v128
	v_exp_f32_e32 v193, v128
	v_log_f32_e32 v191, v191
	v_exp_f32_e32 v123, v123
	v_max_f32_e32 v116, v116, v116
	v_pk_add_f32 v[194:195], v[192:193], 1.0 op_sel_hi:[1,0]
	v_mul_f32_e32 v128, 0x3f317217, v191
	v_fma_f32 v190, v191, s70, -v128
	v_fmac_f32_e32 v190, 0x3377d1cf, v191
	v_fmac_f32_e32 v190, 0x3f317217, v191
	v_rcp_f32_e32 v135, v194
; DI bf16x8 pack8(const f32x4& a, const f32x4& b) { v4u w; w.x = pk2(a[0], a[1]); w.y = pk2(a[2], a[3]); w.z = pk2(b[0], b[1]); w.w = pk2(b[2], b[3]); return __builtin_bit_cast(bf16x8, w); }
;     DI void operator()(const f32x4 (&acc)[2][2][4][2], const pg8::Unit& u, int wr, int wc, int fr, int fq) const {
;     ...
;         if (ty == 1) {
;             f32x4 lbv[2][2];
; #pragma unroll
;             for (int bj = 0; bj < 2; ++bj) { lbv[bj][0] = *(const f32x4*)(lb0 + cbase + bj * 128); lbv[bj][1] = *(const f32x4*)(lb0 + cbase + bj * 128 + 4); }
;             EPI_LOOP_BEGIN
; #pragma unroll
;                 for (int bj = 0; bj < 2; ++bj) { const size_t o = (size_t)row * D + cbase + bj * 128; f32x4 lg[2], kk[2];
; #pragma unroll
;                     for (int n = 0; n < 2; ++n)
; #pragma unroll
;                         for (int e = 0; e < 4; ++e) { const float f = fminf(fmaxf(acc[ai][bj][m][n][e], -30.f), 30.f), lb = lbv[bj][n][e], ef = __expf(-f), sg = 1.f / (1.f + ef), sgn = ef / (1.f + ef);
;                             lg[n][e] = __logf(lb + (1.f - lb) * sg); kk[n][e] = (1.f - lb) * sgn; }
;                     *(f32x4*)(lf + o) = lg[0]; *(f32x4*)(lf + o + 4) = lg[1]; *(bf16x8*)(zq + (size_t)T * D + o) = pack8(kk[0], kk[1]); }
	v_pk_add_f32 v[128:129], v[68:69], 1.0 op_sel_hi:[1,0] neg_lo:[1,0] neg_hi:[1,0]
	v_cmp_lt_f32_e64 s[8:9], |v191|, s71
	v_fma_f32 v135, v135, v128, v68
	v_cmp_gt_f32_e32 vcc, s69, v135
	v_med3_f32 v116, v116, s68, v188
	v_mul_f32_e32 v116, 0xbfb8aa3b, v116
	v_cndmask_b32_e64 v196, 0, 32, vcc
	v_ldexp_f32 v135, v135, v196
	v_log_f32_e32 v196, v135
	v_cndmask_b32_e64 v135, v191, v190, s[8:9]
	v_cndmask_b32_e64 v190, 0, v189, s[6:7]
	v_sub_f32_e32 v135, v135, v190
	v_mul_f32_e32 v190, 0x3f317217, v196
	v_fma_f32 v190, v196, s70, -v190
	v_fmac_f32_e32 v190, 0x3377d1cf, v196
	v_fmac_f32_e32 v190, 0x3f317217, v196
	v_cmp_lt_f32_e64 s[6:7], |v196|, s71
	v_max_f32_e32 v118, v118, v118
	v_med3_f32 v118, v118, s68, v188
	v_cndmask_b32_e64 v190, v196, v190, s[6:7]
	v_cndmask_b32_e32 v196, 0, v189, vcc
	v_sub_f32_e32 v190, v190, v196
	v_rcp_f32_e32 v191, v195
	v_mul_f32_e32 v118, 0xbfb8aa3b, v118
	v_mul_f32_e32 v193, v193, v191
	v_rcp_f32_e32 v191, v194
	v_rcp_f32_e32 v195, v195
	v_mul_f32_e32 v192, v192, v191
	v_fma_f32 v195, v195, v129, v69
	v_cmp_gt_f32_e64 s[6:7], s69, v195
	v_max_f32_e32 v112, v112, v112
	v_med3_f32 v112, v112, s68, v188
	v_cndmask_b32_e64 v196, 0, 32, s[6:7]
	v_ldexp_f32 v195, v195, v196
	v_exp_f32_e32 v196, v130
	v_max_f32_e32 v130, v131, v131
	v_med3_f32 v130, v130, s68, v188
	v_mul_f32_e32 v130, 0xbfb8aa3b, v130
	v_exp_f32_e32 v197, v130
	v_log_f32_e32 v200, v195
	v_pk_mul_f32 v[194:195], v[192:193], v[128:129]
	v_mul_f32_e32 v112, 0xbfb8aa3b, v112
	v_pk_add_f32 v[198:199], v[196:197], 1.0 op_sel_hi:[1,0]
	v_mul_f32_e32 v130, 0x3f317217, v200
	v_fma_f32 v192, v200, s70, -v130
	v_fmac_f32_e32 v192, 0x3377d1cf, v200
	v_fmac_f32_e32 v192, 0x3f317217, v200
	v_rcp_f32_e32 v191, v198
	v_pk_add_f32 v[130:131], v[70:71], 1.0 op_sel_hi:[1,0] neg_lo:[1,0] neg_hi:[1,0]
	v_cmp_lt_f32_e64 s[8:9], |v200|, s71
	v_fma_f32 v191, v191, v130, v70
	v_cmp_gt_f32_e32 vcc, s69, v191
	v_max_f32_e32 v114, v114, v114
	v_max_f32_e32 v115, v115, v115
	v_cndmask_b32_e64 v193, 0, 32, vcc
	v_ldexp_f32 v191, v191, v193
	v_log_f32_e32 v193, v191
	v_cndmask_b32_e64 v191, v200, v192, s[8:9]
	v_cndmask_b32_e64 v192, 0, v189, s[6:7]
	v_sub_f32_e32 v191, v191, v192
	v_mul_f32_e32 v192, 0x3f317217, v193
	v_fma_f32 v192, v193, s70, -v192
	v_fmac_f32_e32 v192, 0x3377d1cf, v193
	v_fmac_f32_e32 v192, 0x3f317217, v193
	v_cmp_lt_f32_e64 s[6:7], |v193|, s71
	v_med3_f32 v114, v114, s68, v188
	v_med3_f32 v115, v115, s68, v188
	v_cndmask_b32_e64 v192, v193, v192, s[6:7]
	v_cndmask_b32_e32 v193, 0, v189, vcc
	v_sub_f32_e32 v192, v192, v193
	v_rcp_f32_e32 v193, v199
	v_rcp_f32_e32 v200, v198
	v_mul_f32_e32 v197, v197, v193
	v_mul_f32_e32 v196, v196, v200
	v_rcp_f32_e32 v201, v199
	s_nop 0
	v_fma_f32 v201, v201, v131, v71
	v_cmp_gt_f32_e32 vcc, s69, v201
	v_pk_mul_f32 v[196:197], v[196:197], v[130:131]
	v_mul_f32_e32 v114, 0xbfb8aa3b, v114
	v_cndmask_b32_e64 v202, 0, 32, vcc
	v_ldexp_f32 v201, v201, v202
	v_log_f32_e32 v201, v201
	v_cndmask_b32_e32 v198, 0, v189, vcc
	v_mul_f32_e32 v115, 0xbfb8aa3b, v115
	v_exp_f32_e32 v114, v114
	v_mul_f32_e32 v193, 0x3f317217, v201
	v_fma_f32 v193, v201, s70, -v193
	v_fmac_f32_e32 v193, 0x3377d1cf, v201
	v_fmac_f32_e32 v193, 0x3f317217, v201
	v_cmp_lt_f32_e64 s[6:7], |v201|, s71
	v_exp_f32_e32 v115, v115
	v_max_f32_e32 v108, v108, v108
	v_cndmask_b32_e64 v193, v201, v193, s[6:7]
	v_sub_f32_e32 v193, v193, v198
	global_store_dwordx4 v[170:171], v[132:135], off offset:512
	global_store_dwordx4 v[170:171], v[190:193], off offset:528
	v_exp_f32_e32 v170, v124
	v_max_f32_e32 v124, v125, v125
	v_med3_f32 v124, v124, s68, v188
	v_mul_f32_e32 v124, 0xbfb8aa3b, v124
	v_exp_f32_e32 v171, v124
	v_cvt_pk_bf16_f32 v132, v168, v169
	v_cvt_pk_bf16_f32 v133, v172, v173
	v_cvt_pk_bf16_f32 v134, v194, v195
	v_pk_add_f32 v[168:169], v[170:171], 1.0 op_sel_hi:[1,0]
	v_cvt_pk_bf16_f32 v135, v196, v197
	global_store_dwordx4 v[142:143], v[132:135], off offset:256
	v_add_u32_e32 v124, s45, v178
	v_med3_f32 v108, v108, s68, v188
	v_rcp_f32_e32 v125, v168
	s_nop 0
	v_fma_f32 v125, v125, v166, v88
	v_cmp_gt_f32_e32 vcc, s69, v125
	v_mul_f32_e32 v108, 0xbfb8aa3b, v108
	v_max_f32_e32 v110, v110, v110
	v_cndmask_b32_e64 v132, 0, 32, vcc
	v_ldexp_f32 v125, v125, v132
	v_log_f32_e32 v134, v125
	v_ashrrev_i32_e32 v125, 31, v124
	v_lshlrev_b64 v[124:125], 11, v[124:125]
	v_lshl_add_u64 v[132:133], v[124:125], 0, v[160:161]
	v_mul_f32_e32 v124, 0x3f317217, v134
	v_fma_f32 v124, v134, s70, -v124
	v_fmac_f32_e32 v124, 0x3377d1cf, v134
	v_fmac_f32_e32 v124, 0x3f317217, v134
	v_cmp_lt_f32_e64 s[6:7], |v134|, s71
	v_med3_f32 v110, v110, s68, v188
	v_mul_f32_e32 v110, 0xbfb8aa3b, v110
	v_cndmask_b32_e64 v124, v134, v124, s[6:7]
	v_cndmask_b32_e32 v134, 0, v189, vcc
	v_sub_f32_e32 v124, v124, v134
	v_rcp_f32_e32 v125, v169
	v_max_f32_e32 v104, v104, v104
	v_mul_f32_e32 v135, v171, v125
	v_med3_f32 v104, v104, s68, v188
	v_rcp_f32_e32 v134, v169
	s_nop 0
	v_fma_f32 v134, v134, v167, v89
	v_cmp_gt_f32_e64 s[6:7], s69, v134
	v_mul_f32_e32 v104, 0xbfb8aa3b, v104
	v_max_f32_e32 v106, v106, v106
	v_cndmask_b32_e64 v142, 0, 32, s[6:7]
	v_ldexp_f32 v134, v134, v142
	v_exp_f32_e32 v142, v126
	v_max_f32_e32 v126, v127, v127
	v_med3_f32 v126, v126, s68, v188
	v_mul_f32_e32 v126, 0xbfb8aa3b, v126
	v_exp_f32_e32 v143, v126
	v_log_f32_e32 v171, v134
	v_rcp_f32_e32 v125, v168
	s_nop 0
	v_mul_f32_e32 v134, v170, v125
	v_pk_mul_f32 v[134:135], v[134:135], v[166:167]
	v_pk_add_f32 v[168:169], v[142:143], 1.0 op_sel_hi:[1,0]
	v_mul_f32_e32 v125, 0x3f317217, v171
	v_fma_f32 v125, v171, s70, -v125
	v_fmac_f32_e32 v125, 0x3377d1cf, v171
	v_fmac_f32_e32 v125, 0x3f317217, v171
	v_rcp_f32_e32 v126, v168
; DI bf16x8 pack8(const f32x4& a, const f32x4& b) { v4u w; w.x = pk2(a[0], a[1]); w.y = pk2(a[2], a[3]); w.z = pk2(b[0], b[1]); w.w = pk2(b[2], b[3]); return __builtin_bit_cast(bf16x8, w); }
;     DI void operator()(const f32x4 (&acc)[2][2][4][2], const pg8::Unit& u, int wr, int wc, int fr, int fq) const {
;     ...
;         if (ty == 1) {
;             f32x4 lbv[2][2];
; #pragma unroll
;             for (int bj = 0; bj < 2; ++bj) { lbv[bj][0] = *(const f32x4*)(lb0 + cbase + bj * 128); lbv[bj][1] = *(const f32x4*)(lb0 + cbase + bj * 128 + 4); }
;             EPI_LOOP_BEGIN
; #pragma unroll
;                 for (int bj = 0; bj < 2; ++bj) { const size_t o = (size_t)row * D + cbase + bj * 128; f32x4 lg[2], kk[2];
; #pragma unroll
;                     for (int n = 0; n < 2; ++n)
; #pragma unroll
;                         for (int e = 0; e < 4; ++e) { const float f = fminf(fmaxf(acc[ai][bj][m][n][e], -30.f), 30.f), lb = lbv[bj][n][e], ef = __expf(-f), sg = 1.f / (1.f + ef), sgn = ef / (1.f + ef);
;                             lg[n][e] = __logf(lb + (1.f - lb) * sg); kk[n][e] = (1.f - lb) * sgn; }
;                     *(f32x4*)(lf + o) = lg[0]; *(f32x4*)(lf + o + 4) = lg[1]; *(bf16x8*)(zq + (size_t)T * D + o) = pack8(kk[0], kk[1]); }
	s_nop 0
	v_fma_f32 v126, v126, v162, v90
	v_cmp_gt_f32_e32 vcc, s69, v126
	v_cmp_lt_f32_e64 s[8:9], |v171|, s71
	v_max_f32_e32 v107, v107, v107
	v_cndmask_b32_e64 v127, 0, 32, vcc
	v_ldexp_f32 v126, v126, v127
	v_log_f32_e32 v126, v126
	v_cndmask_b32_e64 v125, v171, v125, s[8:9]
	v_cndmask_b32_e64 v127, 0, v189, s[6:7]
	v_sub_f32_e32 v125, v125, v127
	v_mul_f32_e32 v127, 0x3f317217, v126
	v_fma_f32 v127, v126, s70, -v127
	v_fmac_f32_e32 v127, 0x3377d1cf, v126
	v_fmac_f32_e32 v127, 0x3f317217, v126
	v_cmp_lt_f32_e64 s[6:7], |v126|, s71
	v_med3_f32 v106, v106, s68, v188
	v_med3_f32 v107, v107, s68, v188
	v_cndmask_b32_e64 v126, v126, v127, s[6:7]
	v_cndmask_b32_e32 v127, 0, v189, vcc
	v_sub_f32_e32 v126, v126, v127
	v_rcp_f32_e32 v127, v169
	v_mul_f32_e32 v106, 0xbfb8aa3b, v106
	v_mul_f32_e32 v143, v143, v127
	v_rcp_f32_e32 v127, v168
	v_rcp_f32_e32 v169, v169
	v_mul_f32_e32 v142, v142, v127
	v_fma_f32 v169, v169, v163, v91
	v_cmp_gt_f32_e64 s[6:7], s69, v169
	v_mul_f32_e32 v107, 0xbfb8aa3b, v107
	v_exp_f32_e32 v106, v106
	v_cndmask_b32_e64 v170, 0, 32, s[6:7]
	v_ldexp_f32 v169, v169, v170
	v_exp_f32_e32 v170, v120
	v_max_f32_e32 v120, v121, v121
	v_med3_f32 v120, v120, s68, v188
	v_mul_f32_e32 v120, 0xbfb8aa3b, v120
	v_exp_f32_e32 v171, v120
	v_pk_mul_f32 v[120:121], v[142:143], v[162:163]
	v_log_f32_e32 v169, v169
	v_exp_f32_e32 v107, v107
	v_pk_add_f32 v[142:143], v[170:171], 1.0 op_sel_hi:[1,0]
	v_max_f32_e32 v100, v100, v100
	v_mul_f32_e32 v127, 0x3f317217, v169
	v_fma_f32 v127, v169, s70, -v127
	v_fmac_f32_e32 v127, 0x3377d1cf, v169
	v_rcp_f32_e32 v168, v142
	s_nop 0
	v_fma_f32 v168, v168, v136, v80
	v_cmp_gt_f32_e32 vcc, s69, v168
	v_fmac_f32_e32 v127, 0x3f317217, v169
	v_cmp_lt_f32_e64 s[8:9], |v169|, s71
	v_cndmask_b32_e64 v172, 0, 32, vcc
	v_ldexp_f32 v168, v168, v172
	v_log_f32_e32 v168, v168
	v_cndmask_b32_e64 v127, v169, v127, s[8:9]
	v_cndmask_b32_e64 v169, 0, v189, s[6:7]
	v_sub_f32_e32 v127, v127, v169
	v_mul_f32_e32 v169, 0x3f317217, v168
	v_fma_f32 v169, v168, s70, -v169
	v_fmac_f32_e32 v169, 0x3377d1cf, v168
	v_fmac_f32_e32 v169, 0x3f317217, v168
	v_cmp_lt_f32_e64 s[6:7], |v168|, s71
	v_med3_f32 v100, v100, s68, v188
	v_mul_f32_e32 v100, 0xbfb8aa3b, v100
	v_cndmask_b32_e64 v168, v168, v169, s[6:7]
	v_cndmask_b32_e32 v169, 0, v189, vcc
	v_sub_f32_e32 v168, v168, v169
	v_rcp_f32_e32 v169, v143
	v_max_f32_e32 v102, v102, v102
	v_mul_f32_e32 v171, v171, v169
	v_rcp_f32_e32 v169, v142
	v_rcp_f32_e32 v143, v143
	v_mul_f32_e32 v170, v170, v169
	v_fma_f32 v143, v143, v137, v81
	v_cmp_gt_f32_e64 s[6:7], s69, v143
	v_med3_f32 v102, v102, s68, v188
	v_mul_f32_e32 v102, 0xbfb8aa3b, v102
	v_cndmask_b32_e64 v172, 0, 32, s[6:7]
	v_ldexp_f32 v143, v143, v172
	v_pk_add_f32 v[172:173], v[122:123], 1.0 op_sel_hi:[1,0]
	v_log_f32_e32 v190, v143
	v_pk_mul_f32 v[142:143], v[170:171], v[136:137]
	v_mul_f32_e32 v169, 0x3f317217, v190
	v_fma_f32 v169, v190, s70, -v169
	v_fmac_f32_e32 v169, 0x3377d1cf, v190
	v_rcp_f32_e32 v170, v172
	s_nop 0
	v_fma_f32 v170, v170, v164, v82
	v_cmp_gt_f32_e32 vcc, s69, v170
	v_fmac_f32_e32 v169, 0x3f317217, v190
	v_cmp_lt_f32_e64 s[8:9], |v190|, s71
	v_cndmask_b32_e64 v171, 0, 32, vcc
	v_ldexp_f32 v170, v170, v171
	v_log_f32_e32 v170, v170
	v_cndmask_b32_e64 v169, v190, v169, s[8:9]
	v_cndmask_b32_e64 v171, 0, v189, s[6:7]
	v_sub_f32_e32 v169, v169, v171
	v_mul_f32_e32 v171, 0x3f317217, v170
	v_fma_f32 v171, v170, s70, -v171
	v_fmac_f32_e32 v171, 0x3377d1cf, v170
	v_fmac_f32_e32 v171, 0x3f317217, v170
	v_cmp_lt_f32_e64 s[6:7], |v170|, s71
	v_max_f32_e32 v96, v96, v96
	v_med3_f32 v96, v96, s68, v188
	v_cndmask_b32_e64 v170, v170, v171, s[6:7]
	v_cndmask_b32_e32 v171, 0, v189, vcc
	v_sub_f32_e32 v170, v170, v171
	v_rcp_f32_e32 v171, v173
	v_rcp_f32_e32 v190, v172
	v_mul_f32_e32 v123, v123, v171
	v_mul_f32_e32 v122, v122, v190
	v_rcp_f32_e32 v191, v173
	s_nop 0
	v_fma_f32 v191, v191, v165, v83
	v_cmp_gt_f32_e32 vcc, s69, v191
	v_pk_mul_f32 v[172:173], v[122:123], v[164:165]
	v_exp_f32_e32 v190, v116
	v_cndmask_b32_e64 v192, 0, 32, vcc
	v_ldexp_f32 v191, v191, v192
	v_log_f32_e32 v191, v191
	v_max_f32_e32 v116, v117, v117
	v_med3_f32 v116, v116, s68, v188
	v_mul_f32_e32 v116, 0xbfb8aa3b, v116
	v_mul_f32_e32 v122, 0x3f317217, v191
	v_fma_f32 v122, v191, s70, -v122
	v_fmac_f32_e32 v122, 0x3377d1cf, v191
	v_fmac_f32_e32 v122, 0x3f317217, v191
	v_cmp_lt_f32_e64 s[6:7], |v191|, s71
	v_cndmask_b32_e32 v123, 0, v189, vcc
	v_mul_f32_e32 v96, 0xbfb8aa3b, v96
	v_cndmask_b32_e64 v122, v191, v122, s[6:7]
	v_exp_f32_e32 v191, v116
	v_sub_f32_e32 v171, v122, v123
	v_lshl_add_u64 v[122:123], v[132:133], 2, s[18:19]
	global_store_dwordx4 v[122:123], v[124:127], off
	global_store_dwordx4 v[122:123], v[168:171], off offset:16
	v_max_f32_e32 v98, v98, v98
	v_cvt_pk_bf16_f32 v125, v120, v121
	v_pk_add_f32 v[168:169], v[190:191], 1.0 op_sel_hi:[1,0]
	v_cvt_pk_bf16_f32 v124, v134, v135
	v_cvt_pk_bf16_f32 v126, v142, v143
	v_max_f32_e32 v99, v99, v99
	v_med3_f32 v98, v98, s68, v188
	v_rcp_f32_e32 v116, v168
	s_nop 0
	v_fma_f32 v116, v116, v138, v76
	v_cmp_gt_f32_e32 vcc, s69, v116
	v_cvt_pk_bf16_f32 v127, v172, v173
	v_lshl_add_u64 v[120:121], v[132:133], 1, s[42:43]
	v_cndmask_b32_e64 v117, 0, 32, vcc
	v_ldexp_f32 v116, v116, v117
	v_log_f32_e32 v116, v116
	global_store_dwordx4 v[120:121], v[124:127], off
	v_med3_f32 v99, v99, s68, v188
	v_mul_f32_e32 v98, 0xbfb8aa3b, v98
	v_mul_f32_e32 v117, 0x3f317217, v116
	v_fma_f32 v117, v116, s70, -v117
	v_fmac_f32_e32 v117, 0x3377d1cf, v116
	v_fmac_f32_e32 v117, 0x3f317217, v116
	v_cmp_lt_f32_e64 s[6:7], |v116|, s71
	v_mul_f32_e32 v99, 0xbfb8aa3b, v99
	v_exp_f32_e32 v98, v98
; DI bf16x8 pack8(const f32x4& a, const f32x4& b) { v4u w; w.x = pk2(a[0], a[1]); w.y = pk2(a[2], a[3]); w.z = pk2(b[0], b[1]); w.w = pk2(b[2], b[3]); return __builtin_bit_cast(bf16x8, w); }
;     DI void operator()(const f32x4 (&acc)[2][2][4][2], const pg8::Unit& u, int wr, int wc, int fr, int fq) const {
;     ...
;         if (ty == 1) {
;             f32x4 lbv[2][2];
; #pragma unroll
;             for (int bj = 0; bj < 2; ++bj) { lbv[bj][0] = *(const f32x4*)(lb0 + cbase + bj * 128); lbv[bj][1] = *(const f32x4*)(lb0 + cbase + bj * 128 + 4); }
;             EPI_LOOP_BEGIN
; #pragma unroll
;                 for (int bj = 0; bj < 2; ++bj) { const size_t o = (size_t)row * D + cbase + bj * 128; f32x4 lg[2], kk[2];
; #pragma unroll
;                     for (int n = 0; n < 2; ++n)
; #pragma unroll
;                         for (int e = 0; e < 4; ++e) { const float f = fminf(fmaxf(acc[ai][bj][m][n][e], -30.f), 30.f), lb = lbv[bj][n][e], ef = __expf(-f), sg = 1.f / (1.f + ef), sgn = ef / (1.f + ef);
;                             lg[n][e] = __logf(lb + (1.f - lb) * sg); kk[n][e] = (1.f - lb) * sgn; }
;                     *(f32x4*)(lf + o) = lg[0]; *(f32x4*)(lf + o + 4) = lg[1]; *(bf16x8*)(zq + (size_t)T * D + o) = pack8(kk[0], kk[1]); }
	v_cndmask_b32_e64 v116, v116, v117, s[6:7]
	v_cndmask_b32_e32 v117, 0, v189, vcc
	v_sub_f32_e32 v116, v116, v117
	v_rcp_f32_e32 v117, v169
	v_exp_f32_e32 v99, v99
	v_mul_f32_e32 v125, v191, v117
	v_max_f32_e32 v92, v92, v92
	v_rcp_f32_e32 v124, v169
	s_nop 0
	v_fma_f32 v124, v124, v139, v77
	v_cmp_gt_f32_e64 s[6:7], s69, v124
	v_med3_f32 v92, v92, s68, v188
	v_mul_f32_e32 v92, 0xbfb8aa3b, v92
	v_cndmask_b32_e64 v126, 0, 32, s[6:7]
	v_ldexp_f32 v124, v124, v126
	v_exp_f32_e32 v126, v118
	v_max_f32_e32 v118, v119, v119
	v_med3_f32 v118, v118, s68, v188
	v_mul_f32_e32 v118, 0xbfb8aa3b, v118
	v_exp_f32_e32 v127, v118
	v_log_f32_e32 v134, v124
	v_rcp_f32_e32 v117, v168
	s_nop 0
	v_mul_f32_e32 v124, v190, v117
	v_pk_mul_f32 v[124:125], v[124:125], v[138:139]
	v_pk_add_f32 v[132:133], v[126:127], 1.0 op_sel_hi:[1,0]
	v_mul_f32_e32 v117, 0x3f317217, v134
	v_fma_f32 v117, v134, s70, -v117
	v_fmac_f32_e32 v117, 0x3377d1cf, v134
	v_fmac_f32_e32 v117, 0x3f317217, v134
	v_rcp_f32_e32 v118, v132
	s_nop 0
	v_fma_f32 v118, v118, v140, v78
	v_cmp_gt_f32_e32 vcc, s69, v118
	v_cmp_lt_f32_e64 s[8:9], |v134|, s71
	v_max_f32_e32 v94, v94, v94
	v_cndmask_b32_e64 v119, 0, 32, vcc
	v_ldexp_f32 v118, v118, v119
	v_log_f32_e32 v118, v118
	v_cndmask_b32_e64 v117, v134, v117, s[8:9]
	v_cndmask_b32_e64 v119, 0, v189, s[6:7]
	v_sub_f32_e32 v117, v117, v119
	v_mul_f32_e32 v119, 0x3f317217, v118
	v_fma_f32 v119, v118, s70, -v119
	v_fmac_f32_e32 v119, 0x3377d1cf, v118
	v_fmac_f32_e32 v119, 0x3f317217, v118
	v_cmp_lt_f32_e64 s[6:7], |v118|, s71
	v_med3_f32 v94, v94, s68, v188
	v_mul_f32_e32 v94, 0xbfb8aa3b, v94
	v_cndmask_b32_e64 v118, v118, v119, s[6:7]
	v_cndmask_b32_e32 v119, 0, v189, vcc
	v_sub_f32_e32 v118, v118, v119
	v_rcp_f32_e32 v119, v133
	v_max_f32_e32 v84, v84, v84
	v_mul_f32_e32 v127, v127, v119
	v_rcp_f32_e32 v119, v132
	v_rcp_f32_e32 v133, v133
	v_mul_f32_e32 v126, v126, v119
	v_fma_f32 v133, v133, v141, v79
	v_cmp_gt_f32_e64 s[6:7], s69, v133
	v_med3_f32 v84, v84, s68, v188
	v_mul_f32_e32 v84, 0xbfb8aa3b, v84
	v_cndmask_b32_e64 v134, 0, 32, s[6:7]
	v_ldexp_f32 v133, v133, v134
	v_exp_f32_e32 v134, v112
	v_max_f32_e32 v112, v113, v113
	v_med3_f32 v112, v112, s68, v188
	v_mul_f32_e32 v112, 0xbfb8aa3b, v112
	v_exp_f32_e32 v135, v112
	v_pk_mul_f32 v[112:113], v[126:127], v[140:141]
	v_log_f32_e32 v133, v133
	v_max_f32_e32 v86, v86, v86
	v_pk_add_f32 v[126:127], v[134:135], 1.0 op_sel_hi:[1,0]
	v_max_f32_e32 v87, v87, v87
	v_mul_f32_e32 v119, 0x3f317217, v133
	v_fma_f32 v119, v133, s70, -v119
	v_fmac_f32_e32 v119, 0x3377d1cf, v133
	v_rcp_f32_e32 v132, v126
	s_nop 0
	v_fma_f32 v132, v132, v128, v68
	v_cmp_gt_f32_e32 vcc, s69, v132
	v_fmac_f32_e32 v119, 0x3f317217, v133
	v_cmp_lt_f32_e64 s[8:9], |v133|, s71
	v_cndmask_b32_e64 v142, 0, 32, vcc
	v_ldexp_f32 v132, v132, v142
	v_log_f32_e32 v132, v132
	v_cndmask_b32_e64 v119, v133, v119, s[8:9]
	v_cndmask_b32_e64 v133, 0, v189, s[6:7]
	v_sub_f32_e32 v119, v119, v133
	v_mul_f32_e32 v133, 0x3f317217, v132
	v_fma_f32 v133, v132, s70, -v133
	v_fmac_f32_e32 v133, 0x3377d1cf, v132
	v_fmac_f32_e32 v133, 0x3f317217, v132
	v_cmp_lt_f32_e64 s[6:7], |v132|, s71
	v_med3_f32 v86, v86, s68, v188
	v_med3_f32 v87, v87, s68, v188
	v_cndmask_b32_e64 v132, v132, v133, s[6:7]
	v_cndmask_b32_e32 v133, 0, v189, vcc
	v_sub_f32_e32 v132, v132, v133
	v_rcp_f32_e32 v133, v127
	v_mul_f32_e32 v86, 0xbfb8aa3b, v86
	v_mul_f32_e32 v135, v135, v133
	v_rcp_f32_e32 v133, v126
	v_rcp_f32_e32 v127, v127
	v_mul_f32_e32 v134, v134, v133
	v_fma_f32 v127, v127, v129, v69
	v_cmp_gt_f32_e64 s[6:7], s69, v127
	v_mul_f32_e32 v87, 0xbfb8aa3b, v87
	v_exp_f32_e32 v86, v86
	v_cndmask_b32_e64 v142, 0, 32, s[6:7]
	v_ldexp_f32 v127, v127, v142
	v_pk_add_f32 v[142:143], v[114:115], 1.0 op_sel_hi:[1,0]
	v_log_f32_e32 v168, v127
	v_pk_mul_f32 v[126:127], v[134:135], v[128:129]
	v_mul_f32_e32 v133, 0x3f317217, v168
	v_fma_f32 v133, v168, s70, -v133
	v_fmac_f32_e32 v133, 0x3377d1cf, v168
	v_rcp_f32_e32 v134, v142
	s_nop 0
	v_fma_f32 v134, v134, v130, v70
	v_cmp_gt_f32_e32 vcc, s69, v134
	v_fmac_f32_e32 v133, 0x3f317217, v168
	v_cmp_lt_f32_e64 s[8:9], |v168|, s71
	v_cndmask_b32_e64 v135, 0, 32, vcc
	v_ldexp_f32 v134, v134, v135
	v_log_f32_e32 v134, v134
	v_cndmask_b32_e64 v133, v168, v133, s[8:9]
	v_cndmask_b32_e64 v135, 0, v189, s[6:7]
	v_sub_f32_e32 v133, v133, v135
	v_mul_f32_e32 v135, 0x3f317217, v134
	v_fma_f32 v135, v134, s70, -v135
	v_fmac_f32_e32 v135, 0x3377d1cf, v134
	v_fmac_f32_e32 v135, 0x3f317217, v134
	v_cmp_lt_f32_e64 s[6:7], |v134|, s71
	v_exp_f32_e32 v87, v87
	v_max_f32_e32 v72, v72, v72
	v_cndmask_b32_e64 v134, v134, v135, s[6:7]
	v_cndmask_b32_e32 v135, 0, v189, vcc
	v_sub_f32_e32 v134, v134, v135
	v_rcp_f32_e32 v135, v143
	v_rcp_f32_e32 v168, v142
	v_mul_f32_e32 v115, v115, v135
	v_mul_f32_e32 v114, v114, v168
	v_rcp_f32_e32 v169, v143
	s_nop 0
	v_fma_f32 v169, v169, v131, v71
	v_cmp_gt_f32_e32 vcc, s69, v169
	v_pk_mul_f32 v[142:143], v[114:115], v[130:131]
	v_med3_f32 v72, v72, s68, v188
	v_cndmask_b32_e64 v170, 0, 32, vcc
	v_ldexp_f32 v169, v169, v170
	v_log_f32_e32 v169, v169
	v_cndmask_b32_e32 v115, 0, v189, vcc
	v_mul_f32_e32 v72, 0xbfb8aa3b, v72
	v_max_f32_e32 v74, v74, v74
	v_mul_f32_e32 v114, 0x3f317217, v169
	v_fma_f32 v114, v169, s70, -v114
	v_fmac_f32_e32 v114, 0x3377d1cf, v169
	v_fmac_f32_e32 v114, 0x3f317217, v169
	v_cmp_lt_f32_e64 s[6:7], |v169|, s71
	v_med3_f32 v74, v74, s68, v188
	v_mul_f32_e32 v74, 0xbfb8aa3b, v74
	v_cndmask_b32_e64 v114, v169, v114, s[6:7]
	v_sub_f32_e32 v135, v114, v115
	global_store_dwordx4 v[122:123], v[116:119], off offset:512
	global_store_dwordx4 v[122:123], v[132:135], off offset:528
	v_cvt_pk_bf16_f32 v115, v112, v113
; DI bf16x8 pack8(const f32x4& a, const f32x4& b) { v4u w; w.x = pk2(a[0], a[1]); w.y = pk2(a[2], a[3]); w.z = pk2(b[0], b[1]); w.w = pk2(b[2], b[3]); return __builtin_bit_cast(bf16x8, w); }
;     DI void operator()(const f32x4 (&acc)[2][2][4][2], const pg8::Unit& u, int wr, int wc, int fr, int fq) const {
;     ...
;         if (ty == 1) {
;             f32x4 lbv[2][2];
; #pragma unroll
;             for (int bj = 0; bj < 2; ++bj) { lbv[bj][0] = *(const f32x4*)(lb0 + cbase + bj * 128); lbv[bj][1] = *(const f32x4*)(lb0 + cbase + bj * 128 + 4); }
;             EPI_LOOP_BEGIN
; #pragma unroll
;                 for (int bj = 0; bj < 2; ++bj) { const size_t o = (size_t)row * D + cbase + bj * 128; f32x4 lg[2], kk[2];
; #pragma unroll
;                     for (int n = 0; n < 2; ++n)
; #pragma unroll
;                         for (int e = 0; e < 4; ++e) { const float f = fminf(fmaxf(acc[ai][bj][m][n][e], -30.f), 30.f), lb = lbv[bj][n][e], ef = __expf(-f), sg = 1.f / (1.f + ef), sgn = ef / (1.f + ef);
;                             lg[n][e] = __logf(lb + (1.f - lb) * sg); kk[n][e] = (1.f - lb) * sgn; }
;                     *(f32x4*)(lf + o) = lg[0]; *(f32x4*)(lf + o + 4) = lg[1]; *(bf16x8*)(zq + (size_t)T * D + o) = pack8(kk[0], kk[1]); }
	v_exp_f32_e32 v118, v108
	v_max_f32_e32 v108, v109, v109
	v_med3_f32 v108, v108, s68, v188
	v_mul_f32_e32 v108, 0xbfb8aa3b, v108
	v_exp_f32_e32 v119, v108
	v_cvt_pk_bf16_f32 v114, v124, v125
	v_cvt_pk_bf16_f32 v116, v126, v127
	v_cvt_pk_bf16_f32 v117, v142, v143
	v_pk_add_f32 v[122:123], v[118:119], 1.0 op_sel_hi:[1,0]
	global_store_dwordx4 v[120:121], v[114:117], off offset:256
	v_add_u32_e32 v108, s45, v179
	v_max_f32_e32 v64, v64, v64
	v_med3_f32 v64, v64, s68, v188
	v_rcp_f32_e32 v109, v122
	s_nop 0
	v_fma_f32 v109, v109, v166, v88
	v_cmp_gt_f32_e32 vcc, s69, v109
	v_mul_f32_e32 v64, 0xbfb8aa3b, v64
	v_max_f32_e32 v66, v66, v66
	v_cndmask_b32_e64 v112, 0, 32, vcc
	v_ldexp_f32 v109, v109, v112
	v_log_f32_e32 v114, v109
	v_ashrrev_i32_e32 v109, 31, v108
	v_lshlrev_b64 v[108:109], 11, v[108:109]
	v_lshl_add_u64 v[112:113], v[108:109], 0, v[160:161]
	v_mul_f32_e32 v108, 0x3f317217, v114
	v_fma_f32 v108, v114, s70, -v108
	v_fmac_f32_e32 v108, 0x3377d1cf, v114
	v_fmac_f32_e32 v108, 0x3f317217, v114
	v_cmp_lt_f32_e64 s[6:7], |v114|, s71
	v_max_f32_e32 v67, v67, v67
	v_med3_f32 v66, v66, s68, v188
	v_cndmask_b32_e64 v108, v114, v108, s[6:7]
	v_cndmask_b32_e32 v114, 0, v189, vcc
	v_sub_f32_e32 v108, v108, v114
	v_rcp_f32_e32 v109, v123
	s_nop 0
	v_mul_f32_e32 v115, v119, v109
	v_med3_f32 v67, v67, s68, v188
	v_mul_f32_e32 v66, 0xbfb8aa3b, v66
	v_rcp_f32_e32 v114, v123
	s_nop 0
	v_fma_f32 v114, v114, v167, v89
	v_cmp_gt_f32_e64 s[6:7], s69, v114
	v_mul_f32_e32 v67, 0xbfb8aa3b, v67
	v_exp_f32_e32 v66, v66
	v_cndmask_b32_e64 v116, 0, 32, s[6:7]
	v_ldexp_f32 v114, v114, v116
	v_exp_f32_e32 v116, v110
	v_max_f32_e32 v110, v111, v111
	v_med3_f32 v110, v110, s68, v188
	v_mul_f32_e32 v110, 0xbfb8aa3b, v110
	v_exp_f32_e32 v117, v110
	v_log_f32_e32 v120, v114
	v_rcp_f32_e32 v109, v122
	s_nop 0
	v_mul_f32_e32 v114, v118, v109
	v_pk_mul_f32 v[114:115], v[114:115], v[166:167]
	v_pk_add_f32 v[118:119], v[116:117], 1.0 op_sel_hi:[1,0]
	v_mul_f32_e32 v109, 0x3f317217, v120
	v_fma_f32 v109, v120, s70, -v109
	v_fmac_f32_e32 v109, 0x3377d1cf, v120
	v_fmac_f32_e32 v109, 0x3f317217, v120
	v_rcp_f32_e32 v110, v118
	s_nop 0
	v_fma_f32 v110, v110, v162, v90
	v_cmp_gt_f32_e32 vcc, s69, v110
	v_cmp_lt_f32_e64 s[8:9], |v120|, s71
	v_exp_f32_e32 v67, v67
	v_cndmask_b32_e64 v111, 0, 32, vcc
	v_ldexp_f32 v110, v110, v111
	v_log_f32_e32 v110, v110
	v_cndmask_b32_e64 v109, v120, v109, s[8:9]
	v_cndmask_b32_e64 v111, 0, v189, s[6:7]
	v_sub_f32_e32 v109, v109, v111
	v_mul_f32_e32 v111, 0x3f317217, v110
	v_fma_f32 v111, v110, s70, -v111
	v_fmac_f32_e32 v111, 0x3377d1cf, v110
	v_fmac_f32_e32 v111, 0x3f317217, v110
	v_cmp_lt_f32_e64 s[6:7], |v110|, s71
	v_max_f32_e32 v60, v60, v60
	v_med3_f32 v60, v60, s68, v188
	v_cndmask_b32_e64 v110, v110, v111, s[6:7]
	v_cndmask_b32_e32 v111, 0, v189, vcc
	v_sub_f32_e32 v110, v110, v111
	v_rcp_f32_e32 v111, v119
	v_mul_f32_e32 v60, 0xbfb8aa3b, v60
	v_mul_f32_e32 v117, v117, v111
	v_rcp_f32_e32 v111, v118
	v_rcp_f32_e32 v119, v119
	v_mul_f32_e32 v116, v116, v111
	v_fma_f32 v119, v119, v163, v91
	v_cmp_gt_f32_e64 s[6:7], s69, v119
	v_max_f32_e32 v62, v62, v62
	v_med3_f32 v62, v62, s68, v188
	v_cndmask_b32_e64 v120, 0, 32, s[6:7]
	v_ldexp_f32 v119, v119, v120
	v_exp_f32_e32 v120, v104
	v_max_f32_e32 v104, v105, v105
	v_med3_f32 v104, v104, s68, v188
	v_mul_f32_e32 v104, 0xbfb8aa3b, v104
	v_exp_f32_e32 v121, v104
	v_log_f32_e32 v122, v119
	v_pk_mul_f32 v[104:105], v[116:117], v[162:163]
	v_mul_f32_e32 v62, 0xbfb8aa3b, v62
	v_pk_add_f32 v[118:119], v[120:121], 1.0 op_sel_hi:[1,0]
	v_mul_f32_e32 v111, 0x3f317217, v122
	v_fma_f32 v111, v122, s70, -v111
	v_fmac_f32_e32 v111, 0x3377d1cf, v122
	v_fmac_f32_e32 v111, 0x3f317217, v122
	v_rcp_f32_e32 v116, v118
	s_nop 0
	v_fma_f32 v116, v116, v136, v80
	v_cmp_gt_f32_e32 vcc, s69, v116
	v_cmp_lt_f32_e64 s[8:9], |v122|, s71
	v_max_f32_e32 v56, v56, v56
	v_cndmask_b32_e64 v117, 0, 32, vcc
	v_ldexp_f32 v116, v116, v117
	v_log_f32_e32 v116, v116
	v_cndmask_b32_e64 v111, v122, v111, s[8:9]
	v_cndmask_b32_e64 v117, 0, v189, s[6:7]
	v_sub_f32_e32 v111, v111, v117
	v_mul_f32_e32 v117, 0x3f317217, v116
	v_fma_f32 v117, v116, s70, -v117
	v_fmac_f32_e32 v117, 0x3377d1cf, v116
	v_fmac_f32_e32 v117, 0x3f317217, v116
	v_cmp_lt_f32_e64 s[6:7], |v116|, s71
	v_med3_f32 v56, v56, s68, v188
	v_mul_f32_e32 v56, 0xbfb8aa3b, v56
	v_cndmask_b32_e64 v116, v116, v117, s[6:7]
	v_cndmask_b32_e32 v117, 0, v189, vcc
	v_sub_f32_e32 v116, v116, v117
	v_rcp_f32_e32 v117, v119
	v_max_f32_e32 v58, v58, v58
	v_mul_f32_e32 v121, v121, v117
	v_rcp_f32_e32 v117, v118
	v_rcp_f32_e32 v119, v119
	v_mul_f32_e32 v120, v120, v117
	v_fma_f32 v119, v119, v137, v81
	v_cmp_gt_f32_e64 s[6:7], s69, v119
	v_pk_mul_f32 v[120:121], v[120:121], v[136:137]
	v_max_f32_e32 v59, v59, v59
	v_cndmask_b32_e64 v122, 0, 32, s[6:7]
	v_ldexp_f32 v119, v119, v122
	v_pk_add_f32 v[122:123], v[106:107], 1.0 op_sel_hi:[1,0]
	v_log_f32_e32 v119, v119
	s_nop 0
	v_mul_f32_e32 v117, 0x3f317217, v119
	v_fma_f32 v117, v119, s70, -v117
	v_fmac_f32_e32 v117, 0x3377d1cf, v119
	v_rcp_f32_e32 v118, v122
	s_nop 0
	v_fma_f32 v118, v118, v164, v82
	v_cmp_gt_f32_e32 vcc, s69, v118
	v_fmac_f32_e32 v117, 0x3f317217, v119
	v_cmp_lt_f32_e64 s[8:9], |v119|, s71
	v_cndmask_b32_e64 v124, 0, 32, vcc
	v_ldexp_f32 v118, v118, v124
	v_log_f32_e32 v118, v118
	v_cndmask_b32_e64 v117, v119, v117, s[8:9]
	v_cndmask_b32_e64 v119, 0, v189, s[6:7]
	v_sub_f32_e32 v117, v117, v119
	v_mul_f32_e32 v119, 0x3f317217, v118
	v_fma_f32 v119, v118, s70, -v119
	v_fmac_f32_e32 v119, 0x3377d1cf, v118
	v_fmac_f32_e32 v119, 0x3f317217, v118
	v_cmp_lt_f32_e64 s[6:7], |v118|, s71
	v_med3_f32 v58, v58, s68, v188
; DI bf16x8 pack8(const f32x4& a, const f32x4& b) { v4u w; w.x = pk2(a[0], a[1]); w.y = pk2(a[2], a[3]); w.z = pk2(b[0], b[1]); w.w = pk2(b[2], b[3]); return __builtin_bit_cast(bf16x8, w); }
;     DI void operator()(const f32x4 (&acc)[2][2][4][2], const pg8::Unit& u, int wr, int wc, int fr, int fq) const {
;     ...
;         if (ty == 1) {
;             f32x4 lbv[2][2];
; #pragma unroll
;             for (int bj = 0; bj < 2; ++bj) { lbv[bj][0] = *(const f32x4*)(lb0 + cbase + bj * 128); lbv[bj][1] = *(const f32x4*)(lb0 + cbase + bj * 128 + 4); }
;             EPI_LOOP_BEGIN
; #pragma unroll
;                 for (int bj = 0; bj < 2; ++bj) { const size_t o = (size_t)row * D + cbase + bj * 128; f32x4 lg[2], kk[2];
; #pragma unroll
;                     for (int n = 0; n < 2; ++n)
; #pragma unroll
;                         for (int e = 0; e < 4; ++e) { const float f = fminf(fmaxf(acc[ai][bj][m][n][e], -30.f), 30.f), lb = lbv[bj][n][e], ef = __expf(-f), sg = 1.f / (1.f + ef), sgn = ef / (1.f + ef);
;                             lg[n][e] = __logf(lb + (1.f - lb) * sg); kk[n][e] = (1.f - lb) * sgn; }
;                     *(f32x4*)(lf + o) = lg[0]; *(f32x4*)(lf + o + 4) = lg[1]; *(bf16x8*)(zq + (size_t)T * D + o) = pack8(kk[0], kk[1]); }
	v_med3_f32 v59, v59, s68, v188
	v_cndmask_b32_e64 v118, v118, v119, s[6:7]
	v_cndmask_b32_e32 v119, 0, v189, vcc
	v_sub_f32_e32 v118, v118, v119
	v_rcp_f32_e32 v119, v123
	v_rcp_f32_e32 v124, v122
	v_mul_f32_e32 v107, v107, v119
	v_mul_f32_e32 v106, v106, v124
	v_rcp_f32_e32 v125, v123
	s_nop 0
	v_fma_f32 v125, v125, v165, v83
	v_cmp_gt_f32_e32 vcc, s69, v125
	v_pk_mul_f32 v[122:123], v[106:107], v[164:165]
	v_exp_f32_e32 v124, v100
	v_cndmask_b32_e64 v126, 0, 32, vcc
	v_ldexp_f32 v125, v125, v126
	v_log_f32_e32 v125, v125
	v_max_f32_e32 v100, v101, v101
	v_med3_f32 v100, v100, s68, v188
	v_mul_f32_e32 v100, 0xbfb8aa3b, v100
	v_mul_f32_e32 v106, 0x3f317217, v125
	v_fma_f32 v106, v125, s70, -v106
	v_fmac_f32_e32 v106, 0x3377d1cf, v125
	v_fmac_f32_e32 v106, 0x3f317217, v125
	v_cmp_lt_f32_e64 s[6:7], |v125|, s71
	v_cndmask_b32_e32 v107, 0, v189, vcc
	v_mul_f32_e32 v58, 0xbfb8aa3b, v58
	v_cndmask_b32_e64 v106, v125, v106, s[6:7]
	v_exp_f32_e32 v125, v100
	v_sub_f32_e32 v119, v106, v107
	v_lshl_add_u64 v[106:107], v[112:113], 2, s[18:19]
	global_store_dwordx4 v[106:107], v[108:111], off
	global_store_dwordx4 v[106:107], v[116:119], off offset:16
	v_mul_f32_e32 v59, 0xbfb8aa3b, v59
	v_cvt_pk_bf16_f32 v109, v104, v105
	v_pk_add_f32 v[116:117], v[124:125], 1.0 op_sel_hi:[1,0]
	v_cvt_pk_bf16_f32 v108, v114, v115
	v_cvt_pk_bf16_f32 v110, v120, v121
	v_exp_f32_e32 v58, v58
	v_exp_f32_e32 v59, v59
	v_rcp_f32_e32 v100, v116
	s_nop 0
	v_fma_f32 v100, v100, v138, v76
	v_cmp_gt_f32_e32 vcc, s69, v100
	v_cvt_pk_bf16_f32 v111, v122, v123
	v_lshl_add_u64 v[104:105], v[112:113], 1, s[42:43]
	v_cndmask_b32_e64 v101, 0, 32, vcc
	v_ldexp_f32 v100, v100, v101
	v_log_f32_e32 v100, v100
	global_store_dwordx4 v[104:105], v[108:111], off
	v_max_f32_e32 v52, v52, v52
	v_med3_f32 v52, v52, s68, v188
	v_mul_f32_e32 v101, 0x3f317217, v100
	v_fma_f32 v101, v100, s70, -v101
	v_fmac_f32_e32 v101, 0x3377d1cf, v100
	v_fmac_f32_e32 v101, 0x3f317217, v100
	v_cmp_lt_f32_e64 s[6:7], |v100|, s71
	v_mul_f32_e32 v52, 0xbfb8aa3b, v52
	v_max_f32_e32 v54, v54, v54
	v_cndmask_b32_e64 v100, v100, v101, s[6:7]
	v_cndmask_b32_e32 v101, 0, v189, vcc
	v_sub_f32_e32 v100, v100, v101
	v_rcp_f32_e32 v101, v117
	s_nop 0
	v_mul_f32_e32 v109, v125, v101
	v_med3_f32 v54, v54, s68, v188
	v_mul_f32_e32 v54, 0xbfb8aa3b, v54
	v_rcp_f32_e32 v108, v117
	s_nop 0
	v_fma_f32 v108, v108, v139, v77
	v_cmp_gt_f32_e64 s[6:7], s69, v108
	v_max_f32_e32 v48, v48, v48
	v_med3_f32 v48, v48, s68, v188
	v_cndmask_b32_e64 v110, 0, 32, s[6:7]
	v_ldexp_f32 v108, v108, v110
	v_exp_f32_e32 v110, v102
	v_max_f32_e32 v102, v103, v103
	v_med3_f32 v102, v102, s68, v188
	v_mul_f32_e32 v102, 0xbfb8aa3b, v102
	v_exp_f32_e32 v111, v102
	v_log_f32_e32 v114, v108
	v_rcp_f32_e32 v101, v116
	s_nop 0
	v_mul_f32_e32 v108, v124, v101
	v_pk_mul_f32 v[108:109], v[108:109], v[138:139]
	v_pk_add_f32 v[112:113], v[110:111], 1.0 op_sel_hi:[1,0]
	v_mul_f32_e32 v101, 0x3f317217, v114
	v_fma_f32 v101, v114, s70, -v101
	v_fmac_f32_e32 v101, 0x3377d1cf, v114
	v_fmac_f32_e32 v101, 0x3f317217, v114
	v_rcp_f32_e32 v102, v112
	s_nop 0
	v_fma_f32 v102, v102, v140, v78
	v_cmp_gt_f32_e32 vcc, s69, v102
	v_cmp_lt_f32_e64 s[8:9], |v114|, s71
	v_mul_f32_e32 v48, 0xbfb8aa3b, v48
	v_cndmask_b32_e64 v103, 0, 32, vcc
	v_ldexp_f32 v102, v102, v103
	v_log_f32_e32 v102, v102
	v_cndmask_b32_e64 v101, v114, v101, s[8:9]
	v_cndmask_b32_e64 v103, 0, v189, s[6:7]
	v_sub_f32_e32 v101, v101, v103
	v_mul_f32_e32 v103, 0x3f317217, v102
	v_fma_f32 v103, v102, s70, -v103
	v_fmac_f32_e32 v103, 0x3377d1cf, v102
	v_fmac_f32_e32 v103, 0x3f317217, v102
	v_cmp_lt_f32_e64 s[6:7], |v102|, s71
	v_max_f32_e32 v50, v50, v50
	v_max_f32_e32 v51, v51, v51
	v_cndmask_b32_e64 v102, v102, v103, s[6:7]
	v_cndmask_b32_e32 v103, 0, v189, vcc
	v_sub_f32_e32 v102, v102, v103
	v_rcp_f32_e32 v103, v113
	s_nop 0
	v_mul_f32_e32 v111, v111, v103
	v_med3_f32 v50, v50, s68, v188
	v_rcp_f32_e32 v103, v112
	v_rcp_f32_e32 v113, v113
	v_mul_f32_e32 v110, v110, v103
	v_fma_f32 v113, v113, v141, v79
	v_cmp_gt_f32_e64 s[6:7], s69, v113
	v_med3_f32 v51, v51, s68, v188
	v_mul_f32_e32 v50, 0xbfb8aa3b, v50
	v_cndmask_b32_e64 v114, 0, 32, s[6:7]
	v_ldexp_f32 v113, v113, v114
	v_exp_f32_e32 v114, v96
	v_max_f32_e32 v96, v97, v97
	v_med3_f32 v96, v96, s68, v188
	v_mul_f32_e32 v96, 0xbfb8aa3b, v96
	v_exp_f32_e32 v115, v96
	v_log_f32_e32 v116, v113
	v_pk_mul_f32 v[96:97], v[110:111], v[140:141]
	v_mul_f32_e32 v51, 0xbfb8aa3b, v51
	v_pk_add_f32 v[112:113], v[114:115], 1.0 op_sel_hi:[1,0]
	v_mul_f32_e32 v103, 0x3f317217, v116
	v_fma_f32 v103, v116, s70, -v103
	v_fmac_f32_e32 v103, 0x3377d1cf, v116
	v_fmac_f32_e32 v103, 0x3f317217, v116
	v_rcp_f32_e32 v110, v112
	s_nop 0
	v_fma_f32 v110, v110, v128, v68
	v_cmp_gt_f32_e32 vcc, s69, v110
	v_cmp_lt_f32_e64 s[8:9], |v116|, s71
	v_exp_f32_e32 v50, v50
	v_cndmask_b32_e64 v111, 0, 32, vcc
	v_ldexp_f32 v110, v110, v111
	v_log_f32_e32 v110, v110
	v_cndmask_b32_e64 v103, v116, v103, s[8:9]
	v_cndmask_b32_e64 v111, 0, v189, s[6:7]
	v_sub_f32_e32 v103, v103, v111
	v_mul_f32_e32 v111, 0x3f317217, v110
	v_fma_f32 v111, v110, s70, -v111
	v_fmac_f32_e32 v111, 0x3377d1cf, v110
	v_fmac_f32_e32 v111, 0x3f317217, v110
	v_cmp_lt_f32_e64 s[6:7], |v110|, s71
	v_exp_f32_e32 v51, v51
	v_max_f32_e32 v44, v44, v44
	v_cndmask_b32_e64 v110, v110, v111, s[6:7]
	v_cndmask_b32_e32 v111, 0, v189, vcc
	v_sub_f32_e32 v110, v110, v111
	v_rcp_f32_e32 v111, v113
	s_nop 0
	v_mul_f32_e32 v115, v115, v111
	v_med3_f32 v44, v44, s68, v188
	v_rcp_f32_e32 v111, v112
	v_rcp_f32_e32 v113, v113
	v_mul_f32_e32 v114, v114, v111
	v_fma_f32 v113, v113, v129, v69
	v_cmp_gt_f32_e64 s[6:7], s69, v113
; DI bf16x8 pack8(const f32x4& a, const f32x4& b) { v4u w; w.x = pk2(a[0], a[1]); w.y = pk2(a[2], a[3]); w.z = pk2(b[0], b[1]); w.w = pk2(b[2], b[3]); return __builtin_bit_cast(bf16x8, w); }
;     DI void operator()(const f32x4 (&acc)[2][2][4][2], const pg8::Unit& u, int wr, int wc, int fr, int fq) const {
;     ...
;         if (ty == 1) {
;             f32x4 lbv[2][2];
; #pragma unroll
;             for (int bj = 0; bj < 2; ++bj) { lbv[bj][0] = *(const f32x4*)(lb0 + cbase + bj * 128); lbv[bj][1] = *(const f32x4*)(lb0 + cbase + bj * 128 + 4); }
;             EPI_LOOP_BEGIN
; #pragma unroll
;                 for (int bj = 0; bj < 2; ++bj) { const size_t o = (size_t)row * D + cbase + bj * 128; f32x4 lg[2], kk[2];
; #pragma unroll
;                     for (int n = 0; n < 2; ++n)
; #pragma unroll
;                         for (int e = 0; e < 4; ++e) { const float f = fminf(fmaxf(acc[ai][bj][m][n][e], -30.f), 30.f), lb = lbv[bj][n][e], ef = __expf(-f), sg = 1.f / (1.f + ef), sgn = ef / (1.f + ef);
;                             lg[n][e] = __logf(lb + (1.f - lb) * sg); kk[n][e] = (1.f - lb) * sgn; }
;                     *(f32x4*)(lf + o) = lg[0]; *(f32x4*)(lf + o + 4) = lg[1]; *(bf16x8*)(zq + (size_t)T * D + o) = pack8(kk[0], kk[1]); }
	v_pk_mul_f32 v[114:115], v[114:115], v[128:129]
	v_mul_f32_e32 v44, 0xbfb8aa3b, v44
	v_cndmask_b32_e64 v116, 0, 32, s[6:7]
	v_ldexp_f32 v113, v113, v116
	v_pk_add_f32 v[116:117], v[98:99], 1.0 op_sel_hi:[1,0]
	v_log_f32_e32 v113, v113
	s_nop 0
	v_mul_f32_e32 v111, 0x3f317217, v113
	v_fma_f32 v111, v113, s70, -v111
	v_fmac_f32_e32 v111, 0x3377d1cf, v113
	v_rcp_f32_e32 v112, v116
	s_nop 0
	v_fma_f32 v112, v112, v130, v70
	v_cmp_gt_f32_e32 vcc, s69, v112
	v_fmac_f32_e32 v111, 0x3f317217, v113
	v_cmp_lt_f32_e64 s[8:9], |v113|, s71
	v_cndmask_b32_e64 v118, 0, 32, vcc
	v_ldexp_f32 v112, v112, v118
	v_log_f32_e32 v112, v112
	v_cndmask_b32_e64 v111, v113, v111, s[8:9]
	v_cndmask_b32_e64 v113, 0, v189, s[6:7]
	v_sub_f32_e32 v111, v111, v113
	v_mul_f32_e32 v113, 0x3f317217, v112
	v_fma_f32 v113, v112, s70, -v113
	v_fmac_f32_e32 v113, 0x3377d1cf, v112
	v_fmac_f32_e32 v113, 0x3f317217, v112
	v_cmp_lt_f32_e64 s[6:7], |v112|, s71
	v_max_f32_e32 v46, v46, v46
	v_med3_f32 v46, v46, s68, v188
	v_cndmask_b32_e64 v112, v112, v113, s[6:7]
	v_cndmask_b32_e32 v113, 0, v189, vcc
	v_sub_f32_e32 v112, v112, v113
	v_rcp_f32_e32 v113, v117
	v_rcp_f32_e32 v118, v116
	v_mul_f32_e32 v99, v99, v113
	v_mul_f32_e32 v98, v98, v118
	v_rcp_f32_e32 v119, v117
	s_nop 0
	v_fma_f32 v119, v119, v131, v71
	v_cmp_gt_f32_e32 vcc, s69, v119
	v_pk_mul_f32 v[116:117], v[98:99], v[130:131]
	v_mul_f32_e32 v46, 0xbfb8aa3b, v46
	v_cndmask_b32_e64 v120, 0, 32, vcc
	v_ldexp_f32 v119, v119, v120
	v_log_f32_e32 v119, v119
	v_cndmask_b32_e32 v99, 0, v189, vcc
	v_max_f32_e32 v40, v40, v40
	v_med3_f32 v40, v40, s68, v188
	v_mul_f32_e32 v98, 0x3f317217, v119
	v_fma_f32 v98, v119, s70, -v98
	v_fmac_f32_e32 v98, 0x3377d1cf, v119
	v_fmac_f32_e32 v98, 0x3f317217, v119
	v_cmp_lt_f32_e64 s[6:7], |v119|, s71
	v_mul_f32_e32 v40, 0xbfb8aa3b, v40
	v_max_f32_e32 v42, v42, v42
	v_cndmask_b32_e64 v98, v119, v98, s[6:7]
	v_sub_f32_e32 v113, v98, v99
	global_store_dwordx4 v[106:107], v[100:103], off offset:512
	global_store_dwordx4 v[106:107], v[110:113], off offset:528
	v_cvt_pk_bf16_f32 v99, v96, v97
	v_exp_f32_e32 v102, v92
	v_max_f32_e32 v92, v93, v93
	v_med3_f32 v92, v92, s68, v188
	v_mul_f32_e32 v92, 0xbfb8aa3b, v92
	v_exp_f32_e32 v103, v92
	v_cvt_pk_bf16_f32 v98, v108, v109
	v_cvt_pk_bf16_f32 v100, v114, v115
	v_cvt_pk_bf16_f32 v101, v116, v117
	v_pk_add_f32 v[106:107], v[102:103], 1.0 op_sel_hi:[1,0]
	global_store_dwordx4 v[104:105], v[98:101], off offset:256
	v_add_u32_e32 v92, s45, v180
	v_max_f32_e32 v43, v43, v43
	v_med3_f32 v42, v42, s68, v188
	v_rcp_f32_e32 v93, v106
	s_nop 0
	v_fma_f32 v93, v93, v166, v88
	v_cmp_gt_f32_e32 vcc, s69, v93
	v_med3_f32 v43, v43, s68, v188
	v_mul_f32_e32 v42, 0xbfb8aa3b, v42
	v_cndmask_b32_e64 v96, 0, 32, vcc
	v_ldexp_f32 v93, v93, v96
	v_log_f32_e32 v98, v93
	v_ashrrev_i32_e32 v93, 31, v92
	v_lshlrev_b64 v[92:93], 11, v[92:93]
	v_lshl_add_u64 v[96:97], v[92:93], 0, v[160:161]
	v_mul_f32_e32 v92, 0x3f317217, v98
	v_fma_f32 v92, v98, s70, -v92
	v_fmac_f32_e32 v92, 0x3377d1cf, v98
	v_fmac_f32_e32 v92, 0x3f317217, v98
	v_cmp_lt_f32_e64 s[6:7], |v98|, s71
	v_mul_f32_e32 v43, 0xbfb8aa3b, v43
	v_exp_f32_e32 v42, v42
	v_cndmask_b32_e64 v92, v98, v92, s[6:7]
	v_cndmask_b32_e32 v98, 0, v189, vcc
	v_sub_f32_e32 v92, v92, v98
	v_rcp_f32_e32 v93, v107
	v_exp_f32_e32 v43, v43
	v_mul_f32_e32 v99, v103, v93
	v_max_f32_e32 v36, v36, v36
	v_rcp_f32_e32 v98, v107
	s_nop 0
	v_fma_f32 v98, v98, v167, v89
	v_cmp_gt_f32_e64 s[6:7], s69, v98
	v_med3_f32 v36, v36, s68, v188
	v_mul_f32_e32 v36, 0xbfb8aa3b, v36
	v_cndmask_b32_e64 v100, 0, 32, s[6:7]
	v_ldexp_f32 v98, v98, v100
	v_exp_f32_e32 v100, v94
	v_max_f32_e32 v94, v95, v95
	v_med3_f32 v94, v94, s68, v188
	v_mul_f32_e32 v94, 0xbfb8aa3b, v94
	v_exp_f32_e32 v101, v94
	v_log_f32_e32 v104, v98
	v_rcp_f32_e32 v93, v106
	s_nop 0
	v_mul_f32_e32 v98, v102, v93
	v_pk_mul_f32 v[98:99], v[98:99], v[166:167]
	v_pk_add_f32 v[102:103], v[100:101], 1.0 op_sel_hi:[1,0]
	v_mul_f32_e32 v93, 0x3f317217, v104
	v_fma_f32 v93, v104, s70, -v93
	v_fmac_f32_e32 v93, 0x3377d1cf, v104
	v_fmac_f32_e32 v93, 0x3f317217, v104
	v_rcp_f32_e32 v94, v102
	s_nop 0
	v_fma_f32 v94, v94, v162, v90
	v_cmp_gt_f32_e32 vcc, s69, v94
	v_cmp_lt_f32_e64 s[8:9], |v104|, s71
	v_max_f32_e32 v38, v38, v38
	v_cndmask_b32_e64 v95, 0, 32, vcc
	v_ldexp_f32 v94, v94, v95
	v_log_f32_e32 v94, v94
	v_cndmask_b32_e64 v93, v104, v93, s[8:9]
	v_cndmask_b32_e64 v95, 0, v189, s[6:7]
	v_sub_f32_e32 v93, v93, v95
	v_mul_f32_e32 v95, 0x3f317217, v94
	v_fma_f32 v95, v94, s70, -v95
	v_fmac_f32_e32 v95, 0x3377d1cf, v94
	v_fmac_f32_e32 v95, 0x3f317217, v94
	v_cmp_lt_f32_e64 s[6:7], |v94|, s71
	v_med3_f32 v38, v38, s68, v188
	v_mul_f32_e32 v38, 0xbfb8aa3b, v38
	v_cndmask_b32_e64 v94, v94, v95, s[6:7]
	v_cndmask_b32_e32 v95, 0, v189, vcc
	v_sub_f32_e32 v94, v94, v95
	v_rcp_f32_e32 v95, v103
	v_max_f32_e32 v32, v32, v32
	v_mul_f32_e32 v101, v101, v95
	v_rcp_f32_e32 v95, v102
	v_rcp_f32_e32 v103, v103
	v_mul_f32_e32 v100, v100, v95
	v_fma_f32 v103, v103, v163, v91
	v_cmp_gt_f32_e64 s[6:7], s69, v103
	v_med3_f32 v32, v32, s68, v188
	v_mul_f32_e32 v32, 0xbfb8aa3b, v32
	v_cndmask_b32_e64 v104, 0, 32, s[6:7]
	v_ldexp_f32 v103, v103, v104
	v_exp_f32_e32 v104, v84
	v_max_f32_e32 v84, v85, v85
	v_med3_f32 v84, v84, s68, v188
	v_mul_f32_e32 v84, 0xbfb8aa3b, v84
	v_exp_f32_e32 v105, v84
	v_log_f32_e32 v106, v103
	v_pk_mul_f32 v[84:85], v[100:101], v[162:163]
	v_max_f32_e32 v34, v34, v34
	v_pk_add_f32 v[102:103], v[104:105], 1.0 op_sel_hi:[1,0]
	v_mul_f32_e32 v95, 0x3f317217, v106
	v_fma_f32 v95, v106, s70, -v95
	v_fmac_f32_e32 v95, 0x3377d1cf, v106
	v_fmac_f32_e32 v95, 0x3f317217, v106
	v_rcp_f32_e32 v100, v102
; DI bf16x8 pack8(const f32x4& a, const f32x4& b) { v4u w; w.x = pk2(a[0], a[1]); w.y = pk2(a[2], a[3]); w.z = pk2(b[0], b[1]); w.w = pk2(b[2], b[3]); return __builtin_bit_cast(bf16x8, w); }
;     DI void operator()(const f32x4 (&acc)[2][2][4][2], const pg8::Unit& u, int wr, int wc, int fr, int fq) const {
;     ...
;                 for (int bj = 0; bj < 2; ++bj) { const size_t o = (size_t)row * D + cbase + bj * 128; f32x4 lg[2], kk[2];
; #pragma unroll
;                     for (int n = 0; n < 2; ++n)
; #pragma unroll
;                         for (int e = 0; e < 4; ++e) { const float f = fminf(fmaxf(acc[ai][bj][m][n][e], -30.f), 30.f), lb = lbv[bj][n][e], ef = __expf(-f), sg = 1.f / (1.f + ef), sgn = ef / (1.f + ef);
;                             lg[n][e] = __logf(lb + (1.f - lb) * sg); kk[n][e] = (1.f - lb) * sgn; }
;                     *(f32x4*)(lf + o) = lg[0]; *(f32x4*)(lf + o + 4) = lg[1]; *(bf16x8*)(zq + (size_t)T * D + o) = pack8(kk[0], kk[1]); }
	s_nop 0
	v_fma_f32 v100, v100, v136, v80
	v_cmp_gt_f32_e32 vcc, s69, v100
	v_cmp_lt_f32_e64 s[8:9], |v106|, s71
	v_max_f32_e32 v35, v35, v35
	v_cndmask_b32_e64 v101, 0, 32, vcc
	v_ldexp_f32 v100, v100, v101
	v_log_f32_e32 v100, v100
	v_cndmask_b32_e64 v95, v106, v95, s[8:9]
	v_cndmask_b32_e64 v101, 0, v189, s[6:7]
	v_sub_f32_e32 v95, v95, v101
	v_mul_f32_e32 v101, 0x3f317217, v100
	v_fma_f32 v101, v100, s70, -v101
	v_fmac_f32_e32 v101, 0x3377d1cf, v100
	v_fmac_f32_e32 v101, 0x3f317217, v100
	v_cmp_lt_f32_e64 s[6:7], |v100|, s71
	v_med3_f32 v34, v34, s68, v188
	v_med3_f32 v35, v35, s68, v188
	v_cndmask_b32_e64 v100, v100, v101, s[6:7]
	v_cndmask_b32_e32 v101, 0, v189, vcc
	v_sub_f32_e32 v100, v100, v101
	v_rcp_f32_e32 v101, v103
	v_mul_f32_e32 v34, 0xbfb8aa3b, v34
	v_mul_f32_e32 v105, v105, v101
	v_rcp_f32_e32 v101, v102
	v_rcp_f32_e32 v103, v103
	v_mul_f32_e32 v104, v104, v101
	v_fma_f32 v103, v103, v137, v81
	v_cmp_gt_f32_e64 s[6:7], s69, v103
	v_pk_mul_f32 v[104:105], v[104:105], v[136:137]
	v_mul_f32_e32 v35, 0xbfb8aa3b, v35
	v_cndmask_b32_e64 v106, 0, 32, s[6:7]
	v_ldexp_f32 v103, v103, v106
	v_pk_add_f32 v[106:107], v[86:87], 1.0 op_sel_hi:[1,0]
	v_log_f32_e32 v103, v103
	s_nop 0
	v_mul_f32_e32 v101, 0x3f317217, v103
	v_fma_f32 v101, v103, s70, -v101
	v_fmac_f32_e32 v101, 0x3377d1cf, v103
	v_rcp_f32_e32 v102, v106
	s_nop 0
	v_fma_f32 v102, v102, v164, v82
	v_cmp_gt_f32_e32 vcc, s69, v102
	v_fmac_f32_e32 v101, 0x3f317217, v103
	v_cmp_lt_f32_e64 s[8:9], |v103|, s71
	v_cndmask_b32_e64 v108, 0, 32, vcc
	v_ldexp_f32 v102, v102, v108
	v_log_f32_e32 v102, v102
	v_cndmask_b32_e64 v101, v103, v101, s[8:9]
	v_cndmask_b32_e64 v103, 0, v189, s[6:7]
	v_sub_f32_e32 v101, v101, v103
	v_mul_f32_e32 v103, 0x3f317217, v102
	v_fma_f32 v103, v102, s70, -v103
	v_fmac_f32_e32 v103, 0x3377d1cf, v102
	v_fmac_f32_e32 v103, 0x3f317217, v102
	v_cmp_lt_f32_e64 s[6:7], |v102|, s71
	v_exp_f32_e32 v34, v34
	v_exp_f32_e32 v35, v35
	v_cndmask_b32_e64 v102, v102, v103, s[6:7]
	v_cndmask_b32_e32 v103, 0, v189, vcc
	v_sub_f32_e32 v102, v102, v103
	v_rcp_f32_e32 v103, v107
	v_rcp_f32_e32 v108, v106
	v_mul_f32_e32 v87, v87, v103
	v_mul_f32_e32 v86, v86, v108
	v_rcp_f32_e32 v109, v107
	s_nop 0
	v_fma_f32 v109, v109, v165, v83
	v_cmp_gt_f32_e32 vcc, s69, v109
	v_pk_mul_f32 v[106:107], v[86:87], v[164:165]
	v_exp_f32_e32 v108, v72
	v_cndmask_b32_e64 v110, 0, 32, vcc
	v_ldexp_f32 v109, v109, v110
	v_log_f32_e32 v109, v109
	v_max_f32_e32 v72, v73, v73
	v_med3_f32 v72, v72, s68, v188
	v_mul_f32_e32 v72, 0xbfb8aa3b, v72
	v_mul_f32_e32 v86, 0x3f317217, v109
	v_fma_f32 v86, v109, s70, -v86
	v_fmac_f32_e32 v86, 0x3377d1cf, v109
	v_fmac_f32_e32 v86, 0x3f317217, v109
	v_cmp_lt_f32_e64 s[6:7], |v109|, s71
	v_cndmask_b32_e32 v87, 0, v189, vcc
	v_max_f32_e32 v28, v28, v28
	v_cndmask_b32_e64 v86, v109, v86, s[6:7]
	v_exp_f32_e32 v109, v72
	v_sub_f32_e32 v103, v86, v87
	v_lshl_add_u64 v[86:87], v[96:97], 2, s[18:19]
	global_store_dwordx4 v[86:87], v[92:95], off
	global_store_dwordx4 v[86:87], v[100:103], off offset:16
	v_med3_f32 v28, v28, s68, v188
	v_cvt_pk_bf16_f32 v93, v84, v85
	v_pk_add_f32 v[100:101], v[108:109], 1.0 op_sel_hi:[1,0]
	v_cvt_pk_bf16_f32 v92, v98, v99
	v_cvt_pk_bf16_f32 v94, v104, v105
	v_mul_f32_e32 v28, 0xbfb8aa3b, v28
	v_max_f32_e32 v30, v30, v30
	v_rcp_f32_e32 v72, v100
	s_nop 0
	v_fma_f32 v72, v72, v138, v76
	v_cmp_gt_f32_e32 vcc, s69, v72
	v_cvt_pk_bf16_f32 v95, v106, v107
	v_lshl_add_u64 v[84:85], v[96:97], 1, s[42:43]
	v_cndmask_b32_e64 v73, 0, 32, vcc
	v_ldexp_f32 v72, v72, v73
	v_log_f32_e32 v72, v72
	global_store_dwordx4 v[84:85], v[92:95], off
	v_med3_f32 v30, v30, s68, v188
	v_mul_f32_e32 v30, 0xbfb8aa3b, v30
	v_mul_f32_e32 v73, 0x3f317217, v72
	v_fma_f32 v73, v72, s70, -v73
	v_fmac_f32_e32 v73, 0x3377d1cf, v72
	v_fmac_f32_e32 v73, 0x3f317217, v72
	v_cmp_lt_f32_e64 s[6:7], |v72|, s71
	v_max_f32_e32 v24, v24, v24
	v_med3_f32 v24, v24, s68, v188
	v_cndmask_b32_e64 v72, v72, v73, s[6:7]
	v_cndmask_b32_e32 v73, 0, v189, vcc
	v_sub_f32_e32 v72, v72, v73
	v_rcp_f32_e32 v73, v101
	v_mul_f32_e32 v24, 0xbfb8aa3b, v24
	v_mul_f32_e32 v93, v109, v73
	v_max_f32_e32 v26, v26, v26
	v_rcp_f32_e32 v92, v101
	s_nop 0
	v_fma_f32 v92, v92, v139, v77
	v_cmp_gt_f32_e64 s[6:7], s69, v92
	v_max_f32_e32 v27, v27, v27
	v_med3_f32 v26, v26, s68, v188
	v_cndmask_b32_e64 v94, 0, 32, s[6:7]
	v_ldexp_f32 v92, v92, v94
	v_exp_f32_e32 v94, v74
	v_max_f32_e32 v74, v75, v75
	v_med3_f32 v74, v74, s68, v188
	v_mul_f32_e32 v74, 0xbfb8aa3b, v74
	v_exp_f32_e32 v95, v74
	v_log_f32_e32 v98, v92
	v_rcp_f32_e32 v73, v100
	s_nop 0
	v_mul_f32_e32 v92, v108, v73
	v_pk_mul_f32 v[92:93], v[92:93], v[138:139]
	v_pk_add_f32 v[96:97], v[94:95], 1.0 op_sel_hi:[1,0]
	v_mul_f32_e32 v73, 0x3f317217, v98
	v_fma_f32 v73, v98, s70, -v73
	v_fmac_f32_e32 v73, 0x3377d1cf, v98
	v_fmac_f32_e32 v73, 0x3f317217, v98
	v_rcp_f32_e32 v74, v96
	s_nop 0
	v_fma_f32 v74, v74, v140, v78
	v_cmp_gt_f32_e32 vcc, s69, v74
	v_cmp_lt_f32_e64 s[8:9], |v98|, s71
	v_med3_f32 v27, v27, s68, v188
	v_cndmask_b32_e64 v75, 0, 32, vcc
	v_ldexp_f32 v74, v74, v75
	v_log_f32_e32 v74, v74
	v_cndmask_b32_e64 v73, v98, v73, s[8:9]
	v_cndmask_b32_e64 v75, 0, v189, s[6:7]
	v_sub_f32_e32 v73, v73, v75
	v_mul_f32_e32 v75, 0x3f317217, v74
	v_fma_f32 v75, v74, s70, -v75
	v_fmac_f32_e32 v75, 0x3377d1cf, v74
	v_fmac_f32_e32 v75, 0x3f317217, v74
	v_cmp_lt_f32_e64 s[6:7], |v74|, s71
	v_mul_f32_e32 v26, 0xbfb8aa3b, v26
	v_mul_f32_e32 v27, 0xbfb8aa3b, v27
	v_cndmask_b32_e64 v74, v74, v75, s[6:7]
	v_cndmask_b32_e32 v75, 0, v189, vcc
	v_sub_f32_e32 v74, v74, v75
	v_rcp_f32_e32 v75, v97
	v_exp_f32_e32 v26, v26
	v_mul_f32_e32 v95, v95, v75
	v_rcp_f32_e32 v75, v96
; DI bf16x8 pack8(const f32x4& a, const f32x4& b) { v4u w; w.x = pk2(a[0], a[1]); w.y = pk2(a[2], a[3]); w.z = pk2(b[0], b[1]); w.w = pk2(b[2], b[3]); return __builtin_bit_cast(bf16x8, w); }
;     DI void operator()(const f32x4 (&acc)[2][2][4][2], const pg8::Unit& u, int wr, int wc, int fr, int fq) const {
;     ...
;                 for (int bj = 0; bj < 2; ++bj) { const size_t o = (size_t)row * D + cbase + bj * 128; f32x4 lg[2], kk[2];
; #pragma unroll
;                     for (int n = 0; n < 2; ++n)
; #pragma unroll
;                         for (int e = 0; e < 4; ++e) { const float f = fminf(fmaxf(acc[ai][bj][m][n][e], -30.f), 30.f), lb = lbv[bj][n][e], ef = __expf(-f), sg = 1.f / (1.f + ef), sgn = ef / (1.f + ef);
;                             lg[n][e] = __logf(lb + (1.f - lb) * sg); kk[n][e] = (1.f - lb) * sgn; }
;                     *(f32x4*)(lf + o) = lg[0]; *(f32x4*)(lf + o + 4) = lg[1]; *(bf16x8*)(zq + (size_t)T * D + o) = pack8(kk[0], kk[1]); }
	v_rcp_f32_e32 v97, v97
	v_mul_f32_e32 v94, v94, v75
	v_fma_f32 v97, v97, v141, v79
	v_cmp_gt_f32_e64 s[6:7], s69, v97
	v_exp_f32_e32 v27, v27
	v_max_f32_e32 v20, v20, v20
	v_cndmask_b32_e64 v98, 0, 32, s[6:7]
	v_ldexp_f32 v97, v97, v98
	v_exp_f32_e32 v98, v64
	v_max_f32_e32 v64, v65, v65
	v_med3_f32 v64, v64, s68, v188
	v_mul_f32_e32 v64, 0xbfb8aa3b, v64
	v_exp_f32_e32 v99, v64
	v_log_f32_e32 v100, v97
	v_pk_mul_f32 v[64:65], v[94:95], v[140:141]
	v_med3_f32 v20, v20, s68, v188
	v_pk_add_f32 v[96:97], v[98:99], 1.0 op_sel_hi:[1,0]
	v_mul_f32_e32 v75, 0x3f317217, v100
	v_fma_f32 v75, v100, s70, -v75
	v_fmac_f32_e32 v75, 0x3377d1cf, v100
	v_fmac_f32_e32 v75, 0x3f317217, v100
	v_rcp_f32_e32 v94, v96
	s_nop 0
	v_fma_f32 v94, v94, v128, v68
	v_cmp_gt_f32_e32 vcc, s69, v94
	v_cmp_lt_f32_e64 s[8:9], |v100|, s71
	v_mul_f32_e32 v20, 0xbfb8aa3b, v20
	v_cndmask_b32_e64 v95, 0, 32, vcc
	v_ldexp_f32 v94, v94, v95
	v_log_f32_e32 v94, v94
	v_cndmask_b32_e64 v75, v100, v75, s[8:9]
	v_cndmask_b32_e64 v95, 0, v189, s[6:7]
	v_sub_f32_e32 v75, v75, v95
	v_mul_f32_e32 v95, 0x3f317217, v94
	v_fma_f32 v95, v94, s70, -v95
	v_fmac_f32_e32 v95, 0x3377d1cf, v94
	v_fmac_f32_e32 v95, 0x3f317217, v94
	v_cmp_lt_f32_e64 s[6:7], |v94|, s71
	v_max_f32_e32 v22, v22, v22
	v_med3_f32 v22, v22, s68, v188
	v_cndmask_b32_e64 v94, v94, v95, s[6:7]
	v_cndmask_b32_e32 v95, 0, v189, vcc
	v_sub_f32_e32 v94, v94, v95
	v_rcp_f32_e32 v95, v97
	v_mul_f32_e32 v22, 0xbfb8aa3b, v22
	v_mul_f32_e32 v99, v99, v95
	v_rcp_f32_e32 v95, v96
	v_rcp_f32_e32 v97, v97
	v_mul_f32_e32 v98, v98, v95
	v_fma_f32 v97, v97, v129, v69
	v_cmp_gt_f32_e64 s[6:7], s69, v97
	v_pk_mul_f32 v[98:99], v[98:99], v[128:129]
	v_max_f32_e32 v16, v16, v16
	v_cndmask_b32_e64 v100, 0, 32, s[6:7]
	v_ldexp_f32 v97, v97, v100
	v_pk_add_f32 v[100:101], v[66:67], 1.0 op_sel_hi:[1,0]
	v_log_f32_e32 v97, v97
	s_nop 0
	v_mul_f32_e32 v95, 0x3f317217, v97
	v_fma_f32 v95, v97, s70, -v95
	v_fmac_f32_e32 v95, 0x3377d1cf, v97
	v_rcp_f32_e32 v96, v100
	s_nop 0
	v_fma_f32 v96, v96, v130, v70
	v_cmp_gt_f32_e32 vcc, s69, v96
	v_fmac_f32_e32 v95, 0x3f317217, v97
	v_cmp_lt_f32_e64 s[8:9], |v97|, s71
	v_cndmask_b32_e64 v102, 0, 32, vcc
	v_ldexp_f32 v96, v96, v102
	v_log_f32_e32 v96, v96
	v_cndmask_b32_e64 v95, v97, v95, s[8:9]
	v_cndmask_b32_e64 v97, 0, v189, s[6:7]
	v_sub_f32_e32 v95, v95, v97
	v_mul_f32_e32 v97, 0x3f317217, v96
	v_fma_f32 v97, v96, s70, -v97
	v_fmac_f32_e32 v97, 0x3377d1cf, v96
	v_fmac_f32_e32 v97, 0x3f317217, v96
	v_cmp_lt_f32_e64 s[6:7], |v96|, s71
	v_med3_f32 v16, v16, s68, v188
	v_mul_f32_e32 v16, 0xbfb8aa3b, v16
	v_cndmask_b32_e64 v96, v96, v97, s[6:7]
	v_cndmask_b32_e32 v97, 0, v189, vcc
	v_sub_f32_e32 v96, v96, v97
	v_rcp_f32_e32 v97, v101
	v_rcp_f32_e32 v102, v100
	v_mul_f32_e32 v67, v67, v97
	v_mul_f32_e32 v66, v66, v102
	v_rcp_f32_e32 v103, v101
	s_nop 0
	v_fma_f32 v103, v103, v131, v71
	v_cmp_gt_f32_e32 vcc, s69, v103
	v_pk_mul_f32 v[66:67], v[66:67], v[130:131]
	v_max_f32_e32 v18, v18, v18
	v_cndmask_b32_e64 v104, 0, 32, vcc
	v_ldexp_f32 v103, v103, v104
	v_log_f32_e32 v103, v103
	v_cndmask_b32_e32 v100, 0, v189, vcc
	v_max_f32_e32 v19, v19, v19
	v_med3_f32 v18, v18, s68, v188
	v_mul_f32_e32 v97, 0x3f317217, v103
	v_fma_f32 v97, v103, s70, -v97
	v_fmac_f32_e32 v97, 0x3377d1cf, v103
	v_fmac_f32_e32 v97, 0x3f317217, v103
	v_cmp_lt_f32_e64 s[6:7], |v103|, s71
	v_med3_f32 v19, v19, s68, v188
	v_mul_f32_e32 v18, 0xbfb8aa3b, v18
	v_cndmask_b32_e64 v97, v103, v97, s[6:7]
	v_sub_f32_e32 v97, v97, v100
	global_store_dwordx4 v[86:87], v[72:75], off offset:512
	global_store_dwordx4 v[86:87], v[94:97], off offset:528
	v_exp_f32_e32 v86, v60
	v_max_f32_e32 v60, v61, v61
	v_med3_f32 v60, v60, s68, v188
	v_mul_f32_e32 v60, 0xbfb8aa3b, v60
	v_exp_f32_e32 v87, v60
	v_cvt_pk_bf16_f32 v72, v92, v93
	v_cvt_pk_bf16_f32 v73, v64, v65
	v_cvt_pk_bf16_f32 v75, v66, v67
	v_pk_add_f32 v[92:93], v[86:87], 1.0 op_sel_hi:[1,0]
	v_add_u32_e32 v60, s45, v181
	v_cvt_pk_bf16_f32 v74, v98, v99
	global_store_dwordx4 v[84:85], v[72:75], off offset:256
	v_mul_f32_e32 v19, 0xbfb8aa3b, v19
	v_rcp_f32_e32 v61, v92
	s_nop 0
	v_fma_f32 v61, v61, v166, v88
	v_cmp_gt_f32_e32 vcc, s69, v61
	v_exp_f32_e32 v18, v18
	v_exp_f32_e32 v19, v19
	v_cndmask_b32_e64 v64, 0, 32, vcc
	v_ldexp_f32 v61, v61, v64
	v_log_f32_e32 v66, v61
	v_ashrrev_i32_e32 v61, 31, v60
	v_lshlrev_b64 v[60:61], 11, v[60:61]
	v_lshl_add_u64 v[64:65], v[60:61], 0, v[160:161]
	v_mul_f32_e32 v60, 0x3f317217, v66
	v_fma_f32 v60, v66, s70, -v60
	v_fmac_f32_e32 v60, 0x3377d1cf, v66
	v_fmac_f32_e32 v60, 0x3f317217, v66
	v_cmp_lt_f32_e64 s[6:7], |v66|, s71
	v_max_f32_e32 v12, v12, v12
	v_med3_f32 v12, v12, s68, v188
	v_cndmask_b32_e64 v60, v66, v60, s[6:7]
	v_cndmask_b32_e32 v66, 0, v189, vcc
	v_sub_f32_e32 v60, v60, v66
	v_rcp_f32_e32 v61, v93
	v_mul_f32_e32 v12, 0xbfb8aa3b, v12
	v_mul_f32_e32 v67, v87, v61
	v_max_f32_e32 v14, v14, v14
	v_rcp_f32_e32 v66, v93
	s_nop 0
	v_fma_f32 v66, v66, v167, v89
	v_cmp_gt_f32_e64 s[6:7], s69, v66
	v_med3_f32 v14, v14, s68, v188
	v_mul_f32_e32 v14, 0xbfb8aa3b, v14
	v_cndmask_b32_e64 v72, 0, 32, s[6:7]
	v_ldexp_f32 v66, v66, v72
	v_exp_f32_e32 v72, v62
	v_max_f32_e32 v62, v63, v63
	v_med3_f32 v62, v62, s68, v188
	v_mul_f32_e32 v62, 0xbfb8aa3b, v62
	v_exp_f32_e32 v73, v62
	v_log_f32_e32 v84, v66
	v_rcp_f32_e32 v61, v92
	s_nop 0
	v_mul_f32_e32 v66, v86, v61
	v_pk_mul_f32 v[66:67], v[66:67], v[166:167]
	v_pk_add_f32 v[74:75], v[72:73], 1.0 op_sel_hi:[1,0]
	v_mul_f32_e32 v61, 0x3f317217, v84
	v_fma_f32 v61, v84, s70, -v61
	v_fmac_f32_e32 v61, 0x3377d1cf, v84
	v_fmac_f32_e32 v61, 0x3f317217, v84
	v_rcp_f32_e32 v62, v74
	s_nop 0
	v_fma_f32 v62, v62, v162, v90
; DI bf16x8 pack8(const f32x4& a, const f32x4& b) { v4u w; w.x = pk2(a[0], a[1]); w.y = pk2(a[2], a[3]); w.z = pk2(b[0], b[1]); w.w = pk2(b[2], b[3]); return __builtin_bit_cast(bf16x8, w); }
;     DI void operator()(const f32x4 (&acc)[2][2][4][2], const pg8::Unit& u, int wr, int wc, int fr, int fq) const {
;     ...
;                 for (int bj = 0; bj < 2; ++bj) { const size_t o = (size_t)row * D + cbase + bj * 128; f32x4 lg[2], kk[2];
; #pragma unroll
;                     for (int n = 0; n < 2; ++n)
; #pragma unroll
;                         for (int e = 0; e < 4; ++e) { const float f = fminf(fmaxf(acc[ai][bj][m][n][e], -30.f), 30.f), lb = lbv[bj][n][e], ef = __expf(-f), sg = 1.f / (1.f + ef), sgn = ef / (1.f + ef);
;                             lg[n][e] = __logf(lb + (1.f - lb) * sg); kk[n][e] = (1.f - lb) * sgn; }
;                     *(f32x4*)(lf + o) = lg[0]; *(f32x4*)(lf + o + 4) = lg[1]; *(bf16x8*)(zq + (size_t)T * D + o) = pack8(kk[0], kk[1]); }
	v_cmp_gt_f32_e32 vcc, s69, v62
	v_cmp_lt_f32_e64 s[8:9], |v84|, s71
	v_max_f32_e32 v8, v8, v8
	v_cndmask_b32_e64 v63, 0, 32, vcc
	v_ldexp_f32 v62, v62, v63
	v_log_f32_e32 v62, v62
	v_cndmask_b32_e64 v61, v84, v61, s[8:9]
	v_cndmask_b32_e64 v63, 0, v189, s[6:7]
	v_sub_f32_e32 v61, v61, v63
	v_mul_f32_e32 v63, 0x3f317217, v62
	v_fma_f32 v63, v62, s70, -v63
	v_fmac_f32_e32 v63, 0x3377d1cf, v62
	v_fmac_f32_e32 v63, 0x3f317217, v62
	v_cmp_lt_f32_e64 s[6:7], |v62|, s71
	v_max_f32_e32 v9, v9, v9
	v_med3_f32 v8, v8, s68, v188
	v_cndmask_b32_e64 v62, v62, v63, s[6:7]
	v_cndmask_b32_e32 v63, 0, v189, vcc
	v_sub_f32_e32 v62, v62, v63
	v_rcp_f32_e32 v63, v75
	s_nop 0
	v_mul_f32_e32 v73, v73, v63
	v_med3_f32 v9, v9, s68, v188
	v_rcp_f32_e32 v63, v74
	v_rcp_f32_e32 v75, v75
	v_mul_f32_e32 v72, v72, v63
	v_fma_f32 v75, v75, v163, v91
	v_cmp_gt_f32_e64 s[6:7], s69, v75
	v_mul_f32_e32 v8, 0xbfb8aa3b, v8
	v_mul_f32_e32 v9, 0xbfb8aa3b, v9
	v_cndmask_b32_e64 v84, 0, 32, s[6:7]
	v_ldexp_f32 v75, v75, v84
	v_exp_f32_e32 v84, v56
	v_max_f32_e32 v56, v57, v57
	v_med3_f32 v56, v56, s68, v188
	v_mul_f32_e32 v56, 0xbfb8aa3b, v56
	v_exp_f32_e32 v85, v56
	v_log_f32_e32 v86, v75
	v_pk_mul_f32 v[56:57], v[72:73], v[162:163]
	v_exp_f32_e32 v8, v8
	v_pk_add_f32 v[74:75], v[84:85], 1.0 op_sel_hi:[1,0]
	v_mul_f32_e32 v63, 0x3f317217, v86
	v_fma_f32 v63, v86, s70, -v63
	v_fmac_f32_e32 v63, 0x3377d1cf, v86
	v_fmac_f32_e32 v63, 0x3f317217, v86
	v_rcp_f32_e32 v72, v74
	s_nop 0
	v_fma_f32 v72, v72, v136, v80
	v_cmp_gt_f32_e32 vcc, s69, v72
	v_cmp_lt_f32_e64 s[8:9], |v86|, s71
	v_exp_f32_e32 v9, v9
	v_cndmask_b32_e64 v73, 0, 32, vcc
	v_ldexp_f32 v72, v72, v73
	v_log_f32_e32 v72, v72
	v_cndmask_b32_e64 v63, v86, v63, s[8:9]
	v_cndmask_b32_e64 v73, 0, v189, s[6:7]
	v_sub_f32_e32 v63, v63, v73
	v_mul_f32_e32 v73, 0x3f317217, v72
	v_fma_f32 v73, v72, s70, -v73
	v_fmac_f32_e32 v73, 0x3377d1cf, v72
	v_fmac_f32_e32 v73, 0x3f317217, v72
	v_cmp_lt_f32_e64 s[6:7], |v72|, s71
	v_max_f32_e32 v10, v10, v10
	v_max_f32_e32 v11, v11, v11
	v_cndmask_b32_e64 v72, v72, v73, s[6:7]
	v_cndmask_b32_e32 v73, 0, v189, vcc
	v_sub_f32_e32 v72, v72, v73
	v_rcp_f32_e32 v73, v75
	s_nop 0
	v_mul_f32_e32 v85, v85, v73
	v_med3_f32 v10, v10, s68, v188
	v_rcp_f32_e32 v73, v74
	v_rcp_f32_e32 v75, v75
	v_mul_f32_e32 v84, v84, v73
	v_fma_f32 v75, v75, v137, v81
	v_cmp_gt_f32_e64 s[6:7], s69, v75
	v_pk_mul_f32 v[84:85], v[84:85], v[136:137]
	v_med3_f32 v11, v11, s68, v188
	v_cndmask_b32_e64 v86, 0, 32, s[6:7]
	v_ldexp_f32 v75, v75, v86
	v_pk_add_f32 v[86:87], v[58:59], 1.0 op_sel_hi:[1,0]
	v_log_f32_e32 v75, v75
	s_nop 0
	v_mul_f32_e32 v73, 0x3f317217, v75
	v_fma_f32 v73, v75, s70, -v73
	v_fmac_f32_e32 v73, 0x3377d1cf, v75
	v_rcp_f32_e32 v74, v86
	s_nop 0
	v_fma_f32 v74, v74, v164, v82
	v_cmp_gt_f32_e32 vcc, s69, v74
	v_fmac_f32_e32 v73, 0x3f317217, v75
	v_cmp_lt_f32_e64 s[8:9], |v75|, s71
	v_cndmask_b32_e64 v92, 0, 32, vcc
	v_ldexp_f32 v74, v74, v92
	v_log_f32_e32 v74, v74
	v_cndmask_b32_e64 v73, v75, v73, s[8:9]
	v_cndmask_b32_e64 v75, 0, v189, s[6:7]
	v_sub_f32_e32 v73, v73, v75
	v_mul_f32_e32 v75, 0x3f317217, v74
	v_fma_f32 v75, v74, s70, -v75
	v_fmac_f32_e32 v75, 0x3377d1cf, v74
	v_fmac_f32_e32 v75, 0x3f317217, v74
	v_cmp_lt_f32_e64 s[6:7], |v74|, s71
	v_mul_f32_e32 v10, 0xbfb8aa3b, v10
	v_mul_f32_e32 v11, 0xbfb8aa3b, v11
	v_cndmask_b32_e64 v74, v74, v75, s[6:7]
	v_cndmask_b32_e32 v75, 0, v189, vcc
	v_sub_f32_e32 v74, v74, v75
	v_rcp_f32_e32 v75, v87
	v_rcp_f32_e32 v92, v86
	v_mul_f32_e32 v59, v59, v75
	v_mul_f32_e32 v58, v58, v92
	v_rcp_f32_e32 v93, v87
	s_nop 0
	v_fma_f32 v93, v93, v165, v83
	v_cmp_gt_f32_e32 vcc, s69, v93
	v_pk_mul_f32 v[86:87], v[58:59], v[164:165]
	v_exp_f32_e32 v92, v52
	v_cndmask_b32_e64 v94, 0, 32, vcc
	v_ldexp_f32 v93, v93, v94
	v_log_f32_e32 v93, v93
	v_max_f32_e32 v52, v53, v53
	v_med3_f32 v52, v52, s68, v188
	v_mul_f32_e32 v52, 0xbfb8aa3b, v52
	v_mul_f32_e32 v58, 0x3f317217, v93
	v_fma_f32 v58, v93, s70, -v58
	v_fmac_f32_e32 v58, 0x3377d1cf, v93
	v_fmac_f32_e32 v58, 0x3f317217, v93
	v_cmp_lt_f32_e64 s[6:7], |v93|, s71
	v_cndmask_b32_e32 v59, 0, v189, vcc
	v_exp_f32_e32 v10, v10
	v_cndmask_b32_e64 v58, v93, v58, s[6:7]
	v_exp_f32_e32 v93, v52
	v_sub_f32_e32 v75, v58, v59
	v_lshl_add_u64 v[58:59], v[64:65], 2, s[18:19]
	global_store_dwordx4 v[58:59], v[60:63], off
	global_store_dwordx4 v[58:59], v[72:75], off offset:16
	v_exp_f32_e32 v11, v11
	v_cvt_pk_bf16_f32 v61, v56, v57
	v_pk_add_f32 v[72:73], v[92:93], 1.0 op_sel_hi:[1,0]
	v_cvt_pk_bf16_f32 v60, v66, v67
	v_cvt_pk_bf16_f32 v62, v84, v85
	v_max_f32_e32 v4, v4, v4
	v_med3_f32 v4, v4, s68, v188
	v_rcp_f32_e32 v52, v72
	s_nop 0
	v_fma_f32 v52, v52, v138, v76
	v_cmp_gt_f32_e32 vcc, s69, v52
	v_cvt_pk_bf16_f32 v63, v86, v87
	v_lshl_add_u64 v[56:57], v[64:65], 1, s[42:43]
	v_cndmask_b32_e64 v53, 0, 32, vcc
	v_ldexp_f32 v52, v52, v53
	v_log_f32_e32 v52, v52
	global_store_dwordx4 v[56:57], v[60:63], off
	v_mul_f32_e32 v4, 0xbfb8aa3b, v4
	v_max_f32_e32 v6, v6, v6
	v_mul_f32_e32 v53, 0x3f317217, v52
	v_fma_f32 v53, v52, s70, -v53
	v_fmac_f32_e32 v53, 0x3377d1cf, v52
	v_fmac_f32_e32 v53, 0x3f317217, v52
	v_cmp_lt_f32_e64 s[6:7], |v52|, s71
	v_med3_f32 v6, v6, s68, v188
	v_mul_f32_e32 v6, 0xbfb8aa3b, v6
	v_cndmask_b32_e64 v52, v52, v53, s[6:7]
	v_cndmask_b32_e32 v53, 0, v189, vcc
	v_sub_f32_e32 v52, v52, v53
	v_rcp_f32_e32 v53, v73
	v_max_f32_e32 v0, v0, v0
	v_mul_f32_e32 v61, v93, v53
	v_med3_f32 v0, v0, s68, v188
	v_rcp_f32_e32 v60, v73
	s_nop 0
	v_fma_f32 v60, v60, v139, v77
	v_cmp_gt_f32_e64 s[6:7], s69, v60
	v_mul_f32_e32 v0, 0xbfb8aa3b, v0
	v_max_f32_e32 v2, v2, v2
	v_cndmask_b32_e64 v62, 0, 32, s[6:7]
	v_ldexp_f32 v60, v60, v62
; DI bf16x8 pack8(const f32x4& a, const f32x4& b) { v4u w; w.x = pk2(a[0], a[1]); w.y = pk2(a[2], a[3]); w.z = pk2(b[0], b[1]); w.w = pk2(b[2], b[3]); return __builtin_bit_cast(bf16x8, w); }
;     DI void operator()(const f32x4 (&acc)[2][2][4][2], const pg8::Unit& u, int wr, int wc, int fr, int fq) const {
;     ...
;                 for (int bj = 0; bj < 2; ++bj) { const size_t o = (size_t)row * D + cbase + bj * 128; f32x4 lg[2], kk[2];
; #pragma unroll
;                     for (int n = 0; n < 2; ++n)
; #pragma unroll
;                         for (int e = 0; e < 4; ++e) { const float f = fminf(fmaxf(acc[ai][bj][m][n][e], -30.f), 30.f), lb = lbv[bj][n][e], ef = __expf(-f), sg = 1.f / (1.f + ef), sgn = ef / (1.f + ef);
;                             lg[n][e] = __logf(lb + (1.f - lb) * sg); kk[n][e] = (1.f - lb) * sgn; }
;                     *(f32x4*)(lf + o) = lg[0]; *(f32x4*)(lf + o + 4) = lg[1]; *(bf16x8*)(zq + (size_t)T * D + o) = pack8(kk[0], kk[1]); }
	v_exp_f32_e32 v62, v54
	v_max_f32_e32 v54, v55, v55
	v_med3_f32 v54, v54, s68, v188
	v_mul_f32_e32 v54, 0xbfb8aa3b, v54
	v_exp_f32_e32 v63, v54
	v_log_f32_e32 v66, v60
	v_rcp_f32_e32 v53, v72
	s_nop 0
	v_mul_f32_e32 v60, v92, v53
	v_pk_mul_f32 v[60:61], v[60:61], v[138:139]
	v_pk_add_f32 v[64:65], v[62:63], 1.0 op_sel_hi:[1,0]
	v_mul_f32_e32 v53, 0x3f317217, v66
	v_fma_f32 v53, v66, s70, -v53
	v_fmac_f32_e32 v53, 0x3377d1cf, v66
	v_fmac_f32_e32 v53, 0x3f317217, v66
	v_rcp_f32_e32 v54, v64
	s_nop 0
	v_fma_f32 v54, v54, v140, v78
	v_cmp_gt_f32_e32 vcc, s69, v54
	v_cmp_lt_f32_e64 s[8:9], |v66|, s71
	v_med3_f32 v2, v2, s68, v188
	v_cndmask_b32_e64 v55, 0, 32, vcc
	v_ldexp_f32 v54, v54, v55
	v_log_f32_e32 v54, v54
	v_cndmask_b32_e64 v53, v66, v53, s[8:9]
	v_cndmask_b32_e64 v55, 0, v189, s[6:7]
	v_sub_f32_e32 v53, v53, v55
	v_mul_f32_e32 v55, 0x3f317217, v54
	v_fma_f32 v55, v54, s70, -v55
	v_fmac_f32_e32 v55, 0x3377d1cf, v54
	v_fmac_f32_e32 v55, 0x3f317217, v54
	v_cmp_lt_f32_e64 s[6:7], |v54|, s71
	v_mul_f32_e32 v2, 0xbfb8aa3b, v2
	s_nop 0
	v_cndmask_b32_e64 v54, v54, v55, s[6:7]
	v_cndmask_b32_e32 v55, 0, v189, vcc
	v_sub_f32_e32 v54, v54, v55
	v_rcp_f32_e32 v55, v65
	s_nop 0
	v_mul_f32_e32 v63, v63, v55
	v_rcp_f32_e32 v55, v64
	v_rcp_f32_e32 v65, v65
	v_mul_f32_e32 v62, v62, v55
	v_fma_f32 v65, v65, v141, v79
	v_cmp_gt_f32_e64 s[6:7], s69, v65
	s_nop 1
	v_cndmask_b32_e64 v66, 0, 32, s[6:7]
	v_ldexp_f32 v65, v65, v66
	v_exp_f32_e32 v66, v48
	v_max_f32_e32 v48, v49, v49
	v_med3_f32 v48, v48, s68, v188
	v_mul_f32_e32 v48, 0xbfb8aa3b, v48
	v_exp_f32_e32 v67, v48
	v_log_f32_e32 v72, v65
	v_pk_mul_f32 v[48:49], v[62:63], v[140:141]
	v_pk_add_f32 v[64:65], v[66:67], 1.0 op_sel_hi:[1,0]
	s_nop 0
	v_mul_f32_e32 v55, 0x3f317217, v72
	v_fma_f32 v55, v72, s70, -v55
	v_fmac_f32_e32 v55, 0x3377d1cf, v72
	v_rcp_f32_e32 v62, v64
	s_nop 0
	v_fma_f32 v62, v62, v128, v68
	v_cmp_gt_f32_e32 vcc, s69, v62
	v_fmac_f32_e32 v55, 0x3f317217, v72
	v_cmp_lt_f32_e64 s[8:9], |v72|, s71
	v_cndmask_b32_e64 v63, 0, 32, vcc
	v_ldexp_f32 v62, v62, v63
	v_log_f32_e32 v62, v62
	v_cndmask_b32_e64 v55, v72, v55, s[8:9]
	v_cndmask_b32_e64 v63, 0, v189, s[6:7]
	v_sub_f32_e32 v55, v55, v63
	v_mul_f32_e32 v63, 0x3f317217, v62
	v_fma_f32 v63, v62, s70, -v63
	v_fmac_f32_e32 v63, 0x3377d1cf, v62
	v_fmac_f32_e32 v63, 0x3f317217, v62
	v_cmp_lt_f32_e64 s[6:7], |v62|, s71
	s_nop 1
	v_cndmask_b32_e64 v62, v62, v63, s[6:7]
	v_cndmask_b32_e32 v63, 0, v189, vcc
	v_sub_f32_e32 v62, v62, v63
	v_rcp_f32_e32 v63, v65
	s_nop 0
	v_mul_f32_e32 v67, v67, v63
	v_rcp_f32_e32 v63, v64
	v_rcp_f32_e32 v65, v65
	v_mul_f32_e32 v66, v66, v63
	v_fma_f32 v65, v65, v129, v69
	v_cmp_gt_f32_e64 s[6:7], s69, v65
	v_pk_mul_f32 v[66:67], v[66:67], v[128:129]
	s_nop 0
	v_cndmask_b32_e64 v72, 0, 32, s[6:7]
	v_ldexp_f32 v65, v65, v72
	v_pk_add_f32 v[72:73], v[50:51], 1.0 op_sel_hi:[1,0]
	v_log_f32_e32 v65, v65
	s_nop 0
	v_mul_f32_e32 v63, 0x3f317217, v65
	v_fma_f32 v63, v65, s70, -v63
	v_fmac_f32_e32 v63, 0x3377d1cf, v65
	v_rcp_f32_e32 v64, v72
	s_nop 0
	v_fma_f32 v64, v64, v130, v70
	v_cmp_gt_f32_e32 vcc, s69, v64
	v_fmac_f32_e32 v63, 0x3f317217, v65
	v_cmp_lt_f32_e64 s[8:9], |v65|, s71
	v_cndmask_b32_e64 v74, 0, 32, vcc
	v_ldexp_f32 v64, v64, v74
	v_log_f32_e32 v64, v64
	v_cndmask_b32_e64 v63, v65, v63, s[8:9]
	v_cndmask_b32_e64 v65, 0, v189, s[6:7]
	v_sub_f32_e32 v63, v63, v65
	v_mul_f32_e32 v65, 0x3f317217, v64
	v_fma_f32 v65, v64, s70, -v65
	v_fmac_f32_e32 v65, 0x3377d1cf, v64
	v_fmac_f32_e32 v65, 0x3f317217, v64
	v_cmp_lt_f32_e64 s[6:7], |v64|, s71
	s_nop 1
	v_cndmask_b32_e64 v64, v64, v65, s[6:7]
	v_cndmask_b32_e32 v65, 0, v189, vcc
	v_sub_f32_e32 v64, v64, v65
	v_rcp_f32_e32 v65, v73
	v_rcp_f32_e32 v74, v72
	v_mul_f32_e32 v51, v51, v65
	v_mul_f32_e32 v50, v50, v74
	v_rcp_f32_e32 v75, v73
	s_nop 0
	v_fma_f32 v75, v75, v131, v71
	v_cmp_gt_f32_e32 vcc, s69, v75
	v_pk_mul_f32 v[72:73], v[50:51], v[130:131]
	s_nop 0
	v_cndmask_b32_e64 v84, 0, 32, vcc
	v_ldexp_f32 v75, v75, v84
	v_log_f32_e32 v75, v75
	v_cndmask_b32_e32 v51, 0, v189, vcc
	v_mul_f32_e32 v50, 0x3f317217, v75
	v_fma_f32 v50, v75, s70, -v50
	v_fmac_f32_e32 v50, 0x3377d1cf, v75
	v_fmac_f32_e32 v50, 0x3f317217, v75
	v_cmp_lt_f32_e64 s[6:7], |v75|, s71
	s_nop 1
	v_cndmask_b32_e64 v50, v75, v50, s[6:7]
	v_sub_f32_e32 v65, v50, v51
	global_store_dwordx4 v[58:59], v[52:55], off offset:512
	global_store_dwordx4 v[58:59], v[62:65], off offset:528
	v_cvt_pk_bf16_f32 v51, v48, v49
	v_exp_f32_e32 v54, v44
	v_max_f32_e32 v44, v45, v45
	v_med3_f32 v44, v44, s68, v188
	v_mul_f32_e32 v44, 0xbfb8aa3b, v44
	v_exp_f32_e32 v55, v44
	v_cvt_pk_bf16_f32 v50, v60, v61
	v_cvt_pk_bf16_f32 v52, v66, v67
	v_cvt_pk_bf16_f32 v53, v72, v73
	v_pk_add_f32 v[58:59], v[54:55], 1.0 op_sel_hi:[1,0]
	global_store_dwordx4 v[56:57], v[50:53], off offset:256
	v_add_u32_e32 v44, s45, v182
	v_rcp_f32_e32 v45, v58
	s_nop 0
	v_fma_f32 v45, v45, v166, v88
	v_cmp_gt_f32_e32 vcc, s69, v45
	s_nop 1
	v_cndmask_b32_e64 v48, 0, 32, vcc
	v_ldexp_f32 v45, v45, v48
	v_log_f32_e32 v50, v45
	v_ashrrev_i32_e32 v45, 31, v44
	v_lshlrev_b64 v[44:45], 11, v[44:45]
	v_lshl_add_u64 v[48:49], v[44:45], 0, v[160:161]
	v_mul_f32_e32 v44, 0x3f317217, v50
	v_fma_f32 v44, v50, s70, -v44
	v_fmac_f32_e32 v44, 0x3377d1cf, v50
	v_fmac_f32_e32 v44, 0x3f317217, v50
	v_cmp_lt_f32_e64 s[6:7], |v50|, s71
	s_nop 1
	v_cndmask_b32_e64 v44, v50, v44, s[6:7]
	v_cndmask_b32_e32 v50, 0, v189, vcc
	v_sub_f32_e32 v44, v44, v50
	v_rcp_f32_e32 v45, v59
	v_rcp_f32_e32 v50, v59
	v_mul_f32_e32 v51, v55, v45
	v_fma_f32 v50, v50, v167, v89
	v_cmp_gt_f32_e64 s[6:7], s69, v50
	s_nop 1
	v_cndmask_b32_e64 v52, 0, 32, s[6:7]
	v_ldexp_f32 v50, v50, v52
; DI bf16x8 pack8(const f32x4& a, const f32x4& b) { v4u w; w.x = pk2(a[0], a[1]); w.y = pk2(a[2], a[3]); w.z = pk2(b[0], b[1]); w.w = pk2(b[2], b[3]); return __builtin_bit_cast(bf16x8, w); }
;     DI void operator()(const f32x4 (&acc)[2][2][4][2], const pg8::Unit& u, int wr, int wc, int fr, int fq) const {
;     ...
;                 for (int bj = 0; bj < 2; ++bj) { const size_t o = (size_t)row * D + cbase + bj * 128; f32x4 lg[2], kk[2];
; #pragma unroll
;                     for (int n = 0; n < 2; ++n)
; #pragma unroll
;                         for (int e = 0; e < 4; ++e) { const float f = fminf(fmaxf(acc[ai][bj][m][n][e], -30.f), 30.f), lb = lbv[bj][n][e], ef = __expf(-f), sg = 1.f / (1.f + ef), sgn = ef / (1.f + ef);
;                             lg[n][e] = __logf(lb + (1.f - lb) * sg); kk[n][e] = (1.f - lb) * sgn; }
;                     *(f32x4*)(lf + o) = lg[0]; *(f32x4*)(lf + o + 4) = lg[1]; *(bf16x8*)(zq + (size_t)T * D + o) = pack8(kk[0], kk[1]); }
	v_exp_f32_e32 v52, v46
	v_max_f32_e32 v46, v47, v47
	v_med3_f32 v46, v46, s68, v188
	v_mul_f32_e32 v46, 0xbfb8aa3b, v46
	v_exp_f32_e32 v53, v46
	v_log_f32_e32 v56, v50
	v_rcp_f32_e32 v45, v58
	s_nop 0
	v_mul_f32_e32 v50, v54, v45
	v_pk_mul_f32 v[50:51], v[50:51], v[166:167]
	v_pk_add_f32 v[54:55], v[52:53], 1.0 op_sel_hi:[1,0]
	v_mul_f32_e32 v45, 0x3f317217, v56
	v_fma_f32 v45, v56, s70, -v45
	v_fmac_f32_e32 v45, 0x3377d1cf, v56
	v_fmac_f32_e32 v45, 0x3f317217, v56
	v_rcp_f32_e32 v46, v54
	s_nop 0
	v_fma_f32 v46, v46, v162, v90
	v_cmp_gt_f32_e32 vcc, s69, v46
	v_cmp_lt_f32_e64 s[8:9], |v56|, s71
	s_nop 0
	v_cndmask_b32_e64 v47, 0, 32, vcc
	v_ldexp_f32 v46, v46, v47
	v_log_f32_e32 v46, v46
	v_cndmask_b32_e64 v45, v56, v45, s[8:9]
	v_cndmask_b32_e64 v47, 0, v189, s[6:7]
	v_sub_f32_e32 v45, v45, v47
	v_mul_f32_e32 v47, 0x3f317217, v46
	v_fma_f32 v47, v46, s70, -v47
	v_fmac_f32_e32 v47, 0x3377d1cf, v46
	v_fmac_f32_e32 v47, 0x3f317217, v46
	v_cmp_lt_f32_e64 s[6:7], |v46|, s71
	s_nop 1
	v_cndmask_b32_e64 v46, v46, v47, s[6:7]
	v_cndmask_b32_e32 v47, 0, v189, vcc
	v_sub_f32_e32 v46, v46, v47
	v_rcp_f32_e32 v47, v55
	s_nop 0
	v_mul_f32_e32 v53, v53, v47
	v_rcp_f32_e32 v47, v54
	v_rcp_f32_e32 v55, v55
	v_mul_f32_e32 v52, v52, v47
	v_fma_f32 v55, v55, v163, v91
	v_cmp_gt_f32_e64 s[6:7], s69, v55
	s_nop 1
	v_cndmask_b32_e64 v56, 0, 32, s[6:7]
	v_ldexp_f32 v55, v55, v56
	v_exp_f32_e32 v56, v40
	v_max_f32_e32 v40, v41, v41
	v_med3_f32 v40, v40, s68, v188
	v_mul_f32_e32 v40, 0xbfb8aa3b, v40
	v_exp_f32_e32 v57, v40
	v_log_f32_e32 v58, v55
	v_pk_mul_f32 v[40:41], v[52:53], v[162:163]
	v_pk_add_f32 v[54:55], v[56:57], 1.0 op_sel_hi:[1,0]
	s_nop 0
	v_mul_f32_e32 v47, 0x3f317217, v58
	v_fma_f32 v47, v58, s70, -v47
	v_fmac_f32_e32 v47, 0x3377d1cf, v58
	v_rcp_f32_e32 v52, v54
	s_nop 0
	v_fma_f32 v52, v52, v136, v80
	v_cmp_gt_f32_e32 vcc, s69, v52
	v_fmac_f32_e32 v47, 0x3f317217, v58
	v_cmp_lt_f32_e64 s[8:9], |v58|, s71
	v_cndmask_b32_e64 v53, 0, 32, vcc
	v_ldexp_f32 v52, v52, v53
	v_log_f32_e32 v52, v52
	v_cndmask_b32_e64 v47, v58, v47, s[8:9]
	v_cndmask_b32_e64 v53, 0, v189, s[6:7]
	v_sub_f32_e32 v47, v47, v53
	v_mul_f32_e32 v53, 0x3f317217, v52
	v_fma_f32 v53, v52, s70, -v53
	v_fmac_f32_e32 v53, 0x3377d1cf, v52
	v_fmac_f32_e32 v53, 0x3f317217, v52
	v_cmp_lt_f32_e64 s[6:7], |v52|, s71
	s_nop 1
	v_cndmask_b32_e64 v52, v52, v53, s[6:7]
	v_cndmask_b32_e32 v53, 0, v189, vcc
	v_sub_f32_e32 v52, v52, v53
	v_rcp_f32_e32 v53, v55
	s_nop 0
	v_mul_f32_e32 v57, v57, v53
	v_rcp_f32_e32 v53, v54
	v_rcp_f32_e32 v55, v55
	v_mul_f32_e32 v56, v56, v53
	v_fma_f32 v55, v55, v137, v81
	v_cmp_gt_f32_e64 s[6:7], s69, v55
	v_pk_mul_f32 v[56:57], v[56:57], v[136:137]
	s_nop 0
	v_cndmask_b32_e64 v58, 0, 32, s[6:7]
	v_ldexp_f32 v55, v55, v58
	v_pk_add_f32 v[58:59], v[42:43], 1.0 op_sel_hi:[1,0]
	v_log_f32_e32 v55, v55
	s_nop 0
	v_mul_f32_e32 v53, 0x3f317217, v55
	v_fma_f32 v53, v55, s70, -v53
	v_fmac_f32_e32 v53, 0x3377d1cf, v55
	v_rcp_f32_e32 v54, v58
	s_nop 0
	v_fma_f32 v54, v54, v164, v82
	v_cmp_gt_f32_e32 vcc, s69, v54
	v_fmac_f32_e32 v53, 0x3f317217, v55
	v_cmp_lt_f32_e64 s[8:9], |v55|, s71
	v_cndmask_b32_e64 v60, 0, 32, vcc
	v_ldexp_f32 v54, v54, v60
	v_log_f32_e32 v54, v54
	v_cndmask_b32_e64 v53, v55, v53, s[8:9]
	v_cndmask_b32_e64 v55, 0, v189, s[6:7]
	v_sub_f32_e32 v53, v53, v55
	v_mul_f32_e32 v55, 0x3f317217, v54
	v_fma_f32 v55, v54, s70, -v55
	v_fmac_f32_e32 v55, 0x3377d1cf, v54
	v_fmac_f32_e32 v55, 0x3f317217, v54
	v_cmp_lt_f32_e64 s[6:7], |v54|, s71
	s_nop 1
	v_cndmask_b32_e64 v54, v54, v55, s[6:7]
	v_cndmask_b32_e32 v55, 0, v189, vcc
	v_sub_f32_e32 v54, v54, v55
	v_rcp_f32_e32 v55, v59
	v_rcp_f32_e32 v60, v58
	v_mul_f32_e32 v43, v43, v55
	v_mul_f32_e32 v42, v42, v60
	v_rcp_f32_e32 v61, v59
	s_nop 0
	v_fma_f32 v61, v61, v165, v83
	v_cmp_gt_f32_e32 vcc, s69, v61
	v_pk_mul_f32 v[58:59], v[42:43], v[164:165]
	v_exp_f32_e32 v60, v36
	v_cndmask_b32_e64 v62, 0, 32, vcc
	v_ldexp_f32 v61, v61, v62
	v_log_f32_e32 v61, v61
	v_max_f32_e32 v36, v37, v37
	v_med3_f32 v36, v36, s68, v188
	v_mul_f32_e32 v36, 0xbfb8aa3b, v36
	v_mul_f32_e32 v42, 0x3f317217, v61
	v_fma_f32 v42, v61, s70, -v42
	v_fmac_f32_e32 v42, 0x3377d1cf, v61
	v_fmac_f32_e32 v42, 0x3f317217, v61
	v_cmp_lt_f32_e64 s[6:7], |v61|, s71
	v_cndmask_b32_e32 v43, 0, v189, vcc
	s_nop 0
	v_cndmask_b32_e64 v42, v61, v42, s[6:7]
	v_exp_f32_e32 v61, v36
	v_sub_f32_e32 v55, v42, v43
	v_lshl_add_u64 v[42:43], v[48:49], 2, s[18:19]
	global_store_dwordx4 v[42:43], v[44:47], off
	global_store_dwordx4 v[42:43], v[52:55], off offset:16
	s_nop 0
	v_cvt_pk_bf16_f32 v45, v40, v41
	v_pk_add_f32 v[52:53], v[60:61], 1.0 op_sel_hi:[1,0]
	v_cvt_pk_bf16_f32 v44, v50, v51
	v_cvt_pk_bf16_f32 v46, v56, v57
	v_rcp_f32_e32 v36, v52
	s_nop 0
	v_fma_f32 v36, v36, v138, v76
	v_cmp_gt_f32_e32 vcc, s69, v36
	v_cvt_pk_bf16_f32 v47, v58, v59
	v_lshl_add_u64 v[40:41], v[48:49], 1, s[42:43]
	v_cndmask_b32_e64 v37, 0, 32, vcc
	v_ldexp_f32 v36, v36, v37
	v_log_f32_e32 v36, v36
	global_store_dwordx4 v[40:41], v[44:47], off
	v_mul_f32_e32 v37, 0x3f317217, v36
	s_nop 0
	v_fma_f32 v37, v36, s70, -v37
	v_fmac_f32_e32 v37, 0x3377d1cf, v36
	v_fmac_f32_e32 v37, 0x3f317217, v36
	v_cmp_lt_f32_e64 s[6:7], |v36|, s71
	s_nop 1
	v_cndmask_b32_e64 v36, v36, v37, s[6:7]
	v_cndmask_b32_e32 v37, 0, v189, vcc
	v_sub_f32_e32 v36, v36, v37
	v_rcp_f32_e32 v37, v53
	v_rcp_f32_e32 v44, v53
	v_mul_f32_e32 v45, v61, v37
	v_fma_f32 v44, v44, v139, v77
	v_cmp_gt_f32_e64 s[6:7], s69, v44
	s_nop 1
	v_cndmask_b32_e64 v46, 0, 32, s[6:7]
	v_ldexp_f32 v44, v44, v46
	v_exp_f32_e32 v46, v38
	v_max_f32_e32 v38, v39, v39
	v_med3_f32 v38, v38, s68, v188
	v_mul_f32_e32 v38, 0xbfb8aa3b, v38
; DI bf16x8 pack8(const f32x4& a, const f32x4& b) { v4u w; w.x = pk2(a[0], a[1]); w.y = pk2(a[2], a[3]); w.z = pk2(b[0], b[1]); w.w = pk2(b[2], b[3]); return __builtin_bit_cast(bf16x8, w); }
;     DI void operator()(const f32x4 (&acc)[2][2][4][2], const pg8::Unit& u, int wr, int wc, int fr, int fq) const {
;     ...
;                 for (int bj = 0; bj < 2; ++bj) { const size_t o = (size_t)row * D + cbase + bj * 128; f32x4 lg[2], kk[2];
; #pragma unroll
;                     for (int n = 0; n < 2; ++n)
; #pragma unroll
;                         for (int e = 0; e < 4; ++e) { const float f = fminf(fmaxf(acc[ai][bj][m][n][e], -30.f), 30.f), lb = lbv[bj][n][e], ef = __expf(-f), sg = 1.f / (1.f + ef), sgn = ef / (1.f + ef);
;                             lg[n][e] = __logf(lb + (1.f - lb) * sg); kk[n][e] = (1.f - lb) * sgn; }
;                     *(f32x4*)(lf + o) = lg[0]; *(f32x4*)(lf + o + 4) = lg[1]; *(bf16x8*)(zq + (size_t)T * D + o) = pack8(kk[0], kk[1]); }
	v_exp_f32_e32 v47, v38
	v_log_f32_e32 v50, v44
	v_rcp_f32_e32 v37, v52
	s_nop 0
	v_mul_f32_e32 v44, v60, v37
	v_pk_mul_f32 v[44:45], v[44:45], v[138:139]
	v_pk_add_f32 v[48:49], v[46:47], 1.0 op_sel_hi:[1,0]
	v_mul_f32_e32 v37, 0x3f317217, v50
	v_fma_f32 v37, v50, s70, -v37
	v_fmac_f32_e32 v37, 0x3377d1cf, v50
	v_fmac_f32_e32 v37, 0x3f317217, v50
	v_rcp_f32_e32 v38, v48
	s_nop 0
	v_fma_f32 v38, v38, v140, v78
	v_cmp_gt_f32_e32 vcc, s69, v38
	v_cmp_lt_f32_e64 s[8:9], |v50|, s71
	s_nop 0
	v_cndmask_b32_e64 v39, 0, 32, vcc
	v_ldexp_f32 v38, v38, v39
	v_log_f32_e32 v38, v38
	v_cndmask_b32_e64 v37, v50, v37, s[8:9]
	v_cndmask_b32_e64 v39, 0, v189, s[6:7]
	v_sub_f32_e32 v37, v37, v39
	v_mul_f32_e32 v39, 0x3f317217, v38
	v_fma_f32 v39, v38, s70, -v39
	v_fmac_f32_e32 v39, 0x3377d1cf, v38
	v_fmac_f32_e32 v39, 0x3f317217, v38
	v_cmp_lt_f32_e64 s[6:7], |v38|, s71
	s_nop 1
	v_cndmask_b32_e64 v38, v38, v39, s[6:7]
	v_cndmask_b32_e32 v39, 0, v189, vcc
	v_sub_f32_e32 v38, v38, v39
	v_rcp_f32_e32 v39, v49
	s_nop 0
	v_mul_f32_e32 v47, v47, v39
	v_rcp_f32_e32 v39, v48
	v_rcp_f32_e32 v49, v49
	v_mul_f32_e32 v46, v46, v39
	v_fma_f32 v49, v49, v141, v79
	v_cmp_gt_f32_e64 s[6:7], s69, v49
	s_nop 1
	v_cndmask_b32_e64 v50, 0, 32, s[6:7]
	v_ldexp_f32 v49, v49, v50
	v_exp_f32_e32 v50, v32
	v_max_f32_e32 v32, v33, v33
	v_med3_f32 v32, v32, s68, v188
	v_mul_f32_e32 v32, 0xbfb8aa3b, v32
	v_exp_f32_e32 v51, v32
	v_log_f32_e32 v52, v49
	v_pk_mul_f32 v[32:33], v[46:47], v[140:141]
	v_pk_add_f32 v[48:49], v[50:51], 1.0 op_sel_hi:[1,0]
	s_nop 0
	v_mul_f32_e32 v39, 0x3f317217, v52
	v_fma_f32 v39, v52, s70, -v39
	v_fmac_f32_e32 v39, 0x3377d1cf, v52
	v_rcp_f32_e32 v46, v48
	s_nop 0
	v_fma_f32 v46, v46, v128, v68
	v_cmp_gt_f32_e32 vcc, s69, v46
	v_fmac_f32_e32 v39, 0x3f317217, v52
	v_cmp_lt_f32_e64 s[8:9], |v52|, s71
	v_cndmask_b32_e64 v47, 0, 32, vcc
	v_ldexp_f32 v46, v46, v47
	v_log_f32_e32 v46, v46
	v_cndmask_b32_e64 v39, v52, v39, s[8:9]
	v_cndmask_b32_e64 v47, 0, v189, s[6:7]
	v_sub_f32_e32 v39, v39, v47
	v_mul_f32_e32 v47, 0x3f317217, v46
	v_fma_f32 v47, v46, s70, -v47
	v_fmac_f32_e32 v47, 0x3377d1cf, v46
	v_fmac_f32_e32 v47, 0x3f317217, v46
	v_cmp_lt_f32_e64 s[6:7], |v46|, s71
	s_nop 1
	v_cndmask_b32_e64 v46, v46, v47, s[6:7]
	v_cndmask_b32_e32 v47, 0, v189, vcc
	v_sub_f32_e32 v46, v46, v47
	v_rcp_f32_e32 v47, v49
	s_nop 0
	v_mul_f32_e32 v51, v51, v47
	v_rcp_f32_e32 v47, v48
	v_rcp_f32_e32 v49, v49
	v_mul_f32_e32 v50, v50, v47
	v_fma_f32 v49, v49, v129, v69
	v_cmp_gt_f32_e64 s[6:7], s69, v49
	v_pk_mul_f32 v[50:51], v[50:51], v[128:129]
	s_nop 0
	v_cndmask_b32_e64 v52, 0, 32, s[6:7]
	v_ldexp_f32 v49, v49, v52
	v_pk_add_f32 v[52:53], v[34:35], 1.0 op_sel_hi:[1,0]
	v_log_f32_e32 v49, v49
	s_nop 0
	v_mul_f32_e32 v47, 0x3f317217, v49
	v_fma_f32 v47, v49, s70, -v47
	v_fmac_f32_e32 v47, 0x3377d1cf, v49
	v_rcp_f32_e32 v48, v52
	s_nop 0
	v_fma_f32 v48, v48, v130, v70
	v_cmp_gt_f32_e32 vcc, s69, v48
	v_fmac_f32_e32 v47, 0x3f317217, v49
	v_cmp_lt_f32_e64 s[8:9], |v49|, s71
	v_cndmask_b32_e64 v54, 0, 32, vcc
	v_ldexp_f32 v48, v48, v54
	v_log_f32_e32 v48, v48
	v_cndmask_b32_e64 v47, v49, v47, s[8:9]
	v_cndmask_b32_e64 v49, 0, v189, s[6:7]
	v_sub_f32_e32 v47, v47, v49
	v_mul_f32_e32 v49, 0x3f317217, v48
	v_fma_f32 v49, v48, s70, -v49
	v_fmac_f32_e32 v49, 0x3377d1cf, v48
	v_fmac_f32_e32 v49, 0x3f317217, v48
	v_cmp_lt_f32_e64 s[6:7], |v48|, s71
	s_nop 1
	v_cndmask_b32_e64 v48, v48, v49, s[6:7]
	v_cndmask_b32_e32 v49, 0, v189, vcc
	v_sub_f32_e32 v48, v48, v49
	v_rcp_f32_e32 v49, v53
	v_rcp_f32_e32 v54, v52
	v_mul_f32_e32 v35, v35, v49
	v_mul_f32_e32 v34, v34, v54
	v_rcp_f32_e32 v55, v53
	s_nop 0
	v_fma_f32 v55, v55, v131, v71
	v_cmp_gt_f32_e32 vcc, s69, v55
	v_pk_mul_f32 v[52:53], v[34:35], v[130:131]
	s_nop 0
	v_cndmask_b32_e64 v56, 0, 32, vcc
	v_ldexp_f32 v55, v55, v56
	v_log_f32_e32 v55, v55
	v_cndmask_b32_e32 v35, 0, v189, vcc
	v_mul_f32_e32 v34, 0x3f317217, v55
	v_fma_f32 v34, v55, s70, -v34
	v_fmac_f32_e32 v34, 0x3377d1cf, v55
	v_fmac_f32_e32 v34, 0x3f317217, v55
	v_cmp_lt_f32_e64 s[6:7], |v55|, s71
	s_nop 1
	v_cndmask_b32_e64 v34, v55, v34, s[6:7]
	v_sub_f32_e32 v49, v34, v35
	global_store_dwordx4 v[42:43], v[36:39], off offset:512
	global_store_dwordx4 v[42:43], v[46:49], off offset:528
	v_cvt_pk_bf16_f32 v35, v32, v33
	v_exp_f32_e32 v38, v28
	v_max_f32_e32 v28, v29, v29
	v_med3_f32 v28, v28, s68, v188
	v_mul_f32_e32 v28, 0xbfb8aa3b, v28
	v_exp_f32_e32 v39, v28
	v_cvt_pk_bf16_f32 v34, v44, v45
	v_cvt_pk_bf16_f32 v36, v50, v51
	v_cvt_pk_bf16_f32 v37, v52, v53
	v_pk_add_f32 v[42:43], v[38:39], 1.0 op_sel_hi:[1,0]
	global_store_dwordx4 v[40:41], v[34:37], off offset:256
	v_add_u32_e32 v28, s45, v183
	v_rcp_f32_e32 v29, v42
	s_nop 0
	v_fma_f32 v29, v29, v166, v88
	v_cmp_gt_f32_e32 vcc, s69, v29
	s_nop 1
	v_cndmask_b32_e64 v32, 0, 32, vcc
	v_ldexp_f32 v29, v29, v32
	v_log_f32_e32 v34, v29
	v_ashrrev_i32_e32 v29, 31, v28
	v_lshlrev_b64 v[28:29], 11, v[28:29]
	v_lshl_add_u64 v[32:33], v[28:29], 0, v[160:161]
	v_mul_f32_e32 v28, 0x3f317217, v34
	v_fma_f32 v28, v34, s70, -v28
	v_fmac_f32_e32 v28, 0x3377d1cf, v34
	v_fmac_f32_e32 v28, 0x3f317217, v34
	v_cmp_lt_f32_e64 s[6:7], |v34|, s71
	s_nop 1
	v_cndmask_b32_e64 v28, v34, v28, s[6:7]
	v_cndmask_b32_e32 v34, 0, v189, vcc
	v_sub_f32_e32 v28, v28, v34
	v_rcp_f32_e32 v29, v43
	v_rcp_f32_e32 v34, v43
	v_mul_f32_e32 v35, v39, v29
	v_fma_f32 v34, v34, v167, v89
	v_cmp_gt_f32_e64 s[6:7], s69, v34
	s_nop 1
	v_cndmask_b32_e64 v36, 0, 32, s[6:7]
	v_ldexp_f32 v34, v34, v36
	v_exp_f32_e32 v36, v30
	v_max_f32_e32 v30, v31, v31
	v_med3_f32 v30, v30, s68, v188
	v_mul_f32_e32 v30, 0xbfb8aa3b, v30
	v_exp_f32_e32 v37, v30
	v_log_f32_e32 v40, v34
; DI bf16x8 pack8(const f32x4& a, const f32x4& b) { v4u w; w.x = pk2(a[0], a[1]); w.y = pk2(a[2], a[3]); w.z = pk2(b[0], b[1]); w.w = pk2(b[2], b[3]); return __builtin_bit_cast(bf16x8, w); }
;     DI void operator()(const f32x4 (&acc)[2][2][4][2], const pg8::Unit& u, int wr, int wc, int fr, int fq) const {
;     ...
;                 for (int bj = 0; bj < 2; ++bj) { const size_t o = (size_t)row * D + cbase + bj * 128; f32x4 lg[2], kk[2];
; #pragma unroll
;                     for (int n = 0; n < 2; ++n)
; #pragma unroll
;                         for (int e = 0; e < 4; ++e) { const float f = fminf(fmaxf(acc[ai][bj][m][n][e], -30.f), 30.f), lb = lbv[bj][n][e], ef = __expf(-f), sg = 1.f / (1.f + ef), sgn = ef / (1.f + ef);
;                             lg[n][e] = __logf(lb + (1.f - lb) * sg); kk[n][e] = (1.f - lb) * sgn; }
;                     *(f32x4*)(lf + o) = lg[0]; *(f32x4*)(lf + o + 4) = lg[1]; *(bf16x8*)(zq + (size_t)T * D + o) = pack8(kk[0], kk[1]); }
	v_rcp_f32_e32 v29, v42
	s_nop 0
	v_mul_f32_e32 v34, v38, v29
	v_pk_mul_f32 v[34:35], v[34:35], v[166:167]
	v_pk_add_f32 v[38:39], v[36:37], 1.0 op_sel_hi:[1,0]
	v_mul_f32_e32 v29, 0x3f317217, v40
	v_fma_f32 v29, v40, s70, -v29
	v_fmac_f32_e32 v29, 0x3377d1cf, v40
	v_fmac_f32_e32 v29, 0x3f317217, v40
	v_rcp_f32_e32 v30, v38
	s_nop 0
	v_fma_f32 v30, v30, v162, v90
	v_cmp_gt_f32_e32 vcc, s69, v30
	v_cmp_lt_f32_e64 s[8:9], |v40|, s71
	s_nop 0
	v_cndmask_b32_e64 v31, 0, 32, vcc
	v_ldexp_f32 v30, v30, v31
	v_log_f32_e32 v30, v30
	v_cndmask_b32_e64 v29, v40, v29, s[8:9]
	v_cndmask_b32_e64 v31, 0, v189, s[6:7]
	v_sub_f32_e32 v29, v29, v31
	v_mul_f32_e32 v31, 0x3f317217, v30
	v_fma_f32 v31, v30, s70, -v31
	v_fmac_f32_e32 v31, 0x3377d1cf, v30
	v_fmac_f32_e32 v31, 0x3f317217, v30
	v_cmp_lt_f32_e64 s[6:7], |v30|, s71
	s_nop 1
	v_cndmask_b32_e64 v30, v30, v31, s[6:7]
	v_cndmask_b32_e32 v31, 0, v189, vcc
	v_sub_f32_e32 v30, v30, v31
	v_rcp_f32_e32 v31, v39
	s_nop 0
	v_mul_f32_e32 v37, v37, v31
	v_rcp_f32_e32 v31, v38
	v_rcp_f32_e32 v39, v39
	v_mul_f32_e32 v36, v36, v31
	v_fma_f32 v39, v39, v163, v91
	v_cmp_gt_f32_e64 s[6:7], s69, v39
	s_nop 1
	v_cndmask_b32_e64 v40, 0, 32, s[6:7]
	v_ldexp_f32 v39, v39, v40
	v_exp_f32_e32 v40, v24
	v_max_f32_e32 v24, v25, v25
	v_med3_f32 v24, v24, s68, v188
	v_mul_f32_e32 v24, 0xbfb8aa3b, v24
	v_exp_f32_e32 v41, v24
	v_log_f32_e32 v42, v39
	v_pk_mul_f32 v[24:25], v[36:37], v[162:163]
	v_pk_add_f32 v[38:39], v[40:41], 1.0 op_sel_hi:[1,0]
	s_nop 0
	v_mul_f32_e32 v31, 0x3f317217, v42
	v_fma_f32 v31, v42, s70, -v31
	v_fmac_f32_e32 v31, 0x3377d1cf, v42
	v_rcp_f32_e32 v36, v38
	s_nop 0
	v_fma_f32 v36, v36, v136, v80
	v_cmp_gt_f32_e32 vcc, s69, v36
	v_fmac_f32_e32 v31, 0x3f317217, v42
	v_cmp_lt_f32_e64 s[8:9], |v42|, s71
	v_cndmask_b32_e64 v37, 0, 32, vcc
	v_ldexp_f32 v36, v36, v37
	v_log_f32_e32 v36, v36
	v_cndmask_b32_e64 v31, v42, v31, s[8:9]
	v_cndmask_b32_e64 v37, 0, v189, s[6:7]
	v_sub_f32_e32 v31, v31, v37
	v_mul_f32_e32 v37, 0x3f317217, v36
	v_fma_f32 v37, v36, s70, -v37
	v_fmac_f32_e32 v37, 0x3377d1cf, v36
	v_fmac_f32_e32 v37, 0x3f317217, v36
	v_cmp_lt_f32_e64 s[6:7], |v36|, s71
	s_nop 1
	v_cndmask_b32_e64 v36, v36, v37, s[6:7]
	v_cndmask_b32_e32 v37, 0, v189, vcc
	v_sub_f32_e32 v36, v36, v37
	v_rcp_f32_e32 v37, v39
	s_nop 0
	v_mul_f32_e32 v41, v41, v37
	v_rcp_f32_e32 v37, v38
	v_rcp_f32_e32 v39, v39
	v_mul_f32_e32 v40, v40, v37
	v_fma_f32 v39, v39, v137, v81
	v_cmp_gt_f32_e64 s[6:7], s69, v39
	v_pk_mul_f32 v[40:41], v[40:41], v[136:137]
	s_nop 0
	v_cndmask_b32_e64 v42, 0, 32, s[6:7]
	v_ldexp_f32 v39, v39, v42
	v_pk_add_f32 v[42:43], v[26:27], 1.0 op_sel_hi:[1,0]
	v_log_f32_e32 v39, v39
	s_nop 0
	v_mul_f32_e32 v37, 0x3f317217, v39
	v_fma_f32 v37, v39, s70, -v37
	v_fmac_f32_e32 v37, 0x3377d1cf, v39
	v_rcp_f32_e32 v38, v42
	s_nop 0
	v_fma_f32 v38, v38, v164, v82
	v_cmp_gt_f32_e32 vcc, s69, v38
	v_fmac_f32_e32 v37, 0x3f317217, v39
	v_cmp_lt_f32_e64 s[8:9], |v39|, s71
	v_cndmask_b32_e64 v44, 0, 32, vcc
	v_ldexp_f32 v38, v38, v44
	v_log_f32_e32 v38, v38
	v_cndmask_b32_e64 v37, v39, v37, s[8:9]
	v_cndmask_b32_e64 v39, 0, v189, s[6:7]
	v_sub_f32_e32 v37, v37, v39
	v_mul_f32_e32 v39, 0x3f317217, v38
	v_fma_f32 v39, v38, s70, -v39
	v_fmac_f32_e32 v39, 0x3377d1cf, v38
	v_fmac_f32_e32 v39, 0x3f317217, v38
	v_cmp_lt_f32_e64 s[6:7], |v38|, s71
	s_nop 1
	v_cndmask_b32_e64 v38, v38, v39, s[6:7]
	v_cndmask_b32_e32 v39, 0, v189, vcc
	v_sub_f32_e32 v38, v38, v39
	v_rcp_f32_e32 v39, v43
	v_rcp_f32_e32 v44, v42
	v_mul_f32_e32 v27, v27, v39
	v_mul_f32_e32 v26, v26, v44
	v_rcp_f32_e32 v45, v43
	s_nop 0
	v_fma_f32 v45, v45, v165, v83
	v_cmp_gt_f32_e32 vcc, s69, v45
	v_pk_mul_f32 v[42:43], v[26:27], v[164:165]
	v_exp_f32_e32 v44, v20
	v_cndmask_b32_e64 v46, 0, 32, vcc
	v_ldexp_f32 v45, v45, v46
	v_log_f32_e32 v45, v45
	v_max_f32_e32 v20, v21, v21
	v_med3_f32 v20, v20, s68, v188
	v_mul_f32_e32 v20, 0xbfb8aa3b, v20
	v_mul_f32_e32 v26, 0x3f317217, v45
	v_fma_f32 v26, v45, s70, -v26
	v_fmac_f32_e32 v26, 0x3377d1cf, v45
	v_fmac_f32_e32 v26, 0x3f317217, v45
	v_cmp_lt_f32_e64 s[6:7], |v45|, s71
	v_cndmask_b32_e32 v27, 0, v189, vcc
	s_nop 0
	v_cndmask_b32_e64 v26, v45, v26, s[6:7]
	v_exp_f32_e32 v45, v20
	v_sub_f32_e32 v39, v26, v27
	v_lshl_add_u64 v[26:27], v[32:33], 2, s[18:19]
	global_store_dwordx4 v[26:27], v[28:31], off
	global_store_dwordx4 v[26:27], v[36:39], off offset:16
	s_nop 0
	v_cvt_pk_bf16_f32 v29, v24, v25
	v_pk_add_f32 v[36:37], v[44:45], 1.0 op_sel_hi:[1,0]
	v_cvt_pk_bf16_f32 v28, v34, v35
	v_cvt_pk_bf16_f32 v30, v40, v41
	v_rcp_f32_e32 v20, v36
	s_nop 0
	v_fma_f32 v20, v20, v138, v76
	v_cmp_gt_f32_e32 vcc, s69, v20
	v_cvt_pk_bf16_f32 v31, v42, v43
	v_lshl_add_u64 v[24:25], v[32:33], 1, s[42:43]
	v_cndmask_b32_e64 v21, 0, 32, vcc
	v_ldexp_f32 v20, v20, v21
	v_log_f32_e32 v20, v20
	global_store_dwordx4 v[24:25], v[28:31], off
	v_mul_f32_e32 v21, 0x3f317217, v20
	s_nop 0
	v_fma_f32 v21, v20, s70, -v21
	v_fmac_f32_e32 v21, 0x3377d1cf, v20
	v_fmac_f32_e32 v21, 0x3f317217, v20
	v_cmp_lt_f32_e64 s[6:7], |v20|, s71
	s_nop 1
	v_cndmask_b32_e64 v20, v20, v21, s[6:7]
	v_cndmask_b32_e32 v21, 0, v189, vcc
	v_sub_f32_e32 v20, v20, v21
	v_rcp_f32_e32 v21, v37
	v_rcp_f32_e32 v28, v37
	v_mul_f32_e32 v29, v45, v21
	v_fma_f32 v28, v28, v139, v77
	v_cmp_gt_f32_e64 s[6:7], s69, v28
	s_nop 1
	v_cndmask_b32_e64 v30, 0, 32, s[6:7]
	v_ldexp_f32 v28, v28, v30
	v_exp_f32_e32 v30, v22
	v_max_f32_e32 v22, v23, v23
	v_med3_f32 v22, v22, s68, v188
	v_mul_f32_e32 v22, 0xbfb8aa3b, v22
	v_exp_f32_e32 v31, v22
	v_log_f32_e32 v34, v28
	v_rcp_f32_e32 v21, v36
	s_nop 0
	v_mul_f32_e32 v28, v44, v21
	v_pk_mul_f32 v[28:29], v[28:29], v[138:139]
; DI bf16x8 pack8(const f32x4& a, const f32x4& b) { v4u w; w.x = pk2(a[0], a[1]); w.y = pk2(a[2], a[3]); w.z = pk2(b[0], b[1]); w.w = pk2(b[2], b[3]); return __builtin_bit_cast(bf16x8, w); }
;     DI void operator()(const f32x4 (&acc)[2][2][4][2], const pg8::Unit& u, int wr, int wc, int fr, int fq) const {
;     ...
;                 for (int bj = 0; bj < 2; ++bj) { const size_t o = (size_t)row * D + cbase + bj * 128; f32x4 lg[2], kk[2];
; #pragma unroll
;                     for (int n = 0; n < 2; ++n)
; #pragma unroll
;                         for (int e = 0; e < 4; ++e) { const float f = fminf(fmaxf(acc[ai][bj][m][n][e], -30.f), 30.f), lb = lbv[bj][n][e], ef = __expf(-f), sg = 1.f / (1.f + ef), sgn = ef / (1.f + ef);
;                             lg[n][e] = __logf(lb + (1.f - lb) * sg); kk[n][e] = (1.f - lb) * sgn; }
;                     *(f32x4*)(lf + o) = lg[0]; *(f32x4*)(lf + o + 4) = lg[1]; *(bf16x8*)(zq + (size_t)T * D + o) = pack8(kk[0], kk[1]); }
	v_pk_add_f32 v[32:33], v[30:31], 1.0 op_sel_hi:[1,0]
	v_mul_f32_e32 v21, 0x3f317217, v34
	v_fma_f32 v21, v34, s70, -v21
	v_fmac_f32_e32 v21, 0x3377d1cf, v34
	v_fmac_f32_e32 v21, 0x3f317217, v34
	v_rcp_f32_e32 v22, v32
	s_nop 0
	v_fma_f32 v22, v22, v140, v78
	v_cmp_gt_f32_e32 vcc, s69, v22
	v_cmp_lt_f32_e64 s[8:9], |v34|, s71
	s_nop 0
	v_cndmask_b32_e64 v23, 0, 32, vcc
	v_ldexp_f32 v22, v22, v23
	v_log_f32_e32 v22, v22
	v_cndmask_b32_e64 v21, v34, v21, s[8:9]
	v_cndmask_b32_e64 v23, 0, v189, s[6:7]
	v_sub_f32_e32 v21, v21, v23
	v_mul_f32_e32 v23, 0x3f317217, v22
	v_fma_f32 v23, v22, s70, -v23
	v_fmac_f32_e32 v23, 0x3377d1cf, v22
	v_fmac_f32_e32 v23, 0x3f317217, v22
	v_cmp_lt_f32_e64 s[6:7], |v22|, s71
	s_nop 1
	v_cndmask_b32_e64 v22, v22, v23, s[6:7]
	v_cndmask_b32_e32 v23, 0, v189, vcc
	v_sub_f32_e32 v22, v22, v23
	v_rcp_f32_e32 v23, v33
	s_nop 0
	v_mul_f32_e32 v31, v31, v23
	v_rcp_f32_e32 v23, v32
	v_rcp_f32_e32 v33, v33
	v_mul_f32_e32 v30, v30, v23
	v_fma_f32 v33, v33, v141, v79
	v_cmp_gt_f32_e64 s[6:7], s69, v33
	s_nop 1
	v_cndmask_b32_e64 v34, 0, 32, s[6:7]
	v_ldexp_f32 v33, v33, v34
	v_exp_f32_e32 v34, v16
	v_max_f32_e32 v16, v17, v17
	v_med3_f32 v16, v16, s68, v188
	v_mul_f32_e32 v16, 0xbfb8aa3b, v16
	v_exp_f32_e32 v35, v16
	v_log_f32_e32 v36, v33
	v_pk_mul_f32 v[16:17], v[30:31], v[140:141]
	v_pk_add_f32 v[32:33], v[34:35], 1.0 op_sel_hi:[1,0]
	s_nop 0
	v_mul_f32_e32 v23, 0x3f317217, v36
	v_fma_f32 v23, v36, s70, -v23
	v_fmac_f32_e32 v23, 0x3377d1cf, v36
	v_rcp_f32_e32 v30, v32
	s_nop 0
	v_fma_f32 v30, v30, v128, v68
	v_cmp_gt_f32_e32 vcc, s69, v30
	v_fmac_f32_e32 v23, 0x3f317217, v36
	v_cmp_lt_f32_e64 s[8:9], |v36|, s71
	v_cndmask_b32_e64 v31, 0, 32, vcc
	v_ldexp_f32 v30, v30, v31
	v_log_f32_e32 v30, v30
	v_cndmask_b32_e64 v23, v36, v23, s[8:9]
	v_cndmask_b32_e64 v31, 0, v189, s[6:7]
	v_sub_f32_e32 v23, v23, v31
	v_mul_f32_e32 v31, 0x3f317217, v30
	v_fma_f32 v31, v30, s70, -v31
	v_fmac_f32_e32 v31, 0x3377d1cf, v30
	v_fmac_f32_e32 v31, 0x3f317217, v30
	v_cmp_lt_f32_e64 s[6:7], |v30|, s71
	s_nop 1
	v_cndmask_b32_e64 v30, v30, v31, s[6:7]
	v_cndmask_b32_e32 v31, 0, v189, vcc
	v_sub_f32_e32 v30, v30, v31
	v_rcp_f32_e32 v31, v33
	s_nop 0
	v_mul_f32_e32 v35, v35, v31
	v_rcp_f32_e32 v31, v32
	v_rcp_f32_e32 v33, v33
	v_mul_f32_e32 v34, v34, v31
	v_fma_f32 v33, v33, v129, v69
	v_cmp_gt_f32_e64 s[6:7], s69, v33
	v_pk_mul_f32 v[34:35], v[34:35], v[128:129]
	s_nop 0
	v_cndmask_b32_e64 v36, 0, 32, s[6:7]
	v_ldexp_f32 v33, v33, v36
	v_pk_add_f32 v[36:37], v[18:19], 1.0 op_sel_hi:[1,0]
	v_log_f32_e32 v33, v33
	s_nop 0
	v_mul_f32_e32 v31, 0x3f317217, v33
	v_fma_f32 v31, v33, s70, -v31
	v_fmac_f32_e32 v31, 0x3377d1cf, v33
	v_rcp_f32_e32 v32, v36
	s_nop 0
	v_fma_f32 v32, v32, v130, v70
	v_cmp_gt_f32_e32 vcc, s69, v32
	v_fmac_f32_e32 v31, 0x3f317217, v33
	v_cmp_lt_f32_e64 s[8:9], |v33|, s71
	v_cndmask_b32_e64 v38, 0, 32, vcc
	v_ldexp_f32 v32, v32, v38
	v_log_f32_e32 v32, v32
	v_cndmask_b32_e64 v31, v33, v31, s[8:9]
	v_cndmask_b32_e64 v33, 0, v189, s[6:7]
	v_sub_f32_e32 v31, v31, v33
	v_mul_f32_e32 v33, 0x3f317217, v32
	v_fma_f32 v33, v32, s70, -v33
	v_fmac_f32_e32 v33, 0x3377d1cf, v32
	v_fmac_f32_e32 v33, 0x3f317217, v32
	v_cmp_lt_f32_e64 s[6:7], |v32|, s71
	s_nop 1
	v_cndmask_b32_e64 v32, v32, v33, s[6:7]
	v_cndmask_b32_e32 v33, 0, v189, vcc
	v_sub_f32_e32 v32, v32, v33
	v_rcp_f32_e32 v33, v37
	v_rcp_f32_e32 v38, v36
	v_mul_f32_e32 v19, v19, v33
	v_mul_f32_e32 v18, v18, v38
	v_rcp_f32_e32 v39, v37
	s_nop 0
	v_fma_f32 v39, v39, v131, v71
	v_cmp_gt_f32_e32 vcc, s69, v39
	v_pk_mul_f32 v[36:37], v[18:19], v[130:131]
	s_nop 0
	v_cndmask_b32_e64 v40, 0, 32, vcc
	v_ldexp_f32 v39, v39, v40
	v_log_f32_e32 v39, v39
	v_cndmask_b32_e32 v19, 0, v189, vcc
	v_mul_f32_e32 v18, 0x3f317217, v39
	v_fma_f32 v18, v39, s70, -v18
	v_fmac_f32_e32 v18, 0x3377d1cf, v39
	v_fmac_f32_e32 v18, 0x3f317217, v39
	v_cmp_lt_f32_e64 s[6:7], |v39|, s71
	s_nop 1
	v_cndmask_b32_e64 v18, v39, v18, s[6:7]
	v_sub_f32_e32 v33, v18, v19
	global_store_dwordx4 v[26:27], v[20:23], off offset:512
	global_store_dwordx4 v[26:27], v[30:33], off offset:528
	v_cvt_pk_bf16_f32 v19, v16, v17
	v_exp_f32_e32 v22, v12
	v_max_f32_e32 v12, v13, v13
	v_med3_f32 v12, v12, s68, v188
	v_mul_f32_e32 v12, 0xbfb8aa3b, v12
	v_exp_f32_e32 v23, v12
	v_cvt_pk_bf16_f32 v18, v28, v29
	v_cvt_pk_bf16_f32 v20, v34, v35
	v_cvt_pk_bf16_f32 v21, v36, v37
	v_pk_add_f32 v[26:27], v[22:23], 1.0 op_sel_hi:[1,0]
	global_store_dwordx4 v[24:25], v[18:21], off offset:256
	v_add_u32_e32 v12, s45, v184
	v_rcp_f32_e32 v13, v26
	s_nop 0
	v_fma_f32 v13, v13, v166, v88
	v_cmp_gt_f32_e32 vcc, s69, v13
	s_nop 1
	v_cndmask_b32_e64 v16, 0, 32, vcc
	v_ldexp_f32 v13, v13, v16
	v_log_f32_e32 v18, v13
	v_ashrrev_i32_e32 v13, 31, v12
	v_lshlrev_b64 v[12:13], 11, v[12:13]
	v_lshl_add_u64 v[16:17], v[12:13], 0, v[160:161]
	v_mul_f32_e32 v12, 0x3f317217, v18
	v_fma_f32 v12, v18, s70, -v12
	v_fmac_f32_e32 v12, 0x3377d1cf, v18
	v_fmac_f32_e32 v12, 0x3f317217, v18
	v_cmp_lt_f32_e64 s[6:7], |v18|, s71
	s_nop 1
	v_cndmask_b32_e64 v12, v18, v12, s[6:7]
	v_cndmask_b32_e32 v18, 0, v189, vcc
	v_sub_f32_e32 v12, v12, v18
	v_rcp_f32_e32 v13, v27
	v_rcp_f32_e32 v18, v27
	v_mul_f32_e32 v19, v23, v13
	v_fma_f32 v18, v18, v167, v89
	v_cmp_gt_f32_e64 s[6:7], s69, v18
	s_nop 1
	v_cndmask_b32_e64 v20, 0, 32, s[6:7]
	v_ldexp_f32 v18, v18, v20
	v_exp_f32_e32 v20, v14
	v_max_f32_e32 v14, v15, v15
	v_med3_f32 v14, v14, s68, v188
	v_mul_f32_e32 v14, 0xbfb8aa3b, v14
	v_exp_f32_e32 v21, v14
	v_log_f32_e32 v24, v18
	v_rcp_f32_e32 v13, v26
	s_nop 0
	v_mul_f32_e32 v18, v22, v13
	v_pk_mul_f32 v[18:19], v[18:19], v[166:167]
	v_pk_add_f32 v[22:23], v[20:21], 1.0 op_sel_hi:[1,0]
; DI bf16x8 pack8(const f32x4& a, const f32x4& b) { v4u w; w.x = pk2(a[0], a[1]); w.y = pk2(a[2], a[3]); w.z = pk2(b[0], b[1]); w.w = pk2(b[2], b[3]); return __builtin_bit_cast(bf16x8, w); }
;     DI void operator()(const f32x4 (&acc)[2][2][4][2], const pg8::Unit& u, int wr, int wc, int fr, int fq) const {
;     ...
;                 for (int bj = 0; bj < 2; ++bj) { const size_t o = (size_t)row * D + cbase + bj * 128; f32x4 lg[2], kk[2];
; #pragma unroll
;                     for (int n = 0; n < 2; ++n)
; #pragma unroll
;                         for (int e = 0; e < 4; ++e) { const float f = fminf(fmaxf(acc[ai][bj][m][n][e], -30.f), 30.f), lb = lbv[bj][n][e], ef = __expf(-f), sg = 1.f / (1.f + ef), sgn = ef / (1.f + ef);
;                             lg[n][e] = __logf(lb + (1.f - lb) * sg); kk[n][e] = (1.f - lb) * sgn; }
;                     *(f32x4*)(lf + o) = lg[0]; *(f32x4*)(lf + o + 4) = lg[1]; *(bf16x8*)(zq + (size_t)T * D + o) = pack8(kk[0], kk[1]); }
	v_mul_f32_e32 v13, 0x3f317217, v24
	v_fma_f32 v13, v24, s70, -v13
	v_fmac_f32_e32 v13, 0x3377d1cf, v24
	v_fmac_f32_e32 v13, 0x3f317217, v24
	v_rcp_f32_e32 v14, v22
	s_nop 0
	v_fma_f32 v14, v14, v162, v90
	v_cmp_gt_f32_e32 vcc, s69, v14
	v_cmp_lt_f32_e64 s[8:9], |v24|, s71
	s_nop 0
	v_cndmask_b32_e64 v15, 0, 32, vcc
	v_ldexp_f32 v14, v14, v15
	v_log_f32_e32 v14, v14
	v_cndmask_b32_e64 v13, v24, v13, s[8:9]
	v_cndmask_b32_e64 v15, 0, v189, s[6:7]
	v_sub_f32_e32 v13, v13, v15
	v_mul_f32_e32 v15, 0x3f317217, v14
	v_fma_f32 v15, v14, s70, -v15
	v_fmac_f32_e32 v15, 0x3377d1cf, v14
	v_fmac_f32_e32 v15, 0x3f317217, v14
	v_cmp_lt_f32_e64 s[6:7], |v14|, s71
	s_nop 1
	v_cndmask_b32_e64 v14, v14, v15, s[6:7]
	v_cndmask_b32_e32 v15, 0, v189, vcc
	v_sub_f32_e32 v14, v14, v15
	v_rcp_f32_e32 v15, v23
	s_nop 0
	v_mul_f32_e32 v21, v21, v15
	v_rcp_f32_e32 v15, v22
	v_rcp_f32_e32 v23, v23
	v_mul_f32_e32 v20, v20, v15
	v_pk_add_f32 v[24:25], v[8:9], 1.0 op_sel_hi:[1,0]
	v_fmac_f32_e32 v91, v23, v163
	v_cmp_gt_f32_e64 s[6:7], s69, v91
	v_pk_mul_f32 v[20:21], v[20:21], v[162:163]
	s_nop 0
	v_cndmask_b32_e64 v23, 0, 32, s[6:7]
	v_ldexp_f32 v23, v91, v23
	v_log_f32_e32 v23, v23
	v_rcp_f32_e32 v22, v24
	s_nop 0
	v_fma_f32 v22, v22, v136, v80
	v_cmp_gt_f32_e32 vcc, s69, v22
	v_mul_f32_e32 v15, 0x3f317217, v23
	v_fma_f32 v15, v23, s70, -v15
	v_cndmask_b32_e64 v26, 0, 32, vcc
	v_ldexp_f32 v22, v22, v26
	v_log_f32_e32 v22, v22
	v_fmac_f32_e32 v15, 0x3377d1cf, v23
	v_fmac_f32_e32 v15, 0x3f317217, v23
	v_cmp_lt_f32_e64 s[8:9], |v23|, s71
	s_nop 1
	v_cndmask_b32_e64 v15, v23, v15, s[8:9]
	v_cndmask_b32_e64 v23, 0, v189, s[6:7]
	v_sub_f32_e32 v15, v15, v23
	v_mul_f32_e32 v23, 0x3f317217, v22
	v_fma_f32 v23, v22, s70, -v23
	v_fmac_f32_e32 v23, 0x3377d1cf, v22
	v_fmac_f32_e32 v23, 0x3f317217, v22
	v_cmp_lt_f32_e64 s[6:7], |v22|, s71
	s_nop 1
	v_cndmask_b32_e64 v22, v22, v23, s[6:7]
	v_cndmask_b32_e32 v23, 0, v189, vcc
	v_sub_f32_e32 v22, v22, v23
	v_rcp_f32_e32 v23, v25
	s_nop 0
	v_mul_f32_e32 v9, v9, v23
	v_rcp_f32_e32 v23, v24
	v_rcp_f32_e32 v25, v25
	v_mul_f32_e32 v8, v8, v23
	v_fma_f32 v25, v25, v137, v81
	v_cmp_gt_f32_e64 s[6:7], s69, v25
	s_nop 1
	v_cndmask_b32_e64 v26, 0, 32, s[6:7]
	v_ldexp_f32 v25, v25, v26
	v_pk_mul_f32 v[26:27], v[8:9], v[136:137]
	v_pk_add_f32 v[8:9], v[10:11], 1.0 op_sel_hi:[1,0]
	v_log_f32_e32 v25, v25
	s_nop 0
	v_mul_f32_e32 v23, 0x3f317217, v25
	v_fma_f32 v23, v25, s70, -v23
	v_fmac_f32_e32 v23, 0x3377d1cf, v25
	v_rcp_f32_e32 v24, v8
	s_nop 0
	v_fma_f32 v24, v24, v164, v82
	v_cmp_gt_f32_e32 vcc, s69, v24
	v_fmac_f32_e32 v23, 0x3f317217, v25
	v_cmp_lt_f32_e64 s[8:9], |v25|, s71
	v_cndmask_b32_e64 v28, 0, 32, vcc
	v_ldexp_f32 v24, v24, v28
	v_log_f32_e32 v24, v24
	v_cndmask_b32_e64 v23, v25, v23, s[8:9]
	v_cndmask_b32_e64 v25, 0, v189, s[6:7]
	v_sub_f32_e32 v23, v23, v25
	v_mul_f32_e32 v25, 0x3f317217, v24
	v_fma_f32 v25, v24, s70, -v25
	v_fmac_f32_e32 v25, 0x3377d1cf, v24
	v_fmac_f32_e32 v25, 0x3f317217, v24
	v_cmp_lt_f32_e64 s[6:7], |v24|, s71
	s_nop 1
	v_cndmask_b32_e64 v24, v24, v25, s[6:7]
	v_cndmask_b32_e32 v25, 0, v189, vcc
	v_sub_f32_e32 v24, v24, v25
	v_rcp_f32_e32 v28, v8
	v_rcp_f32_e32 v29, v9
	v_mul_f32_e32 v8, v10, v28
	v_fmac_f32_e32 v83, v29, v165
	v_cmp_gt_f32_e32 vcc, s69, v83
	v_rcp_f32_e32 v25, v9
	s_nop 0
	v_mul_f32_e32 v9, v11, v25
	v_pk_mul_f32 v[10:11], v[8:9], v[164:165]
	v_cndmask_b32_e64 v29, 0, 32, vcc
	v_ldexp_f32 v29, v83, v29
	v_log_f32_e32 v29, v29
	v_exp_f32_e32 v28, v4
	v_max_f32_e32 v4, v5, v5
	v_med3_f32 v4, v4, s68, v188
	v_mul_f32_e32 v8, 0x3f317217, v29
	v_fma_f32 v8, v29, s70, -v8
	v_fmac_f32_e32 v8, 0x3377d1cf, v29
	v_fmac_f32_e32 v8, 0x3f317217, v29
	v_cmp_lt_f32_e64 s[6:7], |v29|, s71
	v_mul_f32_e32 v4, 0xbfb8aa3b, v4
	v_cndmask_b32_e32 v9, 0, v189, vcc
	v_cndmask_b32_e64 v8, v29, v8, s[6:7]
	v_exp_f32_e32 v29, v4
	v_sub_f32_e32 v25, v8, v9
	v_lshl_add_u64 v[8:9], v[16:17], 2, s[18:19]
	global_store_dwordx4 v[8:9], v[12:15], off
	global_store_dwordx4 v[8:9], v[22:25], off offset:16
	s_nop 0
	v_cvt_pk_bf16_f32 v12, v18, v19
	v_pk_add_f32 v[22:23], v[28:29], 1.0 op_sel_hi:[1,0]
	v_cvt_pk_bf16_f32 v13, v20, v21
	v_cvt_pk_bf16_f32 v14, v26, v27
	v_rcp_f32_e32 v4, v22
	s_nop 0
	v_fma_f32 v4, v4, v138, v76
	v_cmp_gt_f32_e32 vcc, s69, v4
	v_cvt_pk_bf16_f32 v15, v10, v11
	v_lshl_add_u64 v[10:11], v[16:17], 1, s[42:43]
	v_cndmask_b32_e64 v5, 0, 32, vcc
	v_ldexp_f32 v4, v4, v5
	v_log_f32_e32 v4, v4
	global_store_dwordx4 v[10:11], v[12:15], off
	v_mul_f32_e32 v5, 0x3f317217, v4
	s_nop 0
	v_fma_f32 v5, v4, s70, -v5
	v_fmac_f32_e32 v5, 0x3377d1cf, v4
	v_fmac_f32_e32 v5, 0x3f317217, v4
	v_cmp_lt_f32_e64 s[6:7], |v4|, s71
	s_nop 1
	v_cndmask_b32_e64 v4, v4, v5, s[6:7]
	v_cndmask_b32_e32 v5, 0, v189, vcc
	v_sub_f32_e32 v4, v4, v5
	v_rcp_f32_e32 v5, v23
; DI bf16x8 pack8(const f32x4& a, const f32x4& b) { v4u w; w.x = pk2(a[0], a[1]); w.y = pk2(a[2], a[3]); w.z = pk2(b[0], b[1]); w.w = pk2(b[2], b[3]); return __builtin_bit_cast(bf16x8, w); }
;     DI void operator()(const f32x4 (&acc)[2][2][4][2], const pg8::Unit& u, int wr, int wc, int fr, int fq) const {
;     ...
;                 for (int bj = 0; bj < 2; ++bj) { const size_t o = (size_t)row * D + cbase + bj * 128; f32x4 lg[2], kk[2];
; #pragma unroll
;                     for (int n = 0; n < 2; ++n)
; #pragma unroll
;                         for (int e = 0; e < 4; ++e) { const float f = fminf(fmaxf(acc[ai][bj][m][n][e], -30.f), 30.f), lb = lbv[bj][n][e], ef = __expf(-f), sg = 1.f / (1.f + ef), sgn = ef / (1.f + ef);
;                             lg[n][e] = __logf(lb + (1.f - lb) * sg); kk[n][e] = (1.f - lb) * sgn; }
;                     *(f32x4*)(lf + o) = lg[0]; *(f32x4*)(lf + o + 4) = lg[1]; *(bf16x8*)(zq + (size_t)T * D + o) = pack8(kk[0], kk[1]); }
;             EPI_LOOP_END
	v_rcp_f32_e32 v12, v23
	v_mul_f32_e32 v13, v29, v5
	v_fma_f32 v12, v12, v139, v77
	v_cmp_gt_f32_e64 s[6:7], s69, v12
	s_nop 1
	v_cndmask_b32_e64 v14, 0, 32, s[6:7]
	v_ldexp_f32 v12, v12, v14
	v_exp_f32_e32 v14, v6
	v_max_f32_e32 v6, v7, v7
	v_med3_f32 v6, v6, s68, v188
	v_mul_f32_e32 v6, 0xbfb8aa3b, v6
	v_exp_f32_e32 v15, v6
	v_log_f32_e32 v18, v12
	v_rcp_f32_e32 v5, v22
	s_nop 0
	v_mul_f32_e32 v12, v28, v5
	v_pk_mul_f32 v[12:13], v[12:13], v[138:139]
	v_pk_add_f32 v[16:17], v[14:15], 1.0 op_sel_hi:[1,0]
	v_mul_f32_e32 v5, 0x3f317217, v18
	v_fma_f32 v5, v18, s70, -v5
	v_fmac_f32_e32 v5, 0x3377d1cf, v18
	v_fmac_f32_e32 v5, 0x3f317217, v18
	v_rcp_f32_e32 v6, v16
	s_nop 0
	v_fma_f32 v6, v6, v140, v78
	v_cmp_gt_f32_e32 vcc, s69, v6
	v_cmp_lt_f32_e64 s[8:9], |v18|, s71
	s_nop 0
	v_cndmask_b32_e64 v7, 0, 32, vcc
	v_ldexp_f32 v6, v6, v7
	v_log_f32_e32 v6, v6
	v_cndmask_b32_e64 v5, v18, v5, s[8:9]
	v_cndmask_b32_e64 v7, 0, v189, s[6:7]
	v_sub_f32_e32 v5, v5, v7
	v_mul_f32_e32 v7, 0x3f317217, v6
	v_fma_f32 v7, v6, s70, -v7
	v_fmac_f32_e32 v7, 0x3377d1cf, v6
	v_fmac_f32_e32 v7, 0x3f317217, v6
	v_cmp_lt_f32_e64 s[6:7], |v6|, s71
	s_nop 1
	v_cndmask_b32_e64 v6, v6, v7, s[6:7]
	v_cndmask_b32_e32 v7, 0, v189, vcc
	v_sub_f32_e32 v6, v6, v7
	v_rcp_f32_e32 v7, v17
	s_nop 0
	v_mul_f32_e32 v15, v15, v7
	v_rcp_f32_e32 v7, v16
	v_rcp_f32_e32 v17, v17
	v_mul_f32_e32 v14, v14, v7
	v_exp_f32_e32 v18, v0
	v_max_f32_e32 v0, v1, v1
	v_med3_f32 v0, v0, s68, v188
	v_mul_f32_e32 v0, 0xbfb8aa3b, v0
	v_fmac_f32_e32 v79, v17, v141
	v_exp_f32_e32 v19, v0
	v_cmp_gt_f32_e64 s[6:7], s69, v79
	v_pk_mul_f32 v[14:15], v[14:15], v[140:141]
	s_nop 0
	v_cndmask_b32_e64 v17, 0, 32, s[6:7]
	v_ldexp_f32 v17, v79, v17
	v_log_f32_e32 v20, v17
	v_pk_add_f32 v[16:17], v[18:19], 1.0 op_sel_hi:[1,0]
	v_mul_f32_e32 v0, 0x3f317217, v20
	v_fma_f32 v0, v20, s70, -v0
	v_fmac_f32_e32 v0, 0x3377d1cf, v20
	v_fmac_f32_e32 v0, 0x3f317217, v20
	v_rcp_f32_e32 v1, v16
	s_nop 0
	v_fma_f32 v1, v1, v128, v68
	v_cmp_gt_f32_e32 vcc, s69, v1
	v_cmp_lt_f32_e64 s[8:9], |v20|, s71
	s_nop 0
	v_cndmask_b32_e64 v7, 0, 32, vcc
	v_ldexp_f32 v1, v1, v7
	v_log_f32_e32 v1, v1
	v_cndmask_b32_e64 v0, v20, v0, s[8:9]
	v_cndmask_b32_e64 v7, 0, v189, s[6:7]
	v_sub_f32_e32 v7, v0, v7
	v_mul_f32_e32 v0, 0x3f317217, v1
	v_fma_f32 v0, v1, s70, -v0
	v_fmac_f32_e32 v0, 0x3377d1cf, v1
	v_fmac_f32_e32 v0, 0x3f317217, v1
	v_cmp_lt_f32_e64 s[6:7], |v1|, s71
	s_nop 1
	v_cndmask_b32_e64 v0, v1, v0, s[6:7]
	v_cndmask_b32_e32 v1, 0, v189, vcc
	v_sub_f32_e32 v0, v0, v1
	v_rcp_f32_e32 v1, v17
	s_nop 0
	v_mul_f32_e32 v19, v19, v1
	v_rcp_f32_e32 v1, v16
	v_rcp_f32_e32 v17, v17
	v_mul_f32_e32 v18, v18, v1
	v_fma_f32 v17, v17, v129, v69
	v_cmp_gt_f32_e64 s[6:7], s69, v17
	s_nop 1
	v_cndmask_b32_e64 v20, 0, 32, s[6:7]
	v_ldexp_f32 v17, v17, v20
	v_exp_f32_e32 v20, v2
	v_max_f32_e32 v2, v3, v3
	v_med3_f32 v2, v2, s68, v188
	v_mul_f32_e32 v2, 0xbfb8aa3b, v2
	v_exp_f32_e32 v21, v2
	v_log_f32_e32 v22, v17
	v_pk_mul_f32 v[16:17], v[18:19], v[128:129]
	v_pk_add_f32 v[18:19], v[20:21], 1.0 op_sel_hi:[1,0]
	s_nop 0
	v_mul_f32_e32 v1, 0x3f317217, v22
	v_fma_f32 v1, v22, s70, -v1
	v_fmac_f32_e32 v1, 0x3377d1cf, v22
	v_rcp_f32_e32 v2, v18
	s_nop 0
	v_fma_f32 v2, v2, v130, v70
	v_cmp_gt_f32_e32 vcc, s69, v2
	v_fmac_f32_e32 v1, 0x3f317217, v22
	v_cmp_lt_f32_e64 s[8:9], |v22|, s71
	v_cndmask_b32_e64 v3, 0, 32, vcc
	v_ldexp_f32 v2, v2, v3
	v_log_f32_e32 v2, v2
	v_cndmask_b32_e64 v1, v22, v1, s[8:9]
	v_cndmask_b32_e64 v3, 0, v189, s[6:7]
	v_sub_f32_e32 v1, v1, v3
	v_mul_f32_e32 v3, 0x3f317217, v2
	v_fma_f32 v3, v2, s70, -v3
	v_fmac_f32_e32 v3, 0x3377d1cf, v2
	v_fmac_f32_e32 v3, 0x3f317217, v2
	v_cmp_lt_f32_e64 s[6:7], |v2|, s71
	s_nop 1
	v_cndmask_b32_e64 v2, v2, v3, s[6:7]
	v_cndmask_b32_e32 v3, 0, v189, vcc
	v_sub_f32_e32 v2, v2, v3
	v_rcp_f32_e32 v22, v18
	v_rcp_f32_e32 v23, v19
	v_mul_f32_e32 v18, v20, v22
	v_fmac_f32_e32 v71, v23, v131
	v_cmp_gt_f32_e32 vcc, s69, v71
	v_rcp_f32_e32 v3, v19
	s_nop 0
	v_mul_f32_e32 v19, v21, v3
	v_pk_mul_f32 v[18:19], v[18:19], v[130:131]
	v_cndmask_b32_e64 v23, 0, 32, vcc
	v_ldexp_f32 v23, v71, v23
	v_log_f32_e32 v23, v23
	v_cndmask_b32_e32 v20, 0, v189, vcc
	v_mul_f32_e32 v3, 0x3f317217, v23
	v_fma_f32 v3, v23, s70, -v3
	v_fmac_f32_e32 v3, 0x3377d1cf, v23
	v_fmac_f32_e32 v3, 0x3f317217, v23
	v_cmp_lt_f32_e64 s[6:7], |v23|, s71
	s_nop 1
	v_cndmask_b32_e64 v3, v23, v3, s[6:7]
	v_sub_f32_e32 v3, v3, v20
	global_store_dwordx4 v[8:9], v[4:7], off offset:512
	global_store_dwordx4 v[8:9], v[0:3], off offset:528
	s_nop 1
	v_cvt_pk_bf16_f32 v0, v12, v13
	v_cvt_pk_bf16_f32 v1, v14, v15
	v_cvt_pk_bf16_f32 v2, v16, v17
	v_cvt_pk_bf16_f32 v3, v18, v19
	global_store_dwordx4 v[10:11], v[0:3], off offset:256
	s_andn2_b64 vcc, exec, s[4:5]
	s_mov_b64 s[4:5], -1
	s_cbranch_vccnz .LBB0_222

; DI float silu(float x) { return x / (1.f + __expf(-x)); }
; #define LDS_WAIT() asm volatile("s_waitcnt lgkmcnt(0)" ::: "memory")
; #define HS_LOAD(r_, bt) do { _Pragma("unroll") for (int i_ = 0; i_ < 8; ++i_) r_[i_] = __builtin_nontemporal_load((const f32x4*)(S0 + (size_t)(2 * (8 * (bt) + i_)) * 128)); } while (0)
; DI void hgrn_sample(LAS float* wsc, const float* RS1, const float* LB0, const float* st_in, float* st_out, const float* gnorm, bf16* OGS, int b, int h, int lane) {
;     { const float* r = RS1 + (size_t)b * NA + h * 128 + 2 * lane;
;       const f32x2 qr = *(const f32x2*)r, fr_ = *(const f32x2*)(r + 2048), lb = *(const f32x2*)(LB0 + h * 128 + 2 * lane);
; #pragma unroll
;       for (int e = 0; e < 2; ++e) { const float f = fminf(fmaxf(fr_[e], -30.f), 30.f), ef = __expf(-f), sg = 1.f / (1.f + ef), sgn = ef / (1.f + ef);
;           wsc[2 * lane + e] = lb[e] + (1.f - lb[e]) * sg; wsc[128 + 2 * lane + e] = (1.f - lb[e]) * sgn; wsc[256 + 2 * lane + e] = silu(qr[e]); } }
;     LDS_WAIT(); asm volatile("" ::: "memory");
;     const int half = lane >> 5, c4 = lane & 31;
;     const f32x4 iv = *(const f32x4*)(RS1 + (size_t)b * NA + 4096 + h * 128 + 4 * c4), gr = *(const f32x4*)(RS1 + (size_t)b * NA + 6144 + h * 128 + 4 * c4);
;     const float* S0 = st_in + ((size_t)(b * 16 + h) * 128 + half) * 128 + 4 * c4; float* So = st_out + ((size_t)(b * 16 + h) * 128 + half) * 128 + 4 * c4;
;     f32x4 o = (f32x4){0.f, 0.f, 0.f, 0.f};
;     f32x4 ra[8], rb[8];
;     ...
;     HS_LOAD(ra, 0);
.LBB0_341:
	s_ashr_i32 s42, s40, 4
	s_ashr_i32 s43, s42, 31
	s_lshl_b64 s[6:7], s[42:43], 15
	s_add_u32 s6, s3, s6
	s_addc_u32 s7, s29, s7
	s_lshl_b32 s8, s40, 7
	s_and_b32 s43, s8, 0x780
	s_lshl_b32 s16, s43, 2
	s_add_u32 s44, s6, s16
	s_addc_u32 s45, s7, 0
	v_lshl_add_u64 v[0:1], v[104:105], 2, s[44:45]
	v_lshl_add_u64 v[4:5], v[106:107], 0, s[16:17]
	global_load_dwordx2 v[2:3], v[0:1], off
	s_ashr_i32 s41, s40, 31
	global_load_dwordx2 v[4:5], v[4:5], off
	v_add_co_u32_e32 v0, vcc, s21, v0
	v_mov_b32_e32 v150, v146
	s_nop 0
	v_addc_co_u32_e32 v1, vcc, 0, v1, vcc
	global_load_dwordx2 v[0:1], v[0:1], off
	v_mov_b64_e32 v[124:125], v[120:121]
	v_mov_b64_e32 v[126:127], v[118:119]
	v_mov_b32_e32 v130, 0
	v_mov_b32_e32 v131, v111
	v_mov_b32_e32 v128, 0
	v_mov_b32_e32 v129, v111
	s_waitcnt vmcnt(0)
	v_mul_f32_e32 v6, 0xbfb8aa3b, v2
	v_mul_f32_e32 v8, 0xbfb8aa3b, v3
	s_waitcnt lgkmcnt(0)
	v_max_f32_e32 v9, v0, v0
	v_max_f32_e32 v10, v1, v1
	v_exp_f32_e32 v0, v6
	v_exp_f32_e32 v1, v8
	v_med3_f32 v8, v9, s34, v147
	v_med3_f32 v9, v10, s34, v147
	v_mul_f32_e32 v8, 0xbfb8aa3b, v8
	v_mul_f32_e32 v9, 0xbfb8aa3b, v9
	v_exp_f32_e32 v8, v8
	v_exp_f32_e32 v9, v9
	v_pk_add_f32 v[0:1], v[0:1], 1.0 op_sel_hi:[1,0]
	v_pk_add_f32 v[6:7], v[4:5], 1.0 op_sel_hi:[1,0] neg_lo:[1,0] neg_hi:[1,0]
	v_pk_add_f32 v[10:11], v[8:9], 1.0 op_sel_hi:[1,0]
	v_rcp_f32_e32 v13, v11
	v_rcp_f32_e32 v18, v11
	v_rcp_f32_e32 v12, v10
	v_mul_f32_e32 v9, v9, v18
	v_rcp_f32_e32 v11, v10
	s_nop 0
	v_mul_f32_e32 v8, v8, v11
	v_rcp_f32_e32 v10, v1
	s_nop 0
	v_mul_f32_e32 v1, v3, v10
	v_rcp_f32_e32 v3, v0
	s_nop 0
	v_mul_f32_e32 v0, v2, v3
	ds_write_b64 v145, v[0:1] offset:1024
	v_lshl_add_u64 v[0:1], s[44:45], 0, v[122:123]
	v_add_co_u32_e32 v2, vcc, s35, v0
	s_lshl_b64 s[6:7], s[40:41], 14
	s_nop 0
	v_addc_co_u32_e32 v3, vcc, 0, v1, vcc
	v_pk_fma_f32 v[4:5], v[6:7], v[12:13], v[4:5]
	v_pk_mul_f32 v[6:7], v[6:7], v[8:9]
	v_add_co_u32_e32 v0, vcc, s37, v0
	v_lshl_add_u64 v[8:9], s[6:7], 0, v[112:113]
	ds_write2st64_b64 v145, v[4:5], v[6:7] offset1:1
	v_addc_co_u32_e32 v1, vcc, 0, v1, vcc
	v_lshl_add_u64 v[24:25], v[8:9], 2, v[114:115]
	s_waitcnt lgkmcnt(0)
	v_add_co_u32_e32 v40, vcc, s46, v24
	global_load_dwordx4 v[4:7], v[2:3], off
	s_nop 0
	global_load_dwordx4 v[0:3], v[0:1], off
	v_addc_co_u32_e32 v41, vcc, 0, v25, vcc
	global_load_dwordx4 v[8:11], v[24:25], off nt
	global_load_dwordx4 v[12:15], v[24:25], off offset:1024 nt
	global_load_dwordx4 v[16:19], v[24:25], off offset:2048 nt
	global_load_dwordx4 v[20:23], v[24:25], off offset:3072 nt
	s_nop 0
	global_load_dwordx4 v[24:27], v[40:41], off nt
	global_load_dwordx4 v[28:31], v[40:41], off offset:1024 nt
	global_load_dwordx4 v[32:35], v[40:41], off offset:2048 nt
	global_load_dwordx4 v[36:39], v[40:41], off offset:3072 nt
	s_mov_b32 s8, 0
	s_branch .LBB0_343

; DI float silu(float x) { return x / (1.f + __expf(-x)); }
; #define LDS_WAIT() asm volatile("s_waitcnt lgkmcnt(0)" ::: "memory")
; #define HS_LOAD(r_, bt) do { _Pragma("unroll") for (int i_ = 0; i_ < 8; ++i_) r_[i_] = __builtin_nontemporal_load((const f32x4*)(S0 + (size_t)(2 * (8 * (bt) + i_)) * 128)); } while (0)
; DI void hgrn_sample(LAS float* wsc, const float* RS1, const float* LB0, const float* st_in, float* st_out, const float* gnorm, bf16* OGS, int b, int h, int lane) {
;     { const float* r = RS1 + (size_t)b * NA + h * 128 + 2 * lane;
;       const f32x2 qr = *(const f32x2*)r, fr_ = *(const f32x2*)(r + 2048), lb = *(const f32x2*)(LB0 + h * 128 + 2 * lane);
; #pragma unroll
;       for (int e = 0; e < 2; ++e) { const float f = fminf(fmaxf(fr_[e], -30.f), 30.f), ef = __expf(-f), sg = 1.f / (1.f + ef), sgn = ef / (1.f + ef);
;           wsc[2 * lane + e] = lb[e] + (1.f - lb[e]) * sg; wsc[128 + 2 * lane + e] = (1.f - lb[e]) * sgn; wsc[256 + 2 * lane + e] = silu(qr[e]); } }
;     LDS_WAIT(); asm volatile("" ::: "memory");
;     const int half = lane >> 5, c4 = lane & 31;
;     const f32x4 iv = *(const f32x4*)(RS1 + (size_t)b * NA + 4096 + h * 128 + 4 * c4), gr = *(const f32x4*)(RS1 + (size_t)b * NA + 6144 + h * 128 + 4 * c4);
;     const float* S0 = st_in + ((size_t)(b * 16 + h) * 128 + half) * 128 + 4 * c4; float* So = st_out + ((size_t)(b * 16 + h) * 128 + half) * 128 + 4 * c4;
;     f32x4 o = (f32x4){0.f, 0.f, 0.f, 0.f};
;     f32x4 ra[8], rb[8];
;     ...
;     HS_LOAD(ra, 0);
.LBB0_386:
	s_ashr_i32 s40, s38, 4
	s_ashr_i32 s41, s40, 31
	s_lshl_b64 s[6:7], s[40:41], 15
	s_add_u32 s6, s3, s6
	s_addc_u32 s7, s29, s7
	s_lshl_b32 s8, s38, 7
	s_and_b32 s41, s8, 0x780
	s_lshl_b32 s16, s41, 2
	s_add_u32 s42, s6, s16
	s_addc_u32 s43, s7, 0
	v_lshl_add_u64 v[0:1], v[104:105], 2, s[42:43]
	v_lshl_add_u64 v[4:5], v[106:107], 0, s[16:17]
	global_load_dwordx2 v[2:3], v[0:1], off
	s_ashr_i32 s39, s38, 31
	global_load_dwordx2 v[4:5], v[4:5], off
	v_add_co_u32_e32 v0, vcc, s21, v0
	v_mov_b32_e32 v148, v145
	s_nop 0
	v_addc_co_u32_e32 v1, vcc, 0, v1, vcc
	global_load_dwordx2 v[0:1], v[0:1], off
	v_mov_b64_e32 v[124:125], v[120:121]
	v_mov_b64_e32 v[126:127], v[118:119]
	v_mov_b32_e32 v130, 0
	v_mov_b32_e32 v131, v111
	v_mov_b32_e32 v128, 0
	v_mov_b32_e32 v129, v111
	s_waitcnt vmcnt(2)
	v_mul_f32_e32 v6, 0xbfb8aa3b, v2
	v_mul_f32_e32 v8, 0xbfb8aa3b, v3
	s_waitcnt vmcnt(0) lgkmcnt(0)
	v_max_f32_e32 v9, v0, v0
	v_max_f32_e32 v10, v1, v1
	v_exp_f32_e32 v0, v6
	v_exp_f32_e32 v1, v8
	v_med3_f32 v8, v9, s34, v109
	v_med3_f32 v9, v10, s34, v109
	v_mul_f32_e32 v8, 0xbfb8aa3b, v8
	v_mul_f32_e32 v9, 0xbfb8aa3b, v9
	v_exp_f32_e32 v8, v8
	v_exp_f32_e32 v9, v9
	v_pk_add_f32 v[0:1], v[0:1], 1.0 op_sel_hi:[1,0]
	v_pk_add_f32 v[6:7], v[4:5], 1.0 op_sel_hi:[1,0] neg_lo:[1,0] neg_hi:[1,0]
	v_pk_add_f32 v[10:11], v[8:9], 1.0 op_sel_hi:[1,0]
	v_rcp_f32_e32 v13, v11
	v_rcp_f32_e32 v18, v11
	v_rcp_f32_e32 v12, v10
	v_mul_f32_e32 v9, v9, v18
	v_rcp_f32_e32 v11, v10
	s_nop 0
	v_mul_f32_e32 v8, v8, v11
	v_rcp_f32_e32 v10, v1
	s_nop 0
	v_mul_f32_e32 v1, v3, v10
	v_rcp_f32_e32 v3, v0
	s_nop 0
	v_mul_f32_e32 v0, v2, v3
	ds_write_b64 v144, v[0:1] offset:1024
	v_lshl_add_u64 v[0:1], s[42:43], 0, v[122:123]
	v_add_co_u32_e32 v2, vcc, s35, v0
	s_lshl_b64 s[6:7], s[38:39], 14
	s_nop 0
	v_addc_co_u32_e32 v3, vcc, 0, v1, vcc
	v_pk_fma_f32 v[4:5], v[6:7], v[12:13], v[4:5]
	v_pk_mul_f32 v[6:7], v[6:7], v[8:9]
	v_add_co_u32_e32 v0, vcc, s37, v0
	v_lshl_add_u64 v[8:9], s[6:7], 0, v[112:113]
	ds_write2st64_b64 v144, v[4:5], v[6:7] offset1:1
	v_addc_co_u32_e32 v1, vcc, 0, v1, vcc
	v_lshl_add_u64 v[24:25], v[8:9], 2, v[114:115]
	s_waitcnt lgkmcnt(0)
	v_add_co_u32_e32 v40, vcc, s44, v24
	global_load_dwordx4 v[4:7], v[2:3], off
	s_nop 0
	global_load_dwordx4 v[0:3], v[0:1], off
	v_addc_co_u32_e32 v41, vcc, 0, v25, vcc
	global_load_dwordx4 v[8:11], v[24:25], off nt
	global_load_dwordx4 v[12:15], v[24:25], off offset:1024 nt
	global_load_dwordx4 v[16:19], v[24:25], off offset:2048 nt
	global_load_dwordx4 v[20:23], v[24:25], off offset:3072 nt
	s_nop 0
	global_load_dwordx4 v[24:27], v[40:41], off nt
	global_load_dwordx4 v[28:31], v[40:41], off offset:1024 nt
	global_load_dwordx4 v[32:35], v[40:41], off offset:2048 nt
	global_load_dwordx4 v[36:39], v[40:41], off offset:3072 nt
	s_mov_b32 s8, 0
	s_branch .LBB0_388

.LBB0_619:
	v_ashrrev_i32_e32 v51, 1, v50
	v_add_u32_e32 v180, s53, v51
	v_ashrrev_i32_e32 v181, 31, v180
	v_add_u32_e32 v52, 0x200, v50
	v_mad_u64_u32 v[176:177], s[6:7], v51, s29, v[38:39]
	v_mad_i64_i32 v[182:183], s[6:7], v180, s50, v[42:43]
	v_lshl_add_u64 v[180:181], v[180:181], 2, s[22:23]
	v_cmp_lt_i32_e32 vcc, s51, v50
	v_mov_b32_e32 v50, v52
	ds_read_b128 v[52:55], v176
	ds_read_b128 v[56:59], v176 offset:16
	ds_read_b128 v[60:63], v176 offset:64
	ds_read_b128 v[64:67], v176 offset:80
	ds_read_b128 v[68:71], v176 offset:9216
	ds_read_b128 v[72:75], v176 offset:9232
	ds_read_b128 v[76:79], v176 offset:9280
	ds_read_b128 v[80:83], v176 offset:9296
	ds_read_b128 v[84:87], v176 offset:18432
	ds_read_b128 v[88:91], v176 offset:18448
	ds_read_b128 v[92:95], v176 offset:18496
	ds_read_b128 v[96:99], v176 offset:18512
	ds_read_b128 v[100:103], v176 offset:27648
	ds_read_b128 v[104:107], v176 offset:27664
	ds_read_b128 v[108:111], v176 offset:27712
	ds_read_b128 v[112:115], v176 offset:27728
	ds_read_b128 v[116:119], v176 offset:36864
	ds_read_b128 v[120:123], v176 offset:36880
	ds_read_b128 v[124:127], v176 offset:36928
	ds_read_b128 v[128:131], v176 offset:36944
	ds_read_b128 v[132:135], v176 offset:46080
	ds_read_b128 v[136:139], v176 offset:46096
	ds_read_b128 v[140:143], v176 offset:46144
	ds_read_b128 v[144:147], v176 offset:46160
	ds_read_b128 v[148:151], v176 offset:55296
	ds_read_b128 v[152:155], v176 offset:55312
	ds_read_b128 v[156:159], v176 offset:55360
	ds_read_b128 v[160:163], v176 offset:55376
	ds_read_b128 v[164:167], v176 offset:64512
	ds_read_b128 v[168:171], v176 offset:64528
	ds_read_b128 v[172:175], v176 offset:64576
	ds_read_b128 v[176:179], v176 offset:64592
	global_load_dword v51, v[180:181], off
	s_waitcnt lgkmcnt(14)
	v_pk_add_f32 v[52:53], v[52:53], 0 op_sel_hi:[1,0]
	s_or_b64 s[44:45], vcc, s[44:45]
	v_pk_add_f32 v[52:53], v[52:53], v[68:69]
	v_pk_add_f32 v[54:55], v[54:55], 0 op_sel_hi:[1,0]
	v_pk_add_f32 v[58:59], v[58:59], 0 op_sel_hi:[1,0]
	v_pk_add_f32 v[56:57], v[56:57], 0 op_sel_hi:[1,0]
	v_pk_add_f32 v[62:63], v[62:63], 0 op_sel_hi:[1,0]
	v_pk_add_f32 v[60:61], v[60:61], 0 op_sel_hi:[1,0]
	v_pk_add_f32 v[66:67], v[66:67], 0 op_sel_hi:[1,0]
	v_pk_add_f32 v[64:65], v[64:65], 0 op_sel_hi:[1,0]
	v_pk_add_f32 v[54:55], v[54:55], v[70:71]
	v_pk_add_f32 v[58:59], v[58:59], v[74:75]
	v_pk_add_f32 v[56:57], v[56:57], v[72:73]
	v_pk_add_f32 v[62:63], v[62:63], v[78:79]
	v_pk_add_f32 v[60:61], v[60:61], v[76:77]
	v_pk_add_f32 v[66:67], v[66:67], v[82:83]
	v_pk_add_f32 v[64:65], v[64:65], v[80:81]
	v_pk_add_f32 v[52:53], v[52:53], v[84:85]
	v_pk_add_f32 v[54:55], v[54:55], v[86:87]
	v_pk_add_f32 v[58:59], v[58:59], v[90:91]
	v_pk_add_f32 v[56:57], v[56:57], v[88:89]
	v_pk_add_f32 v[62:63], v[62:63], v[94:95]
	v_pk_add_f32 v[60:61], v[60:61], v[92:93]
	v_pk_add_f32 v[66:67], v[66:67], v[98:99]
	v_pk_add_f32 v[64:65], v[64:65], v[96:97]
	v_pk_add_f32 v[52:53], v[52:53], v[100:101]
	v_pk_add_f32 v[54:55], v[54:55], v[102:103]
	v_pk_add_f32 v[58:59], v[58:59], v[106:107]
	v_pk_add_f32 v[56:57], v[56:57], v[104:105]
	v_pk_add_f32 v[62:63], v[62:63], v[110:111]
	v_pk_add_f32 v[60:61], v[60:61], v[108:109]
	v_pk_add_f32 v[66:67], v[66:67], v[114:115]
	v_pk_add_f32 v[64:65], v[64:65], v[112:113]
	v_pk_add_f32 v[52:53], v[52:53], v[116:117]
	v_pk_add_f32 v[54:55], v[54:55], v[118:119]
	v_pk_add_f32 v[58:59], v[58:59], v[122:123]
	v_pk_add_f32 v[56:57], v[56:57], v[120:121]
	s_waitcnt lgkmcnt(13)
	v_pk_add_f32 v[62:63], v[62:63], v[126:127]
	v_pk_add_f32 v[60:61], v[60:61], v[124:125]
	s_waitcnt lgkmcnt(12)
	v_pk_add_f32 v[66:67], v[66:67], v[130:131]
	v_pk_add_f32 v[64:65], v[64:65], v[128:129]
	s_waitcnt lgkmcnt(11)
	v_pk_add_f32 v[52:53], v[52:53], v[132:133]
	v_pk_add_f32 v[54:55], v[54:55], v[134:135]
	s_waitcnt lgkmcnt(10)
	v_pk_add_f32 v[58:59], v[58:59], v[138:139]
	v_pk_add_f32 v[56:57], v[56:57], v[136:137]
	s_waitcnt lgkmcnt(9)
	v_pk_add_f32 v[62:63], v[62:63], v[142:143]
	v_pk_add_f32 v[60:61], v[60:61], v[140:141]
	s_waitcnt lgkmcnt(8)
	v_pk_add_f32 v[66:67], v[66:67], v[146:147]
	v_pk_add_f32 v[64:65], v[64:65], v[144:145]
	s_waitcnt lgkmcnt(7)
	v_pk_add_f32 v[52:53], v[52:53], v[148:149]
	v_pk_add_f32 v[54:55], v[54:55], v[150:151]
	s_waitcnt lgkmcnt(6)
	v_pk_add_f32 v[58:59], v[58:59], v[154:155]
	v_pk_add_f32 v[56:57], v[56:57], v[152:153]
	s_waitcnt lgkmcnt(5)
	v_pk_add_f32 v[62:63], v[62:63], v[158:159]
	v_pk_add_f32 v[60:61], v[60:61], v[156:157]
	s_waitcnt lgkmcnt(4)
	v_pk_add_f32 v[66:67], v[66:67], v[162:163]
	v_pk_add_f32 v[64:65], v[64:65], v[160:161]
	s_waitcnt lgkmcnt(3)
	v_pk_add_f32 v[52:53], v[52:53], v[164:165]
	v_pk_add_f32 v[54:55], v[54:55], v[166:167]
	s_waitcnt lgkmcnt(2)
	v_pk_add_f32 v[58:59], v[58:59], v[170:171]
	v_pk_add_f32 v[56:57], v[56:57], v[168:169]
	s_waitcnt lgkmcnt(1)
	v_pk_add_f32 v[62:63], v[62:63], v[174:175]
	v_pk_add_f32 v[60:61], v[60:61], v[172:173]
	s_waitcnt lgkmcnt(0)
	v_pk_add_f32 v[66:67], v[66:67], v[178:179]
	v_pk_add_f32 v[64:65], v[64:65], v[176:177]
	s_waitcnt vmcnt(0)
	v_fmamk_f32 v51, v51, 0x3a000000, v45
	v_mul_f32_e32 v68, 0x4b800000, v51
	v_cmp_gt_f32_e32 vcc, s49, v51
	s_nop 1
	v_cndmask_b32_e32 v51, v51, v68, vcc
	v_rsq_f32_e32 v51, v51
	s_nop 0
	v_mul_f32_e32 v68, 0x45800000, v51
	v_cndmask_b32_e32 v68, v51, v68, vcc
	v_pk_mul_f32 v[52:53], v[52:53], v[68:69] op_sel_hi:[1,0]
	v_pk_mul_f32 v[60:61], v[60:61], v[68:69] op_sel_hi:[1,0]
	v_pk_mul_f32 v[56:57], v[56:57], v[68:69] op_sel_hi:[1,0]
	v_pk_mul_f32 v[64:65], v[64:65], v[68:69] op_sel_hi:[1,0]
	v_pk_mul_f32 v[54:55], v[54:55], v[68:69] op_sel_hi:[1,0]
	v_pk_mul_f32 v[62:63], v[62:63], v[68:69] op_sel_hi:[1,0]
	v_pk_mul_f32 v[58:59], v[58:59], v[68:69] op_sel_hi:[1,0]
	v_pk_mul_f32 v[66:67], v[66:67], v[68:69] op_sel_hi:[1,0]
	v_mul_f32_e32 v51, 0xbfb8aa3b, v52
	v_mul_f32_e32 v69, 0xbfb8aa3b, v53
	v_exp_f32_e32 v68, v51
	v_exp_f32_e32 v69, v69
	v_mul_f32_e32 v70, 0xbfb8aa3b, v56
	v_mul_f32_e32 v71, 0xbfb8aa3b, v57
	v_exp_f32_e32 v70, v70
	v_exp_f32_e32 v71, v71
	v_mul_f32_e32 v72, 0xbfb8aa3b, v54
	v_mul_f32_e32 v73, 0xbfb8aa3b, v55
	v_exp_f32_e32 v72, v72
	v_exp_f32_e32 v73, v73
	v_pk_add_f32 v[68:69], v[68:69], 1.0 op_sel_hi:[1,0]
	v_mul_f32_e32 v74, 0xbfb8aa3b, v58
	v_mul_f32_e32 v75, 0xbfb8aa3b, v59
	v_exp_f32_e32 v74, v74
	v_exp_f32_e32 v75, v75
	v_pk_add_f32 v[70:71], v[70:71], 1.0 op_sel_hi:[1,0]
	v_pk_add_f32 v[72:73], v[72:73], 1.0 op_sel_hi:[1,0]
	v_pk_add_f32 v[74:75], v[74:75], 1.0 op_sel_hi:[1,0]
	v_rcp_f32_e32 v51, v69
	s_nop 0
	v_mul_f32_e32 v53, v53, v51
	v_rcp_f32_e32 v51, v68
	s_nop 0
	v_mul_f32_e32 v52, v52, v51
	v_rcp_f32_e32 v51, v71
	s_nop 0
	v_mul_f32_e32 v57, v57, v51
	v_rcp_f32_e32 v51, v70
	v_pk_mul_f32 v[52:53], v[60:61], v[52:53]
	v_mul_f32_e32 v56, v56, v51
	v_rcp_f32_e32 v61, v73
	v_rcp_f32_e32 v51, v72
	v_mul_f32_e32 v61, v55, v61
	v_mul_f32_e32 v60, v54, v51
	v_pk_mul_f32 v[56:57], v[64:65], v[56:57]
	v_rcp_f32_e32 v51, v75
	v_cvt_pk_bf16_f32 v54, v56, v57
	v_mul_f32_e32 v59, v59, v51
	v_pk_mul_f32 v[56:57], v[62:63], v[60:61]
	v_rcp_f32_e32 v51, v74
	v_cvt_pk_bf16_f32 v52, v52, v53
	v_mul_f32_e32 v58, v58, v51
	v_cvt_pk_bf16_f32 v53, v56, v57
	v_pk_mul_f32 v[56:57], v[66:67], v[58:59]
	s_nop 0
	v_cvt_pk_bf16_f32 v55, v56, v57
	global_store_dwordx4 v[182:183], v[52:55], off
	s_andn2_b64 exec, exec, s[44:45]
	s_cbranch_execnz .LBB0_619

.LBB0_622:
	v_ashrrev_i32_e32 v3, 1, v2
	v_add_u32_e32 v150, s53, v3
	v_add_u32_e32 v4, 0x200, v2
	v_mad_u64_u32 v[42:43], s[6:7], v3, s29, v[38:39]
	v_ashrrev_i32_e32 v151, 31, v150
	v_cmp_lt_i32_e32 vcc, s51, v2
	v_mov_b32_e32 v2, v4
	ds_read_b128 v[4:7], v42
	ds_read_b128 v[8:11], v42 offset:16
	ds_read_b128 v[12:15], v42 offset:64
	ds_read_b128 v[16:19], v42 offset:80
	ds_read_b128 v[20:23], v42 offset:9216
	ds_read_b128 v[24:27], v42 offset:9232
	ds_read_b128 v[28:31], v42 offset:9280
	ds_read_b128 v[50:53], v42 offset:9296
	ds_read_b128 v[54:57], v42 offset:18432
	ds_read_b128 v[58:61], v42 offset:18448
	ds_read_b128 v[62:65], v42 offset:18496
	ds_read_b128 v[66:69], v42 offset:18512
	ds_read_b128 v[70:73], v42 offset:27648
	ds_read_b128 v[74:77], v42 offset:27664
	ds_read_b128 v[78:81], v42 offset:27712
	ds_read_b128 v[82:85], v42 offset:27728
	ds_read_b128 v[86:89], v42 offset:36864
	ds_read_b128 v[90:93], v42 offset:36880
	ds_read_b128 v[94:97], v42 offset:36928
	ds_read_b128 v[98:101], v42 offset:36944
	ds_read_b128 v[102:105], v42 offset:46080
	ds_read_b128 v[106:109], v42 offset:46096
	ds_read_b128 v[110:113], v42 offset:46144
	ds_read_b128 v[114:117], v42 offset:46160
	ds_read_b128 v[118:121], v42 offset:55296
	ds_read_b128 v[122:125], v42 offset:55312
	ds_read_b128 v[126:129], v42 offset:55360
	ds_read_b128 v[130:133], v42 offset:55376
	ds_read_b128 v[134:137], v42 offset:64512
	ds_read_b128 v[138:141], v42 offset:64528
	ds_read_b128 v[142:145], v42 offset:64576
	ds_read_b128 v[146:149], v42 offset:64592
	v_mad_i64_i32 v[42:43], s[6:7], v150, s50, v[0:1]
	v_lshl_add_u64 v[150:151], v[150:151], 2, s[22:23]
	global_load_dword v3, v[150:151], off
	s_waitcnt lgkmcnt(14)
	v_pk_add_f32 v[4:5], v[4:5], 0 op_sel_hi:[1,0]
	s_or_b64 s[40:41], vcc, s[40:41]
	v_pk_add_f32 v[4:5], v[4:5], v[20:21]
	v_pk_add_f32 v[6:7], v[6:7], 0 op_sel_hi:[1,0]
	v_pk_add_f32 v[10:11], v[10:11], 0 op_sel_hi:[1,0]
	v_pk_add_f32 v[8:9], v[8:9], 0 op_sel_hi:[1,0]
	v_pk_add_f32 v[14:15], v[14:15], 0 op_sel_hi:[1,0]
	v_pk_add_f32 v[12:13], v[12:13], 0 op_sel_hi:[1,0]
	v_pk_add_f32 v[18:19], v[18:19], 0 op_sel_hi:[1,0]
	v_pk_add_f32 v[16:17], v[16:17], 0 op_sel_hi:[1,0]
	v_pk_add_f32 v[6:7], v[6:7], v[22:23]
	v_pk_add_f32 v[10:11], v[10:11], v[26:27]
	v_pk_add_f32 v[8:9], v[8:9], v[24:25]
	v_pk_add_f32 v[14:15], v[14:15], v[30:31]
	v_pk_add_f32 v[12:13], v[12:13], v[28:29]
	v_pk_add_f32 v[18:19], v[18:19], v[52:53]
	v_pk_add_f32 v[16:17], v[16:17], v[50:51]
	v_pk_add_f32 v[4:5], v[4:5], v[54:55]
	v_pk_add_f32 v[6:7], v[6:7], v[56:57]
	v_pk_add_f32 v[10:11], v[10:11], v[60:61]
	v_pk_add_f32 v[8:9], v[8:9], v[58:59]
	v_pk_add_f32 v[14:15], v[14:15], v[64:65]
	v_pk_add_f32 v[12:13], v[12:13], v[62:63]
	v_pk_add_f32 v[18:19], v[18:19], v[68:69]
	v_pk_add_f32 v[16:17], v[16:17], v[66:67]
	v_pk_add_f32 v[4:5], v[4:5], v[70:71]
	v_pk_add_f32 v[6:7], v[6:7], v[72:73]
	v_pk_add_f32 v[10:11], v[10:11], v[76:77]
	v_pk_add_f32 v[8:9], v[8:9], v[74:75]
	v_pk_add_f32 v[14:15], v[14:15], v[80:81]
	v_pk_add_f32 v[12:13], v[12:13], v[78:79]
	v_pk_add_f32 v[18:19], v[18:19], v[84:85]
	v_pk_add_f32 v[16:17], v[16:17], v[82:83]
	v_pk_add_f32 v[4:5], v[4:5], v[86:87]
	v_pk_add_f32 v[6:7], v[6:7], v[88:89]
	v_pk_add_f32 v[10:11], v[10:11], v[92:93]
	v_pk_add_f32 v[8:9], v[8:9], v[90:91]
	s_waitcnt lgkmcnt(13)
	v_pk_add_f32 v[14:15], v[14:15], v[96:97]
	v_pk_add_f32 v[12:13], v[12:13], v[94:95]
	s_waitcnt lgkmcnt(12)
	v_pk_add_f32 v[18:19], v[18:19], v[100:101]
	v_pk_add_f32 v[16:17], v[16:17], v[98:99]
	s_waitcnt lgkmcnt(11)
	v_pk_add_f32 v[4:5], v[4:5], v[102:103]
	v_pk_add_f32 v[6:7], v[6:7], v[104:105]
	s_waitcnt lgkmcnt(10)
	v_pk_add_f32 v[10:11], v[10:11], v[108:109]
	v_pk_add_f32 v[8:9], v[8:9], v[106:107]
	s_waitcnt lgkmcnt(9)
	v_pk_add_f32 v[14:15], v[14:15], v[112:113]
	v_pk_add_f32 v[12:13], v[12:13], v[110:111]
	s_waitcnt lgkmcnt(8)
	v_pk_add_f32 v[18:19], v[18:19], v[116:117]
	v_pk_add_f32 v[16:17], v[16:17], v[114:115]
	s_waitcnt lgkmcnt(7)
	v_pk_add_f32 v[4:5], v[4:5], v[118:119]
	v_pk_add_f32 v[6:7], v[6:7], v[120:121]
	s_waitcnt lgkmcnt(6)
	v_pk_add_f32 v[10:11], v[10:11], v[124:125]
	v_pk_add_f32 v[8:9], v[8:9], v[122:123]
	s_waitcnt lgkmcnt(5)
	v_pk_add_f32 v[14:15], v[14:15], v[128:129]
	v_pk_add_f32 v[12:13], v[12:13], v[126:127]
	s_waitcnt lgkmcnt(4)
	v_pk_add_f32 v[18:19], v[18:19], v[132:133]
	v_pk_add_f32 v[16:17], v[16:17], v[130:131]
	s_waitcnt lgkmcnt(3)
	v_pk_add_f32 v[4:5], v[4:5], v[134:135]
	v_pk_add_f32 v[6:7], v[6:7], v[136:137]
	s_waitcnt lgkmcnt(2)
	v_pk_add_f32 v[10:11], v[10:11], v[140:141]
	v_pk_add_f32 v[8:9], v[8:9], v[138:139]
	s_waitcnt lgkmcnt(1)
	v_pk_add_f32 v[14:15], v[14:15], v[144:145]
	v_pk_add_f32 v[12:13], v[12:13], v[142:143]
	s_waitcnt lgkmcnt(0)
	v_pk_add_f32 v[18:19], v[18:19], v[148:149]
	v_pk_add_f32 v[16:17], v[16:17], v[146:147]
	s_waitcnt vmcnt(0)
	v_fmamk_f32 v3, v3, 0x3a000000, v45
	v_mul_f32_e32 v20, 0x4b800000, v3
	v_cmp_gt_f32_e32 vcc, s49, v3
	s_nop 1
	v_cndmask_b32_e32 v3, v3, v20, vcc
	v_rsq_f32_e32 v3, v3
	s_nop 0
	v_mul_f32_e32 v20, 0x45800000, v3
	v_cndmask_b32_e32 v20, v3, v20, vcc
	v_pk_mul_f32 v[4:5], v[4:5], v[20:21] op_sel_hi:[1,0]
	v_pk_mul_f32 v[12:13], v[12:13], v[20:21] op_sel_hi:[1,0]
	v_pk_mul_f32 v[8:9], v[8:9], v[20:21] op_sel_hi:[1,0]
	v_pk_mul_f32 v[16:17], v[16:17], v[20:21] op_sel_hi:[1,0]
	v_pk_mul_f32 v[6:7], v[6:7], v[20:21] op_sel_hi:[1,0]
	v_pk_mul_f32 v[14:15], v[14:15], v[20:21] op_sel_hi:[1,0]
	v_pk_mul_f32 v[10:11], v[10:11], v[20:21] op_sel_hi:[1,0]
	v_pk_mul_f32 v[18:19], v[18:19], v[20:21] op_sel_hi:[1,0]
	v_mul_f32_e32 v3, 0xbfb8aa3b, v4
	v_mul_f32_e32 v21, 0xbfb8aa3b, v5
	v_exp_f32_e32 v20, v3
	v_exp_f32_e32 v21, v21
	v_mul_f32_e32 v22, 0xbfb8aa3b, v8
	v_mul_f32_e32 v23, 0xbfb8aa3b, v9
	v_exp_f32_e32 v22, v22
	v_exp_f32_e32 v23, v23
	v_mul_f32_e32 v24, 0xbfb8aa3b, v6
	v_mul_f32_e32 v25, 0xbfb8aa3b, v7
	v_exp_f32_e32 v24, v24
	v_exp_f32_e32 v25, v25
	v_pk_add_f32 v[20:21], v[20:21], 1.0 op_sel_hi:[1,0]
	v_mul_f32_e32 v26, 0xbfb8aa3b, v10
	v_mul_f32_e32 v27, 0xbfb8aa3b, v11
	v_exp_f32_e32 v26, v26
	v_exp_f32_e32 v27, v27
	v_pk_add_f32 v[22:23], v[22:23], 1.0 op_sel_hi:[1,0]
	v_pk_add_f32 v[24:25], v[24:25], 1.0 op_sel_hi:[1,0]
	v_pk_add_f32 v[26:27], v[26:27], 1.0 op_sel_hi:[1,0]
	v_rcp_f32_e32 v3, v21
	s_nop 0
	v_mul_f32_e32 v5, v5, v3
	v_rcp_f32_e32 v3, v20
	s_nop 0
	v_mul_f32_e32 v4, v4, v3
	v_rcp_f32_e32 v3, v23
	s_nop 0
	v_mul_f32_e32 v9, v9, v3
	v_rcp_f32_e32 v3, v22
	v_pk_mul_f32 v[4:5], v[12:13], v[4:5]
	v_mul_f32_e32 v8, v8, v3
	v_rcp_f32_e32 v13, v25
	v_rcp_f32_e32 v3, v24
	v_mul_f32_e32 v13, v7, v13
	v_mul_f32_e32 v12, v6, v3
	v_pk_mul_f32 v[8:9], v[16:17], v[8:9]
	v_rcp_f32_e32 v3, v27
	v_cvt_pk_bf16_f32 v6, v8, v9
	v_mul_f32_e32 v11, v11, v3
	v_pk_mul_f32 v[8:9], v[14:15], v[12:13]
	v_rcp_f32_e32 v3, v26
	v_cvt_pk_bf16_f32 v4, v4, v5
	v_mul_f32_e32 v10, v10, v3
	v_cvt_pk_bf16_f32 v5, v8, v9
	v_pk_mul_f32 v[8:9], v[18:19], v[10:11]
	s_nop 0
	v_cvt_pk_bf16_f32 v7, v8, v9
	global_store_dwordx4 v[42:43], v[4:7], off offset:32
	s_andn2_b64 exec, exec, s[40:41]
	s_cbranch_execnz .LBB0_622
	s_branch .LBB0_616

; DI float silu(float x) { return x / (1.f + __expf(-x)); }
; DI bf16x8 pack8(const f32x4& a, const f32x4& b) { v4u w; w.x = pk2(a[0], a[1]); w.y = pk2(a[2], a[3]); w.z = pk2(b[0], b[1]); w.w = pk2(b[2], b[3]); return __builtin_bit_cast(bf16x8, w); }
;     DI void operator()(const f32x4 (&acc)[2][2][4][2], const pg8::Unit& u, int wr, int wc, int fr, int fq) const {
;     ...
;         EPI_LOOP_BEGIN
;             const float rs = rsqrtf(ssq[row] * (1.f / D) + EPS);
;             f32x4 a = acc[ai][0][m][0], b = acc[ai][0][m][1]; const f32x4 ua = acc[ai][1][m][0], ub = acc[ai][1][m][1];
; #pragma unroll
;             for (int e = 0; e < 4; ++e) { a[e] = silu(a[e] * rs) * (ua[e] * rs); b[e] = silu(b[e] * rs) * (ub[e] * rs); }
;             *(bf16x8*)(hid + (size_t)row * FF + cbase) = pack8(a, b);
;         EPI_LOOP_END
.LBB0_690:
	v_lshl_add_u32 v144, s6, 8, v150
	v_ashrrev_i32_e32 v145, 31, v144
	v_lshl_add_u64 v[146:147], v[144:145], 2, s[40:41]
	global_load_dword v145, v[146:147], off
	s_waitcnt vmcnt(0)
	v_fmamk_f32 v145, v145, 0x3a000000, v156
	v_mul_f32_e32 v146, 0x4b800000, v145
	v_cmp_gt_f32_e32 vcc, s63, v145
	s_nop 1
	v_cndmask_b32_e32 v145, v145, v146, vcc
	v_rsq_f32_e32 v145, v145
	v_lshl_add_u32 v146, s7, 7, v152
	v_ashrrev_i32_e32 v147, 31, v146
	v_mul_f32_e32 v148, 0x45800000, v145
	v_cndmask_b32_e32 v148, v145, v148, vcc
	v_pk_mul_f32 v[124:125], v[124:125], v[148:149] op_sel_hi:[1,0]
	v_pk_mul_f32 v[120:121], v[120:121], v[148:149] op_sel_hi:[1,0]
	v_mul_f32_e32 v145, 0xbfb8aa3b, v124
	v_mul_f32_e32 v157, 0xbfb8aa3b, v125
	v_exp_f32_e32 v158, v145
	v_exp_f32_e32 v159, v157
	v_mul_f32_e32 v160, 0xbfb8aa3b, v120
	v_mul_f32_e32 v161, 0xbfb8aa3b, v121
	v_exp_f32_e32 v160, v160
	v_exp_f32_e32 v161, v161
	v_pk_mul_f32 v[126:127], v[126:127], v[148:149] op_sel_hi:[1,0]
	v_pk_add_f32 v[158:159], v[158:159], 1.0 op_sel_hi:[1,0]
	v_mul_f32_e32 v162, 0xbfb8aa3b, v126
	v_mul_f32_e32 v163, 0xbfb8aa3b, v127
	v_exp_f32_e32 v162, v162
	v_exp_f32_e32 v163, v163
	v_pk_add_f32 v[160:161], v[160:161], 1.0 op_sel_hi:[1,0]
	v_pk_add_f32 v[162:163], v[162:163], 1.0 op_sel_hi:[1,0]
	v_rcp_f32_e32 v145, v159
	v_pk_mul_f32 v[116:117], v[116:117], v[148:149] op_sel_hi:[1,0]
	v_mul_f32_e32 v125, v125, v145
	v_rcp_f32_e32 v145, v158
	s_nop 0
	v_mul_f32_e32 v124, v124, v145
	v_pk_mul_f32 v[116:117], v[116:117], v[124:125]
	v_pk_mul_f32 v[112:113], v[112:113], v[148:149] op_sel_hi:[1,0]
	v_pk_mul_f32 v[122:123], v[122:123], v[148:149] op_sel_hi:[1,0]
	v_rcp_f32_e32 v145, v161
	v_rcp_f32_e32 v124, v160
	v_mul_f32_e32 v121, v121, v145
	v_mul_f32_e32 v120, v120, v124
	v_pk_mul_f32 v[112:113], v[112:113], v[120:121]
	v_mul_f32_e32 v120, 0xbfb8aa3b, v122
	v_rcp_f32_e32 v121, v163
	v_exp_f32_e32 v124, v120
	v_mul_f32_e32 v121, v127, v121
	v_mul_f32_e32 v120, 0xbfb8aa3b, v123
	v_exp_f32_e32 v125, v120
	s_nop 0
	v_pk_add_f32 v[124:125], v[124:125], 1.0 op_sel_hi:[1,0]
	v_rcp_f32_e32 v120, v162
	v_pk_mul_f32 v[118:119], v[118:119], v[148:149] op_sel_hi:[1,0]
	v_mul_f32_e32 v120, v126, v120
	v_pk_mul_f32 v[114:115], v[114:115], v[148:149] op_sel_hi:[1,0]
	v_pk_mul_f32 v[118:119], v[118:119], v[120:121]
	v_rcp_f32_e32 v120, v125
	v_cvt_pk_bf16_f32 v116, v116, v117
	v_mul_f32_e32 v121, v123, v120
	v_rcp_f32_e32 v120, v124
	s_nop 0
	v_mul_f32_e32 v120, v122, v120
	v_pk_mul_f32 v[114:115], v[114:115], v[120:121]
	v_cvt_pk_bf16_f32 v117, v118, v119
	v_cvt_pk_bf16_f32 v118, v112, v113
	v_mov_b64_e32 v[112:113], s[38:39]
	v_cvt_pk_bf16_f32 v119, v114, v115
	v_mad_i64_i32 v[120:121], s[6:7], v144, s64, v[112:113]
	v_lshlrev_b64 v[114:115], 1, v[146:147]
	v_lshl_add_u64 v[120:121], v[120:121], 0, v[114:115]
	global_store_dwordx4 v[120:121], v[116:119], off
	s_nop 1
	v_or_b32_e32 v116, 16, v144
	v_ashrrev_i32_e32 v117, 31, v116
	v_lshl_add_u64 v[118:119], v[116:117], 2, s[40:41]
	global_load_dword v117, v[118:119], off
	s_waitcnt vmcnt(0)
	v_fmamk_f32 v117, v117, 0x3a000000, v156
	v_mul_f32_e32 v118, 0x4b800000, v117
	v_cmp_gt_f32_e32 vcc, s63, v117
	s_nop 1
	v_cndmask_b32_e32 v117, v117, v118, vcc
	v_rsq_f32_e32 v117, v117
	s_nop 0
	v_mul_f32_e32 v118, 0x45800000, v117
	v_cndmask_b32_e32 v118, v117, v118, vcc
	v_pk_mul_f32 v[108:109], v[108:109], v[118:119] op_sel_hi:[1,0]
	v_pk_mul_f32 v[104:105], v[104:105], v[118:119] op_sel_hi:[1,0]
	v_mul_f32_e32 v117, 0xbfb8aa3b, v108
	v_mul_f32_e32 v119, 0xbfb8aa3b, v109
	v_exp_f32_e32 v120, v117
	v_exp_f32_e32 v121, v119
	v_mul_f32_e32 v122, 0xbfb8aa3b, v104
	v_mul_f32_e32 v123, 0xbfb8aa3b, v105
	v_exp_f32_e32 v122, v122
	v_pk_add_f32 v[120:121], v[120:121], 1.0 op_sel_hi:[1,0]
	v_exp_f32_e32 v123, v123
	s_nop 0
	v_pk_add_f32 v[122:123], v[122:123], 1.0 op_sel_hi:[1,0]
	v_pk_mul_f32 v[100:101], v[100:101], v[118:119] op_sel_hi:[1,0]
	v_rcp_f32_e32 v117, v121
	s_nop 0
	v_mul_f32_e32 v109, v109, v117
	v_rcp_f32_e32 v117, v120
	s_nop 0
	v_mul_f32_e32 v108, v108, v117
	v_pk_mul_f32 v[100:101], v[100:101], v[108:109]
	v_rcp_f32_e32 v108, v123
	s_nop 0
	v_mul_f32_e32 v105, v105, v108
	v_pk_mul_f32 v[108:109], v[110:111], v[118:119] op_sel_hi:[1,0]
	v_mul_f32_e32 v110, 0xbfb8aa3b, v108
	v_mul_f32_e32 v111, 0xbfb8aa3b, v109
	v_exp_f32_e32 v110, v110
	v_exp_f32_e32 v111, v111
	v_rcp_f32_e32 v117, v122
	v_pk_add_f32 v[110:111], v[110:111], 1.0 op_sel_hi:[1,0]
	v_mul_f32_e32 v104, v104, v117
	s_nop 0
	v_pk_mul_f32 v[96:97], v[96:97], v[118:119] op_sel_hi:[1,0]
	s_nop 0
	v_pk_mul_f32 v[104:105], v[96:97], v[104:105]
	v_rcp_f32_e32 v96, v111
	v_pk_mul_f32 v[106:107], v[106:107], v[118:119] op_sel_hi:[1,0]
	v_mul_f32_e32 v97, v109, v96
	v_mul_f32_e32 v111, 0xbfb8aa3b, v106
	v_exp_f32_e32 v120, v111
	v_mul_f32_e32 v111, 0xbfb8aa3b, v107
	v_exp_f32_e32 v121, v111
	v_rcp_f32_e32 v96, v110
	v_pk_add_f32 v[120:121], v[120:121], 1.0 op_sel_hi:[1,0]
	v_mul_f32_e32 v96, v108, v96
	v_pk_mul_f32 v[102:103], v[102:103], v[118:119] op_sel_hi:[1,0]
	v_pk_mul_f32 v[102:103], v[102:103], v[96:97]
	v_pk_mul_f32 v[98:99], v[98:99], v[118:119] op_sel_hi:[1,0]
	v_rcp_f32_e32 v97, v121
	v_rcp_f32_e32 v96, v120
	v_mul_f32_e32 v97, v107, v97
	v_mul_f32_e32 v96, v106, v96
	v_pk_mul_f32 v[106:107], v[98:99], v[96:97]
	v_cvt_pk_bf16_f32 v96, v100, v101
	v_mad_i64_i32 v[100:101], s[6:7], v116, s64, v[112:113]
	v_cvt_pk_bf16_f32 v97, v102, v103
	v_cvt_pk_bf16_f32 v98, v104, v105
	v_cvt_pk_bf16_f32 v99, v106, v107
	v_lshl_add_u64 v[100:101], v[100:101], 0, v[114:115]
	global_store_dwordx4 v[100:101], v[96:99], off
	s_nop 1
	v_or_b32_e32 v96, 32, v144
	v_ashrrev_i32_e32 v97, 31, v96
	v_lshl_add_u64 v[98:99], v[96:97], 2, s[40:41]
	global_load_dword v97, v[98:99], off
	s_waitcnt vmcnt(0)
; DI float silu(float x) { return x / (1.f + __expf(-x)); }
; DI bf16x8 pack8(const f32x4& a, const f32x4& b) { v4u w; w.x = pk2(a[0], a[1]); w.y = pk2(a[2], a[3]); w.z = pk2(b[0], b[1]); w.w = pk2(b[2], b[3]); return __builtin_bit_cast(bf16x8, w); }
;     DI void operator()(const f32x4 (&acc)[2][2][4][2], const pg8::Unit& u, int wr, int wc, int fr, int fq) const {
;     ...
;         EPI_LOOP_BEGIN
;             const float rs = rsqrtf(ssq[row] * (1.f / D) + EPS);
;             f32x4 a = acc[ai][0][m][0], b = acc[ai][0][m][1]; const f32x4 ua = acc[ai][1][m][0], ub = acc[ai][1][m][1];
; #pragma unroll
;             for (int e = 0; e < 4; ++e) { a[e] = silu(a[e] * rs) * (ua[e] * rs); b[e] = silu(b[e] * rs) * (ub[e] * rs); }
;             *(bf16x8*)(hid + (size_t)row * FF + cbase) = pack8(a, b);
;         EPI_LOOP_END
	v_fmamk_f32 v97, v97, 0x3a000000, v156
	v_mul_f32_e32 v98, 0x4b800000, v97
	v_cmp_gt_f32_e32 vcc, s63, v97
	s_nop 1
	v_cndmask_b32_e32 v97, v97, v98, vcc
	v_rsq_f32_e32 v97, v97
	s_nop 0
	v_mul_f32_e32 v98, 0x45800000, v97
	v_cndmask_b32_e32 v98, v97, v98, vcc
	v_pk_mul_f32 v[92:93], v[92:93], v[98:99] op_sel_hi:[1,0]
	s_nop 0
	v_mul_f32_e32 v97, 0xbfb8aa3b, v92
	v_exp_f32_e32 v100, v97
	v_mul_f32_e32 v97, 0xbfb8aa3b, v93
	v_exp_f32_e32 v101, v97
	s_nop 0
	v_pk_add_f32 v[100:101], v[100:101], 1.0 op_sel_hi:[1,0]
	s_nop 0
	s_nop 0
	v_rcp_f32_e32 v97, v101
	v_pk_mul_f32 v[88:89], v[88:89], v[98:99] op_sel_hi:[1,0]
	v_mul_f32_e32 v93, v93, v97
	v_mul_f32_e32 v101, 0xbfb8aa3b, v88
	v_exp_f32_e32 v102, v101
	v_mul_f32_e32 v101, 0xbfb8aa3b, v89
	v_exp_f32_e32 v103, v101
	v_rcp_f32_e32 v97, v100
	v_pk_add_f32 v[102:103], v[102:103], 1.0 op_sel_hi:[1,0]
	v_mul_f32_e32 v92, v92, v97
	s_nop 0
	v_pk_mul_f32 v[84:85], v[84:85], v[98:99] op_sel_hi:[1,0]
	s_nop 0
	v_pk_mul_f32 v[84:85], v[84:85], v[92:93]
	v_rcp_f32_e32 v92, v103
	s_nop 0
	v_mul_f32_e32 v89, v89, v92
	v_pk_mul_f32 v[92:93], v[94:95], v[98:99] op_sel_hi:[1,0]
	v_mul_f32_e32 v94, 0xbfb8aa3b, v92
	v_mul_f32_e32 v95, 0xbfb8aa3b, v93
	v_exp_f32_e32 v94, v94
	v_exp_f32_e32 v95, v95
	v_rcp_f32_e32 v97, v102
	v_pk_add_f32 v[94:95], v[94:95], 1.0 op_sel_hi:[1,0]
	v_mul_f32_e32 v88, v88, v97
	s_nop 0
	v_pk_mul_f32 v[80:81], v[80:81], v[98:99] op_sel_hi:[1,0]
	s_nop 0
	v_pk_mul_f32 v[88:89], v[80:81], v[88:89]
	v_rcp_f32_e32 v80, v95
	v_pk_mul_f32 v[90:91], v[90:91], v[98:99] op_sel_hi:[1,0]
	v_mul_f32_e32 v81, v93, v80
	v_mul_f32_e32 v95, 0xbfb8aa3b, v90
	v_exp_f32_e32 v100, v95
	v_mul_f32_e32 v95, 0xbfb8aa3b, v91
	v_exp_f32_e32 v101, v95
	v_rcp_f32_e32 v80, v94
	v_pk_add_f32 v[100:101], v[100:101], 1.0 op_sel_hi:[1,0]
	v_mul_f32_e32 v80, v92, v80
	v_pk_mul_f32 v[86:87], v[86:87], v[98:99] op_sel_hi:[1,0]
	v_pk_mul_f32 v[86:87], v[86:87], v[80:81]
	v_pk_mul_f32 v[82:83], v[82:83], v[98:99] op_sel_hi:[1,0]
	v_rcp_f32_e32 v81, v101
	v_rcp_f32_e32 v80, v100
	v_mul_f32_e32 v81, v91, v81
	v_mul_f32_e32 v80, v90, v80
	v_pk_mul_f32 v[90:91], v[82:83], v[80:81]
	v_cvt_pk_bf16_f32 v80, v84, v85
	v_mad_i64_i32 v[84:85], s[6:7], v96, s64, v[112:113]
	v_cvt_pk_bf16_f32 v81, v86, v87
	v_cvt_pk_bf16_f32 v82, v88, v89
	v_cvt_pk_bf16_f32 v83, v90, v91
	v_lshl_add_u64 v[84:85], v[84:85], 0, v[114:115]
	global_store_dwordx4 v[84:85], v[80:83], off
	s_nop 1
	v_or_b32_e32 v80, 48, v144
	v_ashrrev_i32_e32 v81, 31, v80
	v_lshl_add_u64 v[82:83], v[80:81], 2, s[40:41]
	global_load_dword v81, v[82:83], off
	s_waitcnt vmcnt(0)
	v_fmamk_f32 v81, v81, 0x3a000000, v156
	v_mul_f32_e32 v82, 0x4b800000, v81
	v_cmp_gt_f32_e32 vcc, s63, v81
	s_nop 1
	v_cndmask_b32_e32 v81, v81, v82, vcc
	v_rsq_f32_e32 v81, v81
	s_nop 0
	v_mul_f32_e32 v82, 0x45800000, v81
	v_cndmask_b32_e32 v82, v81, v82, vcc
	v_pk_mul_f32 v[76:77], v[76:77], v[82:83] op_sel_hi:[1,0]
	s_nop 0
	v_mul_f32_e32 v81, 0xbfb8aa3b, v76
	v_exp_f32_e32 v84, v81
	v_mul_f32_e32 v81, 0xbfb8aa3b, v77
	v_exp_f32_e32 v85, v81
	s_nop 0
	v_pk_add_f32 v[84:85], v[84:85], 1.0 op_sel_hi:[1,0]
	s_nop 0
	s_nop 0
	v_rcp_f32_e32 v81, v85
	v_pk_mul_f32 v[72:73], v[72:73], v[82:83] op_sel_hi:[1,0]
	v_mul_f32_e32 v77, v77, v81
	v_mul_f32_e32 v85, 0xbfb8aa3b, v72
	v_exp_f32_e32 v86, v85
	v_mul_f32_e32 v85, 0xbfb8aa3b, v73
	v_exp_f32_e32 v87, v85
	v_rcp_f32_e32 v81, v84
	v_pk_add_f32 v[86:87], v[86:87], 1.0 op_sel_hi:[1,0]
	v_mul_f32_e32 v76, v76, v81
	s_nop 0
	v_pk_mul_f32 v[68:69], v[68:69], v[82:83] op_sel_hi:[1,0]
	s_nop 0
	v_pk_mul_f32 v[68:69], v[68:69], v[76:77]
	v_rcp_f32_e32 v76, v87
	s_nop 0
	v_mul_f32_e32 v73, v73, v76
	v_pk_mul_f32 v[76:77], v[78:79], v[82:83] op_sel_hi:[1,0]
	v_mul_f32_e32 v78, 0xbfb8aa3b, v76
	v_mul_f32_e32 v79, 0xbfb8aa3b, v77
	v_exp_f32_e32 v78, v78
	v_exp_f32_e32 v79, v79
	v_rcp_f32_e32 v81, v86
	v_pk_add_f32 v[78:79], v[78:79], 1.0 op_sel_hi:[1,0]
	v_mul_f32_e32 v72, v72, v81
	s_nop 0
	v_pk_mul_f32 v[64:65], v[64:65], v[82:83] op_sel_hi:[1,0]
	s_nop 0
	v_pk_mul_f32 v[72:73], v[64:65], v[72:73]
	v_rcp_f32_e32 v64, v79
	v_pk_mul_f32 v[74:75], v[74:75], v[82:83] op_sel_hi:[1,0]
	v_mul_f32_e32 v65, v77, v64
	v_mul_f32_e32 v79, 0xbfb8aa3b, v74
	v_exp_f32_e32 v84, v79
	v_mul_f32_e32 v79, 0xbfb8aa3b, v75
	v_exp_f32_e32 v85, v79
	v_rcp_f32_e32 v64, v78
	v_pk_add_f32 v[84:85], v[84:85], 1.0 op_sel_hi:[1,0]
	v_mul_f32_e32 v64, v76, v64
	v_pk_mul_f32 v[70:71], v[70:71], v[82:83] op_sel_hi:[1,0]
	v_pk_mul_f32 v[70:71], v[70:71], v[64:65]
	v_pk_mul_f32 v[66:67], v[66:67], v[82:83] op_sel_hi:[1,0]
	v_rcp_f32_e32 v65, v85
	v_rcp_f32_e32 v64, v84
	v_mul_f32_e32 v65, v75, v65
	v_mul_f32_e32 v64, v74, v64
	v_pk_mul_f32 v[74:75], v[66:67], v[64:65]
	v_cvt_pk_bf16_f32 v64, v68, v69
	v_mad_i64_i32 v[68:69], s[6:7], v80, s64, v[112:113]
	v_cvt_pk_bf16_f32 v65, v70, v71
	v_cvt_pk_bf16_f32 v66, v72, v73
	v_cvt_pk_bf16_f32 v67, v74, v75
	v_lshl_add_u64 v[68:69], v[68:69], 0, v[114:115]
	global_store_dwordx4 v[68:69], v[64:67], off
	s_nop 1
	v_add_u32_e32 v64, 0x80, v144
	v_ashrrev_i32_e32 v65, 31, v64
	v_lshl_add_u64 v[66:67], v[64:65], 2, s[40:41]
	global_load_dword v65, v[66:67], off
	s_waitcnt vmcnt(0)
; DI float silu(float x) { return x / (1.f + __expf(-x)); }
; DI bf16x8 pack8(const f32x4& a, const f32x4& b) { v4u w; w.x = pk2(a[0], a[1]); w.y = pk2(a[2], a[3]); w.z = pk2(b[0], b[1]); w.w = pk2(b[2], b[3]); return __builtin_bit_cast(bf16x8, w); }
;     DI void operator()(const f32x4 (&acc)[2][2][4][2], const pg8::Unit& u, int wr, int wc, int fr, int fq) const {
;     ...
;         EPI_LOOP_BEGIN
;             const float rs = rsqrtf(ssq[row] * (1.f / D) + EPS);
;             f32x4 a = acc[ai][0][m][0], b = acc[ai][0][m][1]; const f32x4 ua = acc[ai][1][m][0], ub = acc[ai][1][m][1];
; #pragma unroll
;             for (int e = 0; e < 4; ++e) { a[e] = silu(a[e] * rs) * (ua[e] * rs); b[e] = silu(b[e] * rs) * (ub[e] * rs); }
;             *(bf16x8*)(hid + (size_t)row * FF + cbase) = pack8(a, b);
;         EPI_LOOP_END
	v_fmamk_f32 v65, v65, 0x3a000000, v156
	v_mul_f32_e32 v66, 0x4b800000, v65
	v_cmp_gt_f32_e32 vcc, s63, v65
	s_nop 1
	v_cndmask_b32_e32 v65, v65, v66, vcc
	v_rsq_f32_e32 v65, v65
	s_nop 0
	v_mul_f32_e32 v66, 0x45800000, v65
	v_cndmask_b32_e32 v66, v65, v66, vcc
	v_pk_mul_f32 v[60:61], v[60:61], v[66:67] op_sel_hi:[1,0]
	s_nop 0
	v_mul_f32_e32 v65, 0xbfb8aa3b, v60
	v_exp_f32_e32 v68, v65
	v_mul_f32_e32 v65, 0xbfb8aa3b, v61
	v_exp_f32_e32 v69, v65
	s_nop 0
	v_pk_add_f32 v[68:69], v[68:69], 1.0 op_sel_hi:[1,0]
	s_nop 0
	s_nop 0
	v_rcp_f32_e32 v65, v69
	v_pk_mul_f32 v[56:57], v[56:57], v[66:67] op_sel_hi:[1,0]
	v_mul_f32_e32 v61, v61, v65
	v_mul_f32_e32 v69, 0xbfb8aa3b, v56
	v_exp_f32_e32 v70, v69
	v_mul_f32_e32 v69, 0xbfb8aa3b, v57
	v_exp_f32_e32 v71, v69
	v_rcp_f32_e32 v65, v68
	v_pk_add_f32 v[70:71], v[70:71], 1.0 op_sel_hi:[1,0]
	v_mul_f32_e32 v60, v60, v65
	s_nop 0
	v_pk_mul_f32 v[52:53], v[52:53], v[66:67] op_sel_hi:[1,0]
	s_nop 0
	v_pk_mul_f32 v[52:53], v[52:53], v[60:61]
	v_rcp_f32_e32 v60, v71
	s_nop 0
	v_mul_f32_e32 v57, v57, v60
	v_pk_mul_f32 v[60:61], v[62:63], v[66:67] op_sel_hi:[1,0]
	v_mul_f32_e32 v62, 0xbfb8aa3b, v60
	v_mul_f32_e32 v63, 0xbfb8aa3b, v61
	v_exp_f32_e32 v62, v62
	v_exp_f32_e32 v63, v63
	v_rcp_f32_e32 v65, v70
	v_pk_add_f32 v[62:63], v[62:63], 1.0 op_sel_hi:[1,0]
	v_mul_f32_e32 v56, v56, v65
	s_nop 0
	v_pk_mul_f32 v[48:49], v[48:49], v[66:67] op_sel_hi:[1,0]
	s_nop 0
	v_pk_mul_f32 v[56:57], v[48:49], v[56:57]
	v_rcp_f32_e32 v48, v63
	v_pk_mul_f32 v[58:59], v[58:59], v[66:67] op_sel_hi:[1,0]
	v_mul_f32_e32 v49, v61, v48
	v_mul_f32_e32 v63, 0xbfb8aa3b, v58
	v_exp_f32_e32 v68, v63
	v_mul_f32_e32 v63, 0xbfb8aa3b, v59
	v_exp_f32_e32 v69, v63
	v_rcp_f32_e32 v48, v62
	v_pk_add_f32 v[68:69], v[68:69], 1.0 op_sel_hi:[1,0]
	v_mul_f32_e32 v48, v60, v48
	v_pk_mul_f32 v[54:55], v[54:55], v[66:67] op_sel_hi:[1,0]
	v_pk_mul_f32 v[54:55], v[54:55], v[48:49]
	v_pk_mul_f32 v[50:51], v[50:51], v[66:67] op_sel_hi:[1,0]
	v_rcp_f32_e32 v49, v69
	v_rcp_f32_e32 v48, v68
	v_mul_f32_e32 v49, v59, v49
	v_mul_f32_e32 v48, v58, v48
	v_pk_mul_f32 v[58:59], v[50:51], v[48:49]
	v_cvt_pk_bf16_f32 v48, v52, v53
	v_mad_i64_i32 v[52:53], s[6:7], v64, s64, v[112:113]
	v_cvt_pk_bf16_f32 v49, v54, v55
	v_cvt_pk_bf16_f32 v50, v56, v57
	v_cvt_pk_bf16_f32 v51, v58, v59
	v_lshl_add_u64 v[52:53], v[52:53], 0, v[114:115]
	global_store_dwordx4 v[52:53], v[48:51], off
	s_nop 1
	v_add_u32_e32 v48, 0x90, v144
	v_ashrrev_i32_e32 v49, 31, v48
	v_lshl_add_u64 v[50:51], v[48:49], 2, s[40:41]
	global_load_dword v49, v[50:51], off
	s_waitcnt vmcnt(0)
	v_fmamk_f32 v49, v49, 0x3a000000, v156
	v_mul_f32_e32 v50, 0x4b800000, v49
	v_cmp_gt_f32_e32 vcc, s63, v49
	s_nop 1
	v_cndmask_b32_e32 v49, v49, v50, vcc
	v_rsq_f32_e32 v49, v49
	s_nop 0
	v_mul_f32_e32 v50, 0x45800000, v49
	v_cndmask_b32_e32 v50, v49, v50, vcc
	v_pk_mul_f32 v[44:45], v[44:45], v[50:51] op_sel_hi:[1,0]
	s_nop 0
	v_mul_f32_e32 v49, 0xbfb8aa3b, v44
	v_exp_f32_e32 v52, v49
	v_mul_f32_e32 v49, 0xbfb8aa3b, v45
	v_exp_f32_e32 v53, v49
	s_nop 0
	v_pk_add_f32 v[52:53], v[52:53], 1.0 op_sel_hi:[1,0]
	s_nop 0
	s_nop 0
	v_rcp_f32_e32 v49, v53
	v_pk_mul_f32 v[40:41], v[40:41], v[50:51] op_sel_hi:[1,0]
	v_mul_f32_e32 v45, v45, v49
	v_mul_f32_e32 v53, 0xbfb8aa3b, v40
	v_exp_f32_e32 v54, v53
	v_mul_f32_e32 v53, 0xbfb8aa3b, v41
	v_exp_f32_e32 v55, v53
	v_rcp_f32_e32 v49, v52
	v_pk_add_f32 v[54:55], v[54:55], 1.0 op_sel_hi:[1,0]
	v_mul_f32_e32 v44, v44, v49
	s_nop 0
	v_pk_mul_f32 v[36:37], v[36:37], v[50:51] op_sel_hi:[1,0]
	s_nop 0
	v_pk_mul_f32 v[36:37], v[36:37], v[44:45]
	v_rcp_f32_e32 v44, v55
	s_nop 0
	v_mul_f32_e32 v41, v41, v44
	v_pk_mul_f32 v[44:45], v[46:47], v[50:51] op_sel_hi:[1,0]
	v_mul_f32_e32 v46, 0xbfb8aa3b, v44
	v_mul_f32_e32 v47, 0xbfb8aa3b, v45
	v_exp_f32_e32 v46, v46
	v_exp_f32_e32 v47, v47
	v_rcp_f32_e32 v49, v54
	v_pk_add_f32 v[46:47], v[46:47], 1.0 op_sel_hi:[1,0]
	v_mul_f32_e32 v40, v40, v49
	s_nop 0
	v_pk_mul_f32 v[32:33], v[32:33], v[50:51] op_sel_hi:[1,0]
	s_nop 0
	v_pk_mul_f32 v[40:41], v[32:33], v[40:41]
	v_rcp_f32_e32 v32, v47
	v_pk_mul_f32 v[42:43], v[42:43], v[50:51] op_sel_hi:[1,0]
	v_mul_f32_e32 v33, v45, v32
	v_mul_f32_e32 v47, 0xbfb8aa3b, v42
	v_exp_f32_e32 v52, v47
	v_mul_f32_e32 v47, 0xbfb8aa3b, v43
	v_exp_f32_e32 v53, v47
	v_rcp_f32_e32 v32, v46
	v_pk_add_f32 v[52:53], v[52:53], 1.0 op_sel_hi:[1,0]
	v_mul_f32_e32 v32, v44, v32
	v_pk_mul_f32 v[38:39], v[38:39], v[50:51] op_sel_hi:[1,0]
	v_pk_mul_f32 v[38:39], v[38:39], v[32:33]
	v_pk_mul_f32 v[34:35], v[34:35], v[50:51] op_sel_hi:[1,0]
	v_rcp_f32_e32 v33, v53
	v_rcp_f32_e32 v32, v52
	v_mul_f32_e32 v33, v43, v33
	v_mul_f32_e32 v32, v42, v32
	v_pk_mul_f32 v[42:43], v[34:35], v[32:33]
	v_cvt_pk_bf16_f32 v32, v36, v37
	v_mad_i64_i32 v[36:37], s[6:7], v48, s64, v[112:113]
	v_cvt_pk_bf16_f32 v33, v38, v39
	v_cvt_pk_bf16_f32 v34, v40, v41
	v_cvt_pk_bf16_f32 v35, v42, v43
	v_lshl_add_u64 v[36:37], v[36:37], 0, v[114:115]
	global_store_dwordx4 v[36:37], v[32:35], off
	s_nop 1
	v_add_u32_e32 v32, 0xa0, v144
	v_ashrrev_i32_e32 v33, 31, v32
	v_lshl_add_u64 v[34:35], v[32:33], 2, s[40:41]
	global_load_dword v33, v[34:35], off
	s_waitcnt vmcnt(0)
; #define PG8_BAR __builtin_amdgcn_s_barrier()
; DI float silu(float x) { return x / (1.f + __expf(-x)); }
; DI bf16x8 pack8(const f32x4& a, const f32x4& b) { v4u w; w.x = pk2(a[0], a[1]); w.y = pk2(a[2], a[3]); w.z = pk2(b[0], b[1]); w.w = pk2(b[2], b[3]); return __builtin_bit_cast(bf16x8, w); }
; template <class Epi, class Sched, bool ALIGN_EPI = false, bool SP2 = false>
; __device__ __forceinline__ void gemm_phase(PG8_LAS unsigned char* lds, const Gemm g, const Sched& S, const Epi& E, const int wid  ) {
;     ...
;         if constexpr (ALIGN_EPI) { if (wr == 0) PG8_BAR; }
;         if constexpr (!Epi::AFTER_DRAIN) { E(acc, cur, wr, wc, fr, fq); S.done(cur); }
;         if (!has_next) break;
; #pragma unroll
;         for (int a = 0; a < 2; ++a)
; #pragma unroll
;             for (int b = 0; b < 2; ++b)
; #pragma unroll
;                 for (int m = 0; m < 4; ++m)
; #pragma unroll
;                     for (int n = 0; n < 2; ++n) acc[a][b][m][n] = (f32x4){0.f, 0.f, 0.f, 0.f};
;         cur = nxt; cA = nA; cB = nB; ++ui;
;         if constexpr (ALIGN_EPI) { if (wr == 1) PG8_BAR; }
;     DI void operator()(const f32x4 (&acc)[2][2][4][2], const pg8::Unit& u, int wr, int wc, int fr, int fq) const {
;     ...
;         EPI_LOOP_BEGIN
;             const float rs = rsqrtf(ssq[row] * (1.f / D) + EPS);
;             f32x4 a = acc[ai][0][m][0], b = acc[ai][0][m][1]; const f32x4 ua = acc[ai][1][m][0], ub = acc[ai][1][m][1];
; #pragma unroll
;             for (int e = 0; e < 4; ++e) { a[e] = silu(a[e] * rs) * (ua[e] * rs); b[e] = silu(b[e] * rs) * (ub[e] * rs); }
;             *(bf16x8*)(hid + (size_t)row * FF + cbase) = pack8(a, b);
;         EPI_LOOP_END
	v_fmamk_f32 v33, v33, 0x3a000000, v156
	v_mul_f32_e32 v34, 0x4b800000, v33
	v_cmp_gt_f32_e32 vcc, s63, v33
	s_nop 1
	v_cndmask_b32_e32 v33, v33, v34, vcc
	v_rsq_f32_e32 v33, v33
	s_nop 0
	v_mul_f32_e32 v34, 0x45800000, v33
	v_cndmask_b32_e32 v34, v33, v34, vcc
	v_pk_mul_f32 v[28:29], v[28:29], v[34:35] op_sel_hi:[1,0]
	s_nop 0
	v_mul_f32_e32 v33, 0xbfb8aa3b, v28
	v_exp_f32_e32 v36, v33
	v_mul_f32_e32 v33, 0xbfb8aa3b, v29
	v_exp_f32_e32 v37, v33
	s_nop 0
	v_pk_add_f32 v[36:37], v[36:37], 1.0 op_sel_hi:[1,0]
	s_nop 0
	s_nop 0
	v_rcp_f32_e32 v33, v37
	v_pk_mul_f32 v[24:25], v[24:25], v[34:35] op_sel_hi:[1,0]
	v_mul_f32_e32 v29, v29, v33
	v_mul_f32_e32 v37, 0xbfb8aa3b, v24
	v_exp_f32_e32 v38, v37
	v_mul_f32_e32 v37, 0xbfb8aa3b, v25
	v_exp_f32_e32 v39, v37
	v_rcp_f32_e32 v33, v36
	v_pk_add_f32 v[38:39], v[38:39], 1.0 op_sel_hi:[1,0]
	v_mul_f32_e32 v28, v28, v33
	s_nop 0
	v_pk_mul_f32 v[20:21], v[20:21], v[34:35] op_sel_hi:[1,0]
	s_nop 0
	v_pk_mul_f32 v[20:21], v[20:21], v[28:29]
	v_rcp_f32_e32 v28, v39
	s_nop 0
	v_mul_f32_e32 v25, v25, v28
	v_pk_mul_f32 v[28:29], v[30:31], v[34:35] op_sel_hi:[1,0]
	v_mul_f32_e32 v30, 0xbfb8aa3b, v28
	v_mul_f32_e32 v31, 0xbfb8aa3b, v29
	v_exp_f32_e32 v30, v30
	v_exp_f32_e32 v31, v31
	v_rcp_f32_e32 v33, v38
	v_pk_add_f32 v[30:31], v[30:31], 1.0 op_sel_hi:[1,0]
	v_mul_f32_e32 v24, v24, v33
	s_nop 0
	v_pk_mul_f32 v[16:17], v[16:17], v[34:35] op_sel_hi:[1,0]
	s_nop 0
	v_pk_mul_f32 v[24:25], v[16:17], v[24:25]
	v_rcp_f32_e32 v16, v31
	v_pk_mul_f32 v[26:27], v[26:27], v[34:35] op_sel_hi:[1,0]
	v_mul_f32_e32 v17, v29, v16
	v_mul_f32_e32 v31, 0xbfb8aa3b, v26
	v_exp_f32_e32 v36, v31
	v_mul_f32_e32 v31, 0xbfb8aa3b, v27
	v_exp_f32_e32 v37, v31
	v_rcp_f32_e32 v16, v30
	v_pk_add_f32 v[36:37], v[36:37], 1.0 op_sel_hi:[1,0]
	v_mul_f32_e32 v16, v28, v16
	v_pk_mul_f32 v[22:23], v[22:23], v[34:35] op_sel_hi:[1,0]
	v_pk_mul_f32 v[22:23], v[22:23], v[16:17]
	v_pk_mul_f32 v[18:19], v[18:19], v[34:35] op_sel_hi:[1,0]
	v_rcp_f32_e32 v17, v37
	v_rcp_f32_e32 v16, v36
	v_mul_f32_e32 v17, v27, v17
	v_mul_f32_e32 v16, v26, v16
	v_pk_mul_f32 v[26:27], v[18:19], v[16:17]
	v_cvt_pk_bf16_f32 v16, v20, v21
	v_mad_i64_i32 v[20:21], s[6:7], v32, s64, v[112:113]
	v_cvt_pk_bf16_f32 v17, v22, v23
	v_cvt_pk_bf16_f32 v18, v24, v25
	v_cvt_pk_bf16_f32 v19, v26, v27
	v_lshl_add_u64 v[20:21], v[20:21], 0, v[114:115]
	global_store_dwordx4 v[20:21], v[16:19], off
	s_nop 1
	v_add_u32_e32 v16, 0xb0, v144
	v_ashrrev_i32_e32 v17, 31, v16
	v_lshl_add_u64 v[18:19], v[16:17], 2, s[40:41]
	global_load_dword v17, v[18:19], off
	s_waitcnt vmcnt(0)
	v_fmamk_f32 v17, v17, 0x3a000000, v156
	v_mul_f32_e32 v18, 0x4b800000, v17
	v_cmp_gt_f32_e32 vcc, s63, v17
	s_nop 1
	v_cndmask_b32_e32 v17, v17, v18, vcc
	v_rsq_f32_e32 v17, v17
	s_nop 0
	v_mul_f32_e32 v18, 0x45800000, v17
	v_cndmask_b32_e32 v18, v17, v18, vcc
	v_pk_mul_f32 v[12:13], v[12:13], v[18:19] op_sel_hi:[1,0]
	s_nop 0
	v_mul_f32_e32 v17, 0xbfb8aa3b, v12
	v_exp_f32_e32 v20, v17
	v_mul_f32_e32 v17, 0xbfb8aa3b, v13
	v_exp_f32_e32 v21, v17
	s_nop 0
	v_pk_add_f32 v[20:21], v[20:21], 1.0 op_sel_hi:[1,0]
	s_nop 0
	s_nop 0
	v_rcp_f32_e32 v17, v21
	v_pk_mul_f32 v[8:9], v[8:9], v[18:19] op_sel_hi:[1,0]
	v_mul_f32_e32 v13, v13, v17
	v_mul_f32_e32 v21, 0xbfb8aa3b, v8
	v_exp_f32_e32 v22, v21
	v_mul_f32_e32 v21, 0xbfb8aa3b, v9
	v_exp_f32_e32 v23, v21
	v_rcp_f32_e32 v17, v20
	v_pk_add_f32 v[22:23], v[22:23], 1.0 op_sel_hi:[1,0]
	v_mul_f32_e32 v12, v12, v17
	s_nop 0
	v_pk_mul_f32 v[4:5], v[4:5], v[18:19] op_sel_hi:[1,0]
	s_nop 0
	v_pk_mul_f32 v[4:5], v[4:5], v[12:13]
	v_rcp_f32_e32 v12, v23
	s_nop 0
	v_mul_f32_e32 v9, v9, v12
	v_pk_mul_f32 v[12:13], v[14:15], v[18:19] op_sel_hi:[1,0]
	v_mul_f32_e32 v14, 0xbfb8aa3b, v12
	v_mul_f32_e32 v15, 0xbfb8aa3b, v13
	v_exp_f32_e32 v14, v14
	v_exp_f32_e32 v15, v15
	v_rcp_f32_e32 v17, v22
	v_pk_add_f32 v[14:15], v[14:15], 1.0 op_sel_hi:[1,0]
	v_mul_f32_e32 v8, v8, v17
	s_nop 0
	v_pk_mul_f32 v[0:1], v[0:1], v[18:19] op_sel_hi:[1,0]
	s_nop 0
	v_pk_mul_f32 v[8:9], v[0:1], v[8:9]
	v_rcp_f32_e32 v0, v15
	v_pk_mul_f32 v[10:11], v[10:11], v[18:19] op_sel_hi:[1,0]
	v_mul_f32_e32 v1, v13, v0
	v_mul_f32_e32 v15, 0xbfb8aa3b, v10
	v_exp_f32_e32 v20, v15
	v_mul_f32_e32 v15, 0xbfb8aa3b, v11
	v_exp_f32_e32 v21, v15
	v_rcp_f32_e32 v0, v14
	v_pk_add_f32 v[20:21], v[20:21], 1.0 op_sel_hi:[1,0]
	v_mul_f32_e32 v0, v12, v0
	v_pk_mul_f32 v[6:7], v[6:7], v[18:19] op_sel_hi:[1,0]
	v_pk_mul_f32 v[6:7], v[6:7], v[0:1]
	v_pk_mul_f32 v[2:3], v[2:3], v[18:19] op_sel_hi:[1,0]
	v_rcp_f32_e32 v1, v21
	v_rcp_f32_e32 v0, v20
	v_mul_f32_e32 v1, v11, v1
	v_mul_f32_e32 v0, v10, v0
	v_pk_mul_f32 v[10:11], v[2:3], v[0:1]
	v_cvt_pk_bf16_f32 v0, v4, v5
	v_mad_i64_i32 v[4:5], s[6:7], v16, s64, v[112:113]
	v_cvt_pk_bf16_f32 v1, v6, v7
	v_cvt_pk_bf16_f32 v2, v8, v9
	v_cvt_pk_bf16_f32 v3, v10, v11
	v_lshl_add_u64 v[4:5], v[4:5], 0, v[114:115]
	s_andn2_b64 vcc, exec, s[4:5]
	s_mov_b64 s[4:5], -1
	global_store_dwordx4 v[4:5], v[0:3], off
	s_cbranch_vccnz .LBB0_683
	s_andn2_b64 vcc, exec, s[22:23]
	s_cbranch_vccnz .LBB0_682
	s_barrier
	s_branch .LBB0_682

.LBB0_5693:
	v_ashrrev_i32_e32 v51, 1, v50
	v_add_u32_e32 v180, s51, v51
	v_ashrrev_i32_e32 v181, 31, v180
	v_add_u32_e32 v52, 0x200, v50
	v_mad_u64_u32 v[176:177], s[6:7], v51, s30, v[38:39]
	v_mad_i64_i32 v[182:183], s[6:7], v180, s48, v[42:43]
	v_lshl_add_u64 v[180:181], v[180:181], 2, s[20:21]
	v_cmp_lt_i32_e32 vcc, s49, v50
	v_mov_b32_e32 v50, v52
	ds_read_b128 v[52:55], v176
	ds_read_b128 v[56:59], v176 offset:16
	ds_read_b128 v[60:63], v176 offset:64
	ds_read_b128 v[64:67], v176 offset:80
	ds_read_b128 v[68:71], v176 offset:9216
	ds_read_b128 v[72:75], v176 offset:9232
	ds_read_b128 v[76:79], v176 offset:9280
	ds_read_b128 v[80:83], v176 offset:9296
	ds_read_b128 v[84:87], v176 offset:18432
	ds_read_b128 v[88:91], v176 offset:18448
	ds_read_b128 v[92:95], v176 offset:18496
	ds_read_b128 v[96:99], v176 offset:18512
	ds_read_b128 v[100:103], v176 offset:27648
	ds_read_b128 v[104:107], v176 offset:27664
	ds_read_b128 v[108:111], v176 offset:27712
	ds_read_b128 v[112:115], v176 offset:27728
	ds_read_b128 v[116:119], v176 offset:36864
	ds_read_b128 v[120:123], v176 offset:36880
	ds_read_b128 v[124:127], v176 offset:36928
	ds_read_b128 v[128:131], v176 offset:36944
	ds_read_b128 v[132:135], v176 offset:46080
	ds_read_b128 v[136:139], v176 offset:46096
	ds_read_b128 v[140:143], v176 offset:46144
	ds_read_b128 v[144:147], v176 offset:46160
	ds_read_b128 v[148:151], v176 offset:55296
	ds_read_b128 v[152:155], v176 offset:55312
	ds_read_b128 v[156:159], v176 offset:55360
	ds_read_b128 v[160:163], v176 offset:55376
	ds_read_b128 v[164:167], v176 offset:64512
	ds_read_b128 v[168:171], v176 offset:64528
	ds_read_b128 v[172:175], v176 offset:64576
	ds_read_b128 v[176:179], v176 offset:64592
	global_load_dword v51, v[180:181], off
	s_waitcnt lgkmcnt(14)
	v_pk_add_f32 v[52:53], v[52:53], 0 op_sel_hi:[1,0]
	s_or_b64 s[40:41], vcc, s[40:41]
	v_pk_add_f32 v[52:53], v[52:53], v[68:69]
	v_pk_add_f32 v[54:55], v[54:55], 0 op_sel_hi:[1,0]
	v_pk_add_f32 v[58:59], v[58:59], 0 op_sel_hi:[1,0]
	v_pk_add_f32 v[56:57], v[56:57], 0 op_sel_hi:[1,0]
	v_pk_add_f32 v[62:63], v[62:63], 0 op_sel_hi:[1,0]
	v_pk_add_f32 v[60:61], v[60:61], 0 op_sel_hi:[1,0]
	v_pk_add_f32 v[66:67], v[66:67], 0 op_sel_hi:[1,0]
	v_pk_add_f32 v[64:65], v[64:65], 0 op_sel_hi:[1,0]
	v_pk_add_f32 v[54:55], v[54:55], v[70:71]
	v_pk_add_f32 v[58:59], v[58:59], v[74:75]
	v_pk_add_f32 v[56:57], v[56:57], v[72:73]
	v_pk_add_f32 v[62:63], v[62:63], v[78:79]
	v_pk_add_f32 v[60:61], v[60:61], v[76:77]
	v_pk_add_f32 v[66:67], v[66:67], v[82:83]
	v_pk_add_f32 v[64:65], v[64:65], v[80:81]
	v_pk_add_f32 v[52:53], v[52:53], v[84:85]
	v_pk_add_f32 v[54:55], v[54:55], v[86:87]
	v_pk_add_f32 v[58:59], v[58:59], v[90:91]
	v_pk_add_f32 v[56:57], v[56:57], v[88:89]
	v_pk_add_f32 v[62:63], v[62:63], v[94:95]
	v_pk_add_f32 v[60:61], v[60:61], v[92:93]
	v_pk_add_f32 v[66:67], v[66:67], v[98:99]
	v_pk_add_f32 v[64:65], v[64:65], v[96:97]
	v_pk_add_f32 v[52:53], v[52:53], v[100:101]
	v_pk_add_f32 v[54:55], v[54:55], v[102:103]
	v_pk_add_f32 v[58:59], v[58:59], v[106:107]
	v_pk_add_f32 v[56:57], v[56:57], v[104:105]
	v_pk_add_f32 v[62:63], v[62:63], v[110:111]
	v_pk_add_f32 v[60:61], v[60:61], v[108:109]
	v_pk_add_f32 v[66:67], v[66:67], v[114:115]
	v_pk_add_f32 v[64:65], v[64:65], v[112:113]
	v_pk_add_f32 v[52:53], v[52:53], v[116:117]
	v_pk_add_f32 v[54:55], v[54:55], v[118:119]
	v_pk_add_f32 v[58:59], v[58:59], v[122:123]
	v_pk_add_f32 v[56:57], v[56:57], v[120:121]
	s_waitcnt lgkmcnt(13)
	v_pk_add_f32 v[62:63], v[62:63], v[126:127]
	v_pk_add_f32 v[60:61], v[60:61], v[124:125]
	s_waitcnt lgkmcnt(12)
	v_pk_add_f32 v[66:67], v[66:67], v[130:131]
	v_pk_add_f32 v[64:65], v[64:65], v[128:129]
	s_waitcnt lgkmcnt(11)
	v_pk_add_f32 v[52:53], v[52:53], v[132:133]
	v_pk_add_f32 v[54:55], v[54:55], v[134:135]
	s_waitcnt lgkmcnt(10)
	v_pk_add_f32 v[58:59], v[58:59], v[138:139]
	v_pk_add_f32 v[56:57], v[56:57], v[136:137]
	s_waitcnt lgkmcnt(9)
	v_pk_add_f32 v[62:63], v[62:63], v[142:143]
	v_pk_add_f32 v[60:61], v[60:61], v[140:141]
	s_waitcnt lgkmcnt(8)
	v_pk_add_f32 v[66:67], v[66:67], v[146:147]
	v_pk_add_f32 v[64:65], v[64:65], v[144:145]
	s_waitcnt lgkmcnt(7)
	v_pk_add_f32 v[52:53], v[52:53], v[148:149]
	v_pk_add_f32 v[54:55], v[54:55], v[150:151]
	s_waitcnt lgkmcnt(6)
	v_pk_add_f32 v[58:59], v[58:59], v[154:155]
	v_pk_add_f32 v[56:57], v[56:57], v[152:153]
	s_waitcnt lgkmcnt(5)
	v_pk_add_f32 v[62:63], v[62:63], v[158:159]
	v_pk_add_f32 v[60:61], v[60:61], v[156:157]
	s_waitcnt lgkmcnt(4)
	v_pk_add_f32 v[66:67], v[66:67], v[162:163]
	v_pk_add_f32 v[64:65], v[64:65], v[160:161]
	s_waitcnt lgkmcnt(3)
	v_pk_add_f32 v[52:53], v[52:53], v[164:165]
	v_pk_add_f32 v[54:55], v[54:55], v[166:167]
	s_waitcnt lgkmcnt(2)
	v_pk_add_f32 v[58:59], v[58:59], v[170:171]
	v_pk_add_f32 v[56:57], v[56:57], v[168:169]
	s_waitcnt lgkmcnt(1)
	v_pk_add_f32 v[62:63], v[62:63], v[174:175]
	v_pk_add_f32 v[60:61], v[60:61], v[172:173]
	s_waitcnt lgkmcnt(0)
	v_pk_add_f32 v[66:67], v[66:67], v[178:179]
	v_pk_add_f32 v[64:65], v[64:65], v[176:177]
	s_waitcnt vmcnt(0)
	v_fmamk_f32 v51, v51, 0x3a000000, v45
	v_mul_f32_e32 v68, 0x4b800000, v51
	v_cmp_gt_f32_e32 vcc, s47, v51
	s_nop 1
	v_cndmask_b32_e32 v51, v51, v68, vcc
	v_rsq_f32_e32 v51, v51
	s_nop 0
	v_mul_f32_e32 v68, 0x45800000, v51
	v_cndmask_b32_e32 v68, v51, v68, vcc
	v_pk_mul_f32 v[52:53], v[52:53], v[68:69] op_sel_hi:[1,0]
	v_pk_mul_f32 v[60:61], v[60:61], v[68:69] op_sel_hi:[1,0]
	v_pk_mul_f32 v[56:57], v[56:57], v[68:69] op_sel_hi:[1,0]
	v_pk_mul_f32 v[64:65], v[64:65], v[68:69] op_sel_hi:[1,0]
	v_pk_mul_f32 v[54:55], v[54:55], v[68:69] op_sel_hi:[1,0]
	v_pk_mul_f32 v[62:63], v[62:63], v[68:69] op_sel_hi:[1,0]
	v_pk_mul_f32 v[58:59], v[58:59], v[68:69] op_sel_hi:[1,0]
	v_pk_mul_f32 v[66:67], v[66:67], v[68:69] op_sel_hi:[1,0]
	v_mul_f32_e32 v51, 0xbfb8aa3b, v52
	v_mul_f32_e32 v69, 0xbfb8aa3b, v53
	v_exp_f32_e32 v68, v51
	v_exp_f32_e32 v69, v69
	v_mul_f32_e32 v70, 0xbfb8aa3b, v56
	v_mul_f32_e32 v71, 0xbfb8aa3b, v57
	v_exp_f32_e32 v70, v70
	v_exp_f32_e32 v71, v71
	v_mul_f32_e32 v72, 0xbfb8aa3b, v54
	v_mul_f32_e32 v73, 0xbfb8aa3b, v55
	v_exp_f32_e32 v72, v72
	v_exp_f32_e32 v73, v73
	v_pk_add_f32 v[68:69], v[68:69], 1.0 op_sel_hi:[1,0]
	v_mul_f32_e32 v74, 0xbfb8aa3b, v58
	v_mul_f32_e32 v75, 0xbfb8aa3b, v59
	v_exp_f32_e32 v74, v74
	v_exp_f32_e32 v75, v75
	v_pk_add_f32 v[70:71], v[70:71], 1.0 op_sel_hi:[1,0]
	v_pk_add_f32 v[72:73], v[72:73], 1.0 op_sel_hi:[1,0]
	v_pk_add_f32 v[74:75], v[74:75], 1.0 op_sel_hi:[1,0]
	v_rcp_f32_e32 v51, v69
	s_nop 0
	v_mul_f32_e32 v53, v53, v51
	v_rcp_f32_e32 v51, v68
	s_nop 0
	v_mul_f32_e32 v52, v52, v51
	v_rcp_f32_e32 v51, v71
	s_nop 0
	v_mul_f32_e32 v57, v57, v51
	v_rcp_f32_e32 v51, v70
	v_pk_mul_f32 v[52:53], v[60:61], v[52:53]
	v_mul_f32_e32 v56, v56, v51
	v_rcp_f32_e32 v61, v73
	v_rcp_f32_e32 v51, v72
	v_mul_f32_e32 v61, v55, v61
	v_mul_f32_e32 v60, v54, v51
	v_pk_mul_f32 v[56:57], v[64:65], v[56:57]
	v_rcp_f32_e32 v51, v75
	v_cvt_pk_bf16_f32 v54, v56, v57
	v_mul_f32_e32 v59, v59, v51
	v_pk_mul_f32 v[56:57], v[62:63], v[60:61]
	v_rcp_f32_e32 v51, v74
	v_cvt_pk_bf16_f32 v52, v52, v53
	v_mul_f32_e32 v58, v58, v51
	v_cvt_pk_bf16_f32 v53, v56, v57
	v_pk_mul_f32 v[56:57], v[66:67], v[58:59]
	s_nop 0
	v_cvt_pk_bf16_f32 v55, v56, v57
	global_store_dwordx4 v[182:183], v[52:55], off
	s_andn2_b64 exec, exec, s[40:41]
	s_cbranch_execnz .LBB0_5693

.LBB0_5696:
	v_ashrrev_i32_e32 v3, 1, v2
	v_add_u32_e32 v150, s51, v3
	v_add_u32_e32 v4, 0x200, v2
	v_mad_u64_u32 v[42:43], s[6:7], v3, s30, v[38:39]
	v_ashrrev_i32_e32 v151, 31, v150
	v_cmp_lt_i32_e32 vcc, s49, v2
	v_mov_b32_e32 v2, v4
	ds_read_b128 v[4:7], v42
	ds_read_b128 v[8:11], v42 offset:16
	ds_read_b128 v[12:15], v42 offset:64
	ds_read_b128 v[16:19], v42 offset:80
	ds_read_b128 v[20:23], v42 offset:9216
	ds_read_b128 v[24:27], v42 offset:9232
	ds_read_b128 v[28:31], v42 offset:9280
	ds_read_b128 v[50:53], v42 offset:9296
	ds_read_b128 v[54:57], v42 offset:18432
	ds_read_b128 v[58:61], v42 offset:18448
	ds_read_b128 v[62:65], v42 offset:18496
	ds_read_b128 v[66:69], v42 offset:18512
	ds_read_b128 v[70:73], v42 offset:27648
	ds_read_b128 v[74:77], v42 offset:27664
	ds_read_b128 v[78:81], v42 offset:27712
	ds_read_b128 v[82:85], v42 offset:27728
	ds_read_b128 v[86:89], v42 offset:36864
	ds_read_b128 v[90:93], v42 offset:36880
	ds_read_b128 v[94:97], v42 offset:36928
	ds_read_b128 v[98:101], v42 offset:36944
	ds_read_b128 v[102:105], v42 offset:46080
	ds_read_b128 v[106:109], v42 offset:46096
	ds_read_b128 v[110:113], v42 offset:46144
	ds_read_b128 v[114:117], v42 offset:46160
	ds_read_b128 v[118:121], v42 offset:55296
	ds_read_b128 v[122:125], v42 offset:55312
	ds_read_b128 v[126:129], v42 offset:55360
	ds_read_b128 v[130:133], v42 offset:55376
	ds_read_b128 v[134:137], v42 offset:64512
	ds_read_b128 v[138:141], v42 offset:64528
	ds_read_b128 v[142:145], v42 offset:64576
	ds_read_b128 v[146:149], v42 offset:64592
	v_mad_i64_i32 v[42:43], s[6:7], v150, s48, v[0:1]
	v_lshl_add_u64 v[150:151], v[150:151], 2, s[20:21]
	global_load_dword v3, v[150:151], off
	s_waitcnt lgkmcnt(14)
	v_pk_add_f32 v[4:5], v[4:5], 0 op_sel_hi:[1,0]
	s_or_b64 s[36:37], vcc, s[36:37]
	v_pk_add_f32 v[4:5], v[4:5], v[20:21]
	v_pk_add_f32 v[6:7], v[6:7], 0 op_sel_hi:[1,0]
	v_pk_add_f32 v[10:11], v[10:11], 0 op_sel_hi:[1,0]
	v_pk_add_f32 v[8:9], v[8:9], 0 op_sel_hi:[1,0]
	v_pk_add_f32 v[14:15], v[14:15], 0 op_sel_hi:[1,0]
	v_pk_add_f32 v[12:13], v[12:13], 0 op_sel_hi:[1,0]
	v_pk_add_f32 v[18:19], v[18:19], 0 op_sel_hi:[1,0]
	v_pk_add_f32 v[16:17], v[16:17], 0 op_sel_hi:[1,0]
	v_pk_add_f32 v[6:7], v[6:7], v[22:23]
	v_pk_add_f32 v[10:11], v[10:11], v[26:27]
	v_pk_add_f32 v[8:9], v[8:9], v[24:25]
	v_pk_add_f32 v[14:15], v[14:15], v[30:31]
	v_pk_add_f32 v[12:13], v[12:13], v[28:29]
	v_pk_add_f32 v[18:19], v[18:19], v[52:53]
	v_pk_add_f32 v[16:17], v[16:17], v[50:51]
	v_pk_add_f32 v[4:5], v[4:5], v[54:55]
	v_pk_add_f32 v[6:7], v[6:7], v[56:57]
	v_pk_add_f32 v[10:11], v[10:11], v[60:61]
	v_pk_add_f32 v[8:9], v[8:9], v[58:59]
	v_pk_add_f32 v[14:15], v[14:15], v[64:65]
	v_pk_add_f32 v[12:13], v[12:13], v[62:63]
	v_pk_add_f32 v[18:19], v[18:19], v[68:69]
	v_pk_add_f32 v[16:17], v[16:17], v[66:67]
	v_pk_add_f32 v[4:5], v[4:5], v[70:71]
	v_pk_add_f32 v[6:7], v[6:7], v[72:73]
	v_pk_add_f32 v[10:11], v[10:11], v[76:77]
	v_pk_add_f32 v[8:9], v[8:9], v[74:75]
	v_pk_add_f32 v[14:15], v[14:15], v[80:81]
	v_pk_add_f32 v[12:13], v[12:13], v[78:79]
	v_pk_add_f32 v[18:19], v[18:19], v[84:85]
	v_pk_add_f32 v[16:17], v[16:17], v[82:83]
	v_pk_add_f32 v[4:5], v[4:5], v[86:87]
	v_pk_add_f32 v[6:7], v[6:7], v[88:89]
	v_pk_add_f32 v[10:11], v[10:11], v[92:93]
	v_pk_add_f32 v[8:9], v[8:9], v[90:91]
	s_waitcnt lgkmcnt(13)
	v_pk_add_f32 v[14:15], v[14:15], v[96:97]
	v_pk_add_f32 v[12:13], v[12:13], v[94:95]
	s_waitcnt lgkmcnt(12)
	v_pk_add_f32 v[18:19], v[18:19], v[100:101]
	v_pk_add_f32 v[16:17], v[16:17], v[98:99]
	s_waitcnt lgkmcnt(11)
	v_pk_add_f32 v[4:5], v[4:5], v[102:103]
	v_pk_add_f32 v[6:7], v[6:7], v[104:105]
	s_waitcnt lgkmcnt(10)
	v_pk_add_f32 v[10:11], v[10:11], v[108:109]
	v_pk_add_f32 v[8:9], v[8:9], v[106:107]
	s_waitcnt lgkmcnt(9)
	v_pk_add_f32 v[14:15], v[14:15], v[112:113]
	v_pk_add_f32 v[12:13], v[12:13], v[110:111]
	s_waitcnt lgkmcnt(8)
	v_pk_add_f32 v[18:19], v[18:19], v[116:117]
	v_pk_add_f32 v[16:17], v[16:17], v[114:115]
	s_waitcnt lgkmcnt(7)
	v_pk_add_f32 v[4:5], v[4:5], v[118:119]
	v_pk_add_f32 v[6:7], v[6:7], v[120:121]
	s_waitcnt lgkmcnt(6)
	v_pk_add_f32 v[10:11], v[10:11], v[124:125]
	v_pk_add_f32 v[8:9], v[8:9], v[122:123]
	s_waitcnt lgkmcnt(5)
	v_pk_add_f32 v[14:15], v[14:15], v[128:129]
	v_pk_add_f32 v[12:13], v[12:13], v[126:127]
	s_waitcnt lgkmcnt(4)
	v_pk_add_f32 v[18:19], v[18:19], v[132:133]
	v_pk_add_f32 v[16:17], v[16:17], v[130:131]
	s_waitcnt lgkmcnt(3)
	v_pk_add_f32 v[4:5], v[4:5], v[134:135]
	v_pk_add_f32 v[6:7], v[6:7], v[136:137]
	s_waitcnt lgkmcnt(2)
	v_pk_add_f32 v[10:11], v[10:11], v[140:141]
	v_pk_add_f32 v[8:9], v[8:9], v[138:139]
	s_waitcnt lgkmcnt(1)
	v_pk_add_f32 v[14:15], v[14:15], v[144:145]
	v_pk_add_f32 v[12:13], v[12:13], v[142:143]
	s_waitcnt lgkmcnt(0)
	v_pk_add_f32 v[18:19], v[18:19], v[148:149]
	v_pk_add_f32 v[16:17], v[16:17], v[146:147]
	s_waitcnt vmcnt(0)
	v_fmamk_f32 v3, v3, 0x3a000000, v45
	v_mul_f32_e32 v20, 0x4b800000, v3
	v_cmp_gt_f32_e32 vcc, s47, v3
	s_nop 1
	v_cndmask_b32_e32 v3, v3, v20, vcc
	v_rsq_f32_e32 v3, v3
	s_nop 0
	v_mul_f32_e32 v20, 0x45800000, v3
	v_cndmask_b32_e32 v20, v3, v20, vcc
	v_pk_mul_f32 v[4:5], v[4:5], v[20:21] op_sel_hi:[1,0]
	v_pk_mul_f32 v[12:13], v[12:13], v[20:21] op_sel_hi:[1,0]
	v_pk_mul_f32 v[8:9], v[8:9], v[20:21] op_sel_hi:[1,0]
	v_pk_mul_f32 v[16:17], v[16:17], v[20:21] op_sel_hi:[1,0]
	v_pk_mul_f32 v[6:7], v[6:7], v[20:21] op_sel_hi:[1,0]
	v_pk_mul_f32 v[14:15], v[14:15], v[20:21] op_sel_hi:[1,0]
	v_pk_mul_f32 v[10:11], v[10:11], v[20:21] op_sel_hi:[1,0]
	v_pk_mul_f32 v[18:19], v[18:19], v[20:21] op_sel_hi:[1,0]
	v_mul_f32_e32 v3, 0xbfb8aa3b, v4
	v_mul_f32_e32 v21, 0xbfb8aa3b, v5
	v_exp_f32_e32 v20, v3
	v_exp_f32_e32 v21, v21
	v_mul_f32_e32 v22, 0xbfb8aa3b, v8
	v_mul_f32_e32 v23, 0xbfb8aa3b, v9
	v_exp_f32_e32 v22, v22
	v_exp_f32_e32 v23, v23
	v_mul_f32_e32 v24, 0xbfb8aa3b, v6
	v_mul_f32_e32 v25, 0xbfb8aa3b, v7
	v_exp_f32_e32 v24, v24
	v_exp_f32_e32 v25, v25
	v_pk_add_f32 v[20:21], v[20:21], 1.0 op_sel_hi:[1,0]
	v_mul_f32_e32 v26, 0xbfb8aa3b, v10
	v_mul_f32_e32 v27, 0xbfb8aa3b, v11
	v_exp_f32_e32 v26, v26
	v_exp_f32_e32 v27, v27
	v_pk_add_f32 v[22:23], v[22:23], 1.0 op_sel_hi:[1,0]
	v_pk_add_f32 v[24:25], v[24:25], 1.0 op_sel_hi:[1,0]
	v_pk_add_f32 v[26:27], v[26:27], 1.0 op_sel_hi:[1,0]
	v_rcp_f32_e32 v3, v21
	s_nop 0
	v_mul_f32_e32 v5, v5, v3
	v_rcp_f32_e32 v3, v20
	s_nop 0
	v_mul_f32_e32 v4, v4, v3
	v_rcp_f32_e32 v3, v23
	s_nop 0
	v_mul_f32_e32 v9, v9, v3
	v_rcp_f32_e32 v3, v22
	v_pk_mul_f32 v[4:5], v[12:13], v[4:5]
	v_mul_f32_e32 v8, v8, v3
	v_rcp_f32_e32 v13, v25
	v_rcp_f32_e32 v3, v24
	v_mul_f32_e32 v13, v7, v13
	v_mul_f32_e32 v12, v6, v3
	v_pk_mul_f32 v[8:9], v[16:17], v[8:9]
	v_rcp_f32_e32 v3, v27
	v_cvt_pk_bf16_f32 v6, v8, v9
	v_mul_f32_e32 v11, v11, v3
	v_pk_mul_f32 v[8:9], v[14:15], v[12:13]
	v_rcp_f32_e32 v3, v26
	v_cvt_pk_bf16_f32 v4, v4, v5
	v_mul_f32_e32 v10, v10, v3
	v_cvt_pk_bf16_f32 v5, v8, v9
	v_pk_mul_f32 v[8:9], v[18:19], v[10:11]
	s_nop 0
	v_cvt_pk_bf16_f32 v7, v8, v9
	global_store_dwordx4 v[42:43], v[4:7], off offset:32
	s_andn2_b64 exec, exec, s[36:37]
	s_cbranch_execnz .LBB0_5696
	s_branch .LBB0_5690

; DI float silu(float x) { return x / (1.f + __expf(-x)); }
; DI bf16x8 pack8(const f32x4& a, const f32x4& b) { v4u w; w.x = pk2(a[0], a[1]); w.y = pk2(a[2], a[3]); w.z = pk2(b[0], b[1]); w.w = pk2(b[2], b[3]); return __builtin_bit_cast(bf16x8, w); }
;     DI void operator()(const f32x4 (&acc)[2][2][4][2], const pg8::Unit& u, int wr, int wc, int fr, int fq) const {
;     ...
;         EPI_LOOP_BEGIN
;             const float rs = rsqrtf(ssq[row] * (1.f / D) + EPS);
;             f32x4 a = acc[ai][0][m][0], b = acc[ai][0][m][1]; const f32x4 ua = acc[ai][1][m][0], ub = acc[ai][1][m][1];
; #pragma unroll
;             for (int e = 0; e < 4; ++e) { a[e] = silu(a[e] * rs) * (ua[e] * rs); b[e] = silu(b[e] * rs) * (ub[e] * rs); }
;             *(bf16x8*)(hid + (size_t)row * FF + cbase) = pack8(a, b);
;         EPI_LOOP_END
.LBB0_5764:
	v_lshl_add_u32 v144, s6, 8, v150
	v_ashrrev_i32_e32 v145, 31, v144
	v_lshl_add_u64 v[146:147], v[144:145], 2, s[36:37]
	global_load_dword v145, v[146:147], off
	s_waitcnt vmcnt(0)
	v_fmamk_f32 v145, v145, 0x3a000000, v156
	v_mul_f32_e32 v146, 0x4b800000, v145
	v_cmp_gt_f32_e32 vcc, s61, v145
	s_nop 1
	v_cndmask_b32_e32 v145, v145, v146, vcc
	v_rsq_f32_e32 v145, v145
	v_lshl_add_u32 v146, s7, 7, v152
	v_ashrrev_i32_e32 v147, 31, v146
	v_mul_f32_e32 v148, 0x45800000, v145
	v_cndmask_b32_e32 v148, v145, v148, vcc
	v_pk_mul_f32 v[124:125], v[124:125], v[148:149] op_sel_hi:[1,0]
	v_pk_mul_f32 v[120:121], v[120:121], v[148:149] op_sel_hi:[1,0]
	v_mul_f32_e32 v145, 0xbfb8aa3b, v124
	v_mul_f32_e32 v157, 0xbfb8aa3b, v125
	v_exp_f32_e32 v158, v145
	v_exp_f32_e32 v159, v157
	v_mul_f32_e32 v160, 0xbfb8aa3b, v120
	v_mul_f32_e32 v161, 0xbfb8aa3b, v121
	v_exp_f32_e32 v160, v160
	v_exp_f32_e32 v161, v161
	v_pk_mul_f32 v[126:127], v[126:127], v[148:149] op_sel_hi:[1,0]
	v_pk_add_f32 v[158:159], v[158:159], 1.0 op_sel_hi:[1,0]
	v_mul_f32_e32 v162, 0xbfb8aa3b, v126
	v_mul_f32_e32 v163, 0xbfb8aa3b, v127
	v_exp_f32_e32 v162, v162
	v_exp_f32_e32 v163, v163
	v_pk_add_f32 v[160:161], v[160:161], 1.0 op_sel_hi:[1,0]
	v_pk_add_f32 v[162:163], v[162:163], 1.0 op_sel_hi:[1,0]
	v_rcp_f32_e32 v145, v159
	v_pk_mul_f32 v[116:117], v[116:117], v[148:149] op_sel_hi:[1,0]
	v_mul_f32_e32 v125, v125, v145
	v_rcp_f32_e32 v145, v158
	s_nop 0
	v_mul_f32_e32 v124, v124, v145
	v_pk_mul_f32 v[116:117], v[116:117], v[124:125]
	v_pk_mul_f32 v[112:113], v[112:113], v[148:149] op_sel_hi:[1,0]
	v_pk_mul_f32 v[122:123], v[122:123], v[148:149] op_sel_hi:[1,0]
	v_rcp_f32_e32 v145, v161
	v_rcp_f32_e32 v124, v160
	v_mul_f32_e32 v121, v121, v145
	v_mul_f32_e32 v120, v120, v124
	v_pk_mul_f32 v[112:113], v[112:113], v[120:121]
	v_mul_f32_e32 v120, 0xbfb8aa3b, v122
	v_rcp_f32_e32 v121, v163
	v_exp_f32_e32 v124, v120
	v_mul_f32_e32 v121, v127, v121
	v_mul_f32_e32 v120, 0xbfb8aa3b, v123
	v_exp_f32_e32 v125, v120
	s_nop 0
	v_pk_add_f32 v[124:125], v[124:125], 1.0 op_sel_hi:[1,0]
	v_rcp_f32_e32 v120, v162
	v_pk_mul_f32 v[118:119], v[118:119], v[148:149] op_sel_hi:[1,0]
	v_mul_f32_e32 v120, v126, v120
	v_pk_mul_f32 v[114:115], v[114:115], v[148:149] op_sel_hi:[1,0]
	v_pk_mul_f32 v[118:119], v[118:119], v[120:121]
	v_rcp_f32_e32 v120, v125
	v_cvt_pk_bf16_f32 v116, v116, v117
	v_mul_f32_e32 v121, v123, v120
	v_rcp_f32_e32 v120, v124
	s_nop 0
	v_mul_f32_e32 v120, v122, v120
	v_pk_mul_f32 v[114:115], v[114:115], v[120:121]
	v_cvt_pk_bf16_f32 v117, v118, v119
	v_cvt_pk_bf16_f32 v118, v112, v113
	v_mov_b64_e32 v[112:113], s[22:23]
	v_cvt_pk_bf16_f32 v119, v114, v115
	v_mad_i64_i32 v[120:121], s[6:7], v144, s62, v[112:113]
	v_lshlrev_b64 v[114:115], 1, v[146:147]
	v_lshl_add_u64 v[120:121], v[120:121], 0, v[114:115]
	global_store_dwordx4 v[120:121], v[116:119], off
	s_nop 1
	v_or_b32_e32 v116, 16, v144
	v_ashrrev_i32_e32 v117, 31, v116
	v_lshl_add_u64 v[118:119], v[116:117], 2, s[36:37]
	global_load_dword v117, v[118:119], off
	s_waitcnt vmcnt(0)
	v_fmamk_f32 v117, v117, 0x3a000000, v156
	v_mul_f32_e32 v118, 0x4b800000, v117
	v_cmp_gt_f32_e32 vcc, s61, v117
	s_nop 1
	v_cndmask_b32_e32 v117, v117, v118, vcc
	v_rsq_f32_e32 v117, v117
	s_nop 0
	v_mul_f32_e32 v118, 0x45800000, v117
	v_cndmask_b32_e32 v118, v117, v118, vcc
	v_pk_mul_f32 v[108:109], v[108:109], v[118:119] op_sel_hi:[1,0]
	v_pk_mul_f32 v[104:105], v[104:105], v[118:119] op_sel_hi:[1,0]
	v_mul_f32_e32 v117, 0xbfb8aa3b, v108
	v_mul_f32_e32 v119, 0xbfb8aa3b, v109
	v_exp_f32_e32 v120, v117
	v_exp_f32_e32 v121, v119
	v_mul_f32_e32 v122, 0xbfb8aa3b, v104
	v_mul_f32_e32 v123, 0xbfb8aa3b, v105
	v_exp_f32_e32 v122, v122
	v_pk_add_f32 v[120:121], v[120:121], 1.0 op_sel_hi:[1,0]
	v_exp_f32_e32 v123, v123
	s_nop 0
	v_pk_add_f32 v[122:123], v[122:123], 1.0 op_sel_hi:[1,0]
	v_pk_mul_f32 v[100:101], v[100:101], v[118:119] op_sel_hi:[1,0]
	v_rcp_f32_e32 v117, v121
	s_nop 0
	v_mul_f32_e32 v109, v109, v117
	v_rcp_f32_e32 v117, v120
	s_nop 0
	v_mul_f32_e32 v108, v108, v117
	v_pk_mul_f32 v[100:101], v[100:101], v[108:109]
	v_rcp_f32_e32 v108, v123
	s_nop 0
	v_mul_f32_e32 v105, v105, v108
	v_pk_mul_f32 v[108:109], v[110:111], v[118:119] op_sel_hi:[1,0]
	v_mul_f32_e32 v110, 0xbfb8aa3b, v108
	v_mul_f32_e32 v111, 0xbfb8aa3b, v109
	v_exp_f32_e32 v110, v110
	v_exp_f32_e32 v111, v111
	v_rcp_f32_e32 v117, v122
	v_pk_add_f32 v[110:111], v[110:111], 1.0 op_sel_hi:[1,0]
	v_mul_f32_e32 v104, v104, v117
	s_nop 0
	v_pk_mul_f32 v[96:97], v[96:97], v[118:119] op_sel_hi:[1,0]
	s_nop 0
	v_pk_mul_f32 v[104:105], v[96:97], v[104:105]
	v_rcp_f32_e32 v96, v111
	v_pk_mul_f32 v[106:107], v[106:107], v[118:119] op_sel_hi:[1,0]
	v_mul_f32_e32 v97, v109, v96
	v_mul_f32_e32 v111, 0xbfb8aa3b, v106
	v_exp_f32_e32 v120, v111
	v_mul_f32_e32 v111, 0xbfb8aa3b, v107
	v_exp_f32_e32 v121, v111
	v_rcp_f32_e32 v96, v110
	v_pk_add_f32 v[120:121], v[120:121], 1.0 op_sel_hi:[1,0]
	v_mul_f32_e32 v96, v108, v96
	v_pk_mul_f32 v[102:103], v[102:103], v[118:119] op_sel_hi:[1,0]
	v_pk_mul_f32 v[102:103], v[102:103], v[96:97]
	v_pk_mul_f32 v[98:99], v[98:99], v[118:119] op_sel_hi:[1,0]
	v_rcp_f32_e32 v97, v121
	v_rcp_f32_e32 v96, v120
	v_mul_f32_e32 v97, v107, v97
	v_mul_f32_e32 v96, v106, v96
	v_pk_mul_f32 v[106:107], v[98:99], v[96:97]
	v_cvt_pk_bf16_f32 v96, v100, v101
	v_mad_i64_i32 v[100:101], s[6:7], v116, s62, v[112:113]
	v_cvt_pk_bf16_f32 v97, v102, v103
	v_cvt_pk_bf16_f32 v98, v104, v105
	v_cvt_pk_bf16_f32 v99, v106, v107
	v_lshl_add_u64 v[100:101], v[100:101], 0, v[114:115]
	global_store_dwordx4 v[100:101], v[96:99], off
	s_nop 1
	v_or_b32_e32 v96, 32, v144
	v_ashrrev_i32_e32 v97, 31, v96
	v_lshl_add_u64 v[98:99], v[96:97], 2, s[36:37]
	global_load_dword v97, v[98:99], off
	s_waitcnt vmcnt(0)
; DI float silu(float x) { return x / (1.f + __expf(-x)); }
; DI bf16x8 pack8(const f32x4& a, const f32x4& b) { v4u w; w.x = pk2(a[0], a[1]); w.y = pk2(a[2], a[3]); w.z = pk2(b[0], b[1]); w.w = pk2(b[2], b[3]); return __builtin_bit_cast(bf16x8, w); }
;     DI void operator()(const f32x4 (&acc)[2][2][4][2], const pg8::Unit& u, int wr, int wc, int fr, int fq) const {
;     ...
;         EPI_LOOP_BEGIN
;             const float rs = rsqrtf(ssq[row] * (1.f / D) + EPS);
;             f32x4 a = acc[ai][0][m][0], b = acc[ai][0][m][1]; const f32x4 ua = acc[ai][1][m][0], ub = acc[ai][1][m][1];
; #pragma unroll
;             for (int e = 0; e < 4; ++e) { a[e] = silu(a[e] * rs) * (ua[e] * rs); b[e] = silu(b[e] * rs) * (ub[e] * rs); }
;             *(bf16x8*)(hid + (size_t)row * FF + cbase) = pack8(a, b);
;         EPI_LOOP_END
	v_fmamk_f32 v97, v97, 0x3a000000, v156
	v_mul_f32_e32 v98, 0x4b800000, v97
	v_cmp_gt_f32_e32 vcc, s61, v97
	s_nop 1
	v_cndmask_b32_e32 v97, v97, v98, vcc
	v_rsq_f32_e32 v97, v97
	s_nop 0
	v_mul_f32_e32 v98, 0x45800000, v97
	v_cndmask_b32_e32 v98, v97, v98, vcc
	v_pk_mul_f32 v[92:93], v[92:93], v[98:99] op_sel_hi:[1,0]
	s_nop 0
	v_mul_f32_e32 v97, 0xbfb8aa3b, v92
	v_exp_f32_e32 v100, v97
	v_mul_f32_e32 v97, 0xbfb8aa3b, v93
	v_exp_f32_e32 v101, v97
	s_nop 0
	v_pk_add_f32 v[100:101], v[100:101], 1.0 op_sel_hi:[1,0]
	s_nop 0
	s_nop 0
	v_rcp_f32_e32 v97, v101
	v_pk_mul_f32 v[88:89], v[88:89], v[98:99] op_sel_hi:[1,0]
	v_mul_f32_e32 v93, v93, v97
	v_mul_f32_e32 v101, 0xbfb8aa3b, v88
	v_exp_f32_e32 v102, v101
	v_mul_f32_e32 v101, 0xbfb8aa3b, v89
	v_exp_f32_e32 v103, v101
	v_rcp_f32_e32 v97, v100
	v_pk_add_f32 v[102:103], v[102:103], 1.0 op_sel_hi:[1,0]
	v_mul_f32_e32 v92, v92, v97
	s_nop 0
	v_pk_mul_f32 v[84:85], v[84:85], v[98:99] op_sel_hi:[1,0]
	s_nop 0
	v_pk_mul_f32 v[84:85], v[84:85], v[92:93]
	v_rcp_f32_e32 v92, v103
	s_nop 0
	v_mul_f32_e32 v89, v89, v92
	v_pk_mul_f32 v[92:93], v[94:95], v[98:99] op_sel_hi:[1,0]
	v_mul_f32_e32 v94, 0xbfb8aa3b, v92
	v_mul_f32_e32 v95, 0xbfb8aa3b, v93
	v_exp_f32_e32 v94, v94
	v_exp_f32_e32 v95, v95
	v_rcp_f32_e32 v97, v102
	v_pk_add_f32 v[94:95], v[94:95], 1.0 op_sel_hi:[1,0]
	v_mul_f32_e32 v88, v88, v97
	s_nop 0
	v_pk_mul_f32 v[80:81], v[80:81], v[98:99] op_sel_hi:[1,0]
	s_nop 0
	v_pk_mul_f32 v[88:89], v[80:81], v[88:89]
	v_rcp_f32_e32 v80, v95
	v_pk_mul_f32 v[90:91], v[90:91], v[98:99] op_sel_hi:[1,0]
	v_mul_f32_e32 v81, v93, v80
	v_mul_f32_e32 v95, 0xbfb8aa3b, v90
	v_exp_f32_e32 v100, v95
	v_mul_f32_e32 v95, 0xbfb8aa3b, v91
	v_exp_f32_e32 v101, v95
	v_rcp_f32_e32 v80, v94
	v_pk_add_f32 v[100:101], v[100:101], 1.0 op_sel_hi:[1,0]
	v_mul_f32_e32 v80, v92, v80
	v_pk_mul_f32 v[86:87], v[86:87], v[98:99] op_sel_hi:[1,0]
	v_pk_mul_f32 v[86:87], v[86:87], v[80:81]
	v_pk_mul_f32 v[82:83], v[82:83], v[98:99] op_sel_hi:[1,0]
	v_rcp_f32_e32 v81, v101
	v_rcp_f32_e32 v80, v100
	v_mul_f32_e32 v81, v91, v81
	v_mul_f32_e32 v80, v90, v80
	v_pk_mul_f32 v[90:91], v[82:83], v[80:81]
	v_cvt_pk_bf16_f32 v80, v84, v85
	v_mad_i64_i32 v[84:85], s[6:7], v96, s62, v[112:113]
	v_cvt_pk_bf16_f32 v81, v86, v87
	v_cvt_pk_bf16_f32 v82, v88, v89
	v_cvt_pk_bf16_f32 v83, v90, v91
	v_lshl_add_u64 v[84:85], v[84:85], 0, v[114:115]
	global_store_dwordx4 v[84:85], v[80:83], off
	s_nop 1
	v_or_b32_e32 v80, 48, v144
	v_ashrrev_i32_e32 v81, 31, v80
	v_lshl_add_u64 v[82:83], v[80:81], 2, s[36:37]
	global_load_dword v81, v[82:83], off
	s_waitcnt vmcnt(0)
	v_fmamk_f32 v81, v81, 0x3a000000, v156
	v_mul_f32_e32 v82, 0x4b800000, v81
	v_cmp_gt_f32_e32 vcc, s61, v81
	s_nop 1
	v_cndmask_b32_e32 v81, v81, v82, vcc
	v_rsq_f32_e32 v81, v81
	s_nop 0
	v_mul_f32_e32 v82, 0x45800000, v81
	v_cndmask_b32_e32 v82, v81, v82, vcc
	v_pk_mul_f32 v[76:77], v[76:77], v[82:83] op_sel_hi:[1,0]
	s_nop 0
	v_mul_f32_e32 v81, 0xbfb8aa3b, v76
	v_exp_f32_e32 v84, v81
	v_mul_f32_e32 v81, 0xbfb8aa3b, v77
	v_exp_f32_e32 v85, v81
	s_nop 0
	v_pk_add_f32 v[84:85], v[84:85], 1.0 op_sel_hi:[1,0]
	s_nop 0
	s_nop 0
	v_rcp_f32_e32 v81, v85
	v_pk_mul_f32 v[72:73], v[72:73], v[82:83] op_sel_hi:[1,0]
	v_mul_f32_e32 v77, v77, v81
	v_mul_f32_e32 v85, 0xbfb8aa3b, v72
	v_exp_f32_e32 v86, v85
	v_mul_f32_e32 v85, 0xbfb8aa3b, v73
	v_exp_f32_e32 v87, v85
	v_rcp_f32_e32 v81, v84
	v_pk_add_f32 v[86:87], v[86:87], 1.0 op_sel_hi:[1,0]
	v_mul_f32_e32 v76, v76, v81
	s_nop 0
	v_pk_mul_f32 v[68:69], v[68:69], v[82:83] op_sel_hi:[1,0]
	s_nop 0
	v_pk_mul_f32 v[68:69], v[68:69], v[76:77]
	v_rcp_f32_e32 v76, v87
	s_nop 0
	v_mul_f32_e32 v73, v73, v76
	v_pk_mul_f32 v[76:77], v[78:79], v[82:83] op_sel_hi:[1,0]
	v_mul_f32_e32 v78, 0xbfb8aa3b, v76
	v_mul_f32_e32 v79, 0xbfb8aa3b, v77
	v_exp_f32_e32 v78, v78
	v_exp_f32_e32 v79, v79
	v_rcp_f32_e32 v81, v86
	v_pk_add_f32 v[78:79], v[78:79], 1.0 op_sel_hi:[1,0]
	v_mul_f32_e32 v72, v72, v81
	s_nop 0
	v_pk_mul_f32 v[64:65], v[64:65], v[82:83] op_sel_hi:[1,0]
	s_nop 0
	v_pk_mul_f32 v[72:73], v[64:65], v[72:73]
	v_rcp_f32_e32 v64, v79
	v_pk_mul_f32 v[74:75], v[74:75], v[82:83] op_sel_hi:[1,0]
	v_mul_f32_e32 v65, v77, v64
	v_mul_f32_e32 v79, 0xbfb8aa3b, v74
	v_exp_f32_e32 v84, v79
	v_mul_f32_e32 v79, 0xbfb8aa3b, v75
	v_exp_f32_e32 v85, v79
	v_rcp_f32_e32 v64, v78
	v_pk_add_f32 v[84:85], v[84:85], 1.0 op_sel_hi:[1,0]
	v_mul_f32_e32 v64, v76, v64
	v_pk_mul_f32 v[70:71], v[70:71], v[82:83] op_sel_hi:[1,0]
	v_pk_mul_f32 v[70:71], v[70:71], v[64:65]
	v_pk_mul_f32 v[66:67], v[66:67], v[82:83] op_sel_hi:[1,0]
	v_rcp_f32_e32 v65, v85
	v_rcp_f32_e32 v64, v84
	v_mul_f32_e32 v65, v75, v65
	v_mul_f32_e32 v64, v74, v64
	v_pk_mul_f32 v[74:75], v[66:67], v[64:65]
	v_cvt_pk_bf16_f32 v64, v68, v69
	v_mad_i64_i32 v[68:69], s[6:7], v80, s62, v[112:113]
	v_cvt_pk_bf16_f32 v65, v70, v71
	v_cvt_pk_bf16_f32 v66, v72, v73
	v_cvt_pk_bf16_f32 v67, v74, v75
	v_lshl_add_u64 v[68:69], v[68:69], 0, v[114:115]
	global_store_dwordx4 v[68:69], v[64:67], off
	s_nop 1
	v_add_u32_e32 v64, 0x80, v144
	v_ashrrev_i32_e32 v65, 31, v64
	v_lshl_add_u64 v[66:67], v[64:65], 2, s[36:37]
	global_load_dword v65, v[66:67], off
	s_waitcnt vmcnt(0)
; DI float silu(float x) { return x / (1.f + __expf(-x)); }
; DI bf16x8 pack8(const f32x4& a, const f32x4& b) { v4u w; w.x = pk2(a[0], a[1]); w.y = pk2(a[2], a[3]); w.z = pk2(b[0], b[1]); w.w = pk2(b[2], b[3]); return __builtin_bit_cast(bf16x8, w); }
;     DI void operator()(const f32x4 (&acc)[2][2][4][2], const pg8::Unit& u, int wr, int wc, int fr, int fq) const {
;     ...
;         EPI_LOOP_BEGIN
;             const float rs = rsqrtf(ssq[row] * (1.f / D) + EPS);
;             f32x4 a = acc[ai][0][m][0], b = acc[ai][0][m][1]; const f32x4 ua = acc[ai][1][m][0], ub = acc[ai][1][m][1];
; #pragma unroll
;             for (int e = 0; e < 4; ++e) { a[e] = silu(a[e] * rs) * (ua[e] * rs); b[e] = silu(b[e] * rs) * (ub[e] * rs); }
;             *(bf16x8*)(hid + (size_t)row * FF + cbase) = pack8(a, b);
;         EPI_LOOP_END
	v_fmamk_f32 v65, v65, 0x3a000000, v156
	v_mul_f32_e32 v66, 0x4b800000, v65
	v_cmp_gt_f32_e32 vcc, s61, v65
	s_nop 1
	v_cndmask_b32_e32 v65, v65, v66, vcc
	v_rsq_f32_e32 v65, v65
	s_nop 0
	v_mul_f32_e32 v66, 0x45800000, v65
	v_cndmask_b32_e32 v66, v65, v66, vcc
	v_pk_mul_f32 v[60:61], v[60:61], v[66:67] op_sel_hi:[1,0]
	s_nop 0
	v_mul_f32_e32 v65, 0xbfb8aa3b, v60
	v_exp_f32_e32 v68, v65
	v_mul_f32_e32 v65, 0xbfb8aa3b, v61
	v_exp_f32_e32 v69, v65
	s_nop 0
	v_pk_add_f32 v[68:69], v[68:69], 1.0 op_sel_hi:[1,0]
	s_nop 0
	s_nop 0
	v_rcp_f32_e32 v65, v69
	v_pk_mul_f32 v[56:57], v[56:57], v[66:67] op_sel_hi:[1,0]
	v_mul_f32_e32 v61, v61, v65
	v_mul_f32_e32 v69, 0xbfb8aa3b, v56
	v_exp_f32_e32 v70, v69
	v_mul_f32_e32 v69, 0xbfb8aa3b, v57
	v_exp_f32_e32 v71, v69
	v_rcp_f32_e32 v65, v68
	v_pk_add_f32 v[70:71], v[70:71], 1.0 op_sel_hi:[1,0]
	v_mul_f32_e32 v60, v60, v65
	s_nop 0
	v_pk_mul_f32 v[52:53], v[52:53], v[66:67] op_sel_hi:[1,0]
	s_nop 0
	v_pk_mul_f32 v[52:53], v[52:53], v[60:61]
	v_rcp_f32_e32 v60, v71
	s_nop 0
	v_mul_f32_e32 v57, v57, v60
	v_pk_mul_f32 v[60:61], v[62:63], v[66:67] op_sel_hi:[1,0]
	v_mul_f32_e32 v62, 0xbfb8aa3b, v60
	v_mul_f32_e32 v63, 0xbfb8aa3b, v61
	v_exp_f32_e32 v62, v62
	v_exp_f32_e32 v63, v63
	v_rcp_f32_e32 v65, v70
	v_pk_add_f32 v[62:63], v[62:63], 1.0 op_sel_hi:[1,0]
	v_mul_f32_e32 v56, v56, v65
	s_nop 0
	v_pk_mul_f32 v[48:49], v[48:49], v[66:67] op_sel_hi:[1,0]
	s_nop 0
	v_pk_mul_f32 v[56:57], v[48:49], v[56:57]
	v_rcp_f32_e32 v48, v63
	v_pk_mul_f32 v[58:59], v[58:59], v[66:67] op_sel_hi:[1,0]
	v_mul_f32_e32 v49, v61, v48
	v_mul_f32_e32 v63, 0xbfb8aa3b, v58
	v_exp_f32_e32 v68, v63
	v_mul_f32_e32 v63, 0xbfb8aa3b, v59
	v_exp_f32_e32 v69, v63
	v_rcp_f32_e32 v48, v62
	v_pk_add_f32 v[68:69], v[68:69], 1.0 op_sel_hi:[1,0]
	v_mul_f32_e32 v48, v60, v48
	v_pk_mul_f32 v[54:55], v[54:55], v[66:67] op_sel_hi:[1,0]
	v_pk_mul_f32 v[54:55], v[54:55], v[48:49]
	v_pk_mul_f32 v[50:51], v[50:51], v[66:67] op_sel_hi:[1,0]
	v_rcp_f32_e32 v49, v69
	v_rcp_f32_e32 v48, v68
	v_mul_f32_e32 v49, v59, v49
	v_mul_f32_e32 v48, v58, v48
	v_pk_mul_f32 v[58:59], v[50:51], v[48:49]
	v_cvt_pk_bf16_f32 v48, v52, v53
	v_mad_i64_i32 v[52:53], s[6:7], v64, s62, v[112:113]
	v_cvt_pk_bf16_f32 v49, v54, v55
	v_cvt_pk_bf16_f32 v50, v56, v57
	v_cvt_pk_bf16_f32 v51, v58, v59
	v_lshl_add_u64 v[52:53], v[52:53], 0, v[114:115]
	global_store_dwordx4 v[52:53], v[48:51], off
	s_nop 1
	v_add_u32_e32 v48, 0x90, v144
	v_ashrrev_i32_e32 v49, 31, v48
	v_lshl_add_u64 v[50:51], v[48:49], 2, s[36:37]
	global_load_dword v49, v[50:51], off
	s_waitcnt vmcnt(0)
	v_fmamk_f32 v49, v49, 0x3a000000, v156
	v_mul_f32_e32 v50, 0x4b800000, v49
	v_cmp_gt_f32_e32 vcc, s61, v49
	s_nop 1
	v_cndmask_b32_e32 v49, v49, v50, vcc
	v_rsq_f32_e32 v49, v49
	s_nop 0
	v_mul_f32_e32 v50, 0x45800000, v49
	v_cndmask_b32_e32 v50, v49, v50, vcc
	v_pk_mul_f32 v[44:45], v[44:45], v[50:51] op_sel_hi:[1,0]
	s_nop 0
	v_mul_f32_e32 v49, 0xbfb8aa3b, v44
	v_exp_f32_e32 v52, v49
	v_mul_f32_e32 v49, 0xbfb8aa3b, v45
	v_exp_f32_e32 v53, v49
	s_nop 0
	v_pk_add_f32 v[52:53], v[52:53], 1.0 op_sel_hi:[1,0]
	s_nop 0
	s_nop 0
	v_rcp_f32_e32 v49, v53
	v_pk_mul_f32 v[40:41], v[40:41], v[50:51] op_sel_hi:[1,0]
	v_mul_f32_e32 v45, v45, v49
	v_mul_f32_e32 v53, 0xbfb8aa3b, v40
	v_exp_f32_e32 v54, v53
	v_mul_f32_e32 v53, 0xbfb8aa3b, v41
	v_exp_f32_e32 v55, v53
	v_rcp_f32_e32 v49, v52
	v_pk_add_f32 v[54:55], v[54:55], 1.0 op_sel_hi:[1,0]
	v_mul_f32_e32 v44, v44, v49
	s_nop 0
	v_pk_mul_f32 v[36:37], v[36:37], v[50:51] op_sel_hi:[1,0]
	s_nop 0
	v_pk_mul_f32 v[36:37], v[36:37], v[44:45]
	v_rcp_f32_e32 v44, v55
	s_nop 0
	v_mul_f32_e32 v41, v41, v44
	v_pk_mul_f32 v[44:45], v[46:47], v[50:51] op_sel_hi:[1,0]
	v_mul_f32_e32 v46, 0xbfb8aa3b, v44
	v_mul_f32_e32 v47, 0xbfb8aa3b, v45
	v_exp_f32_e32 v46, v46
	v_exp_f32_e32 v47, v47
	v_rcp_f32_e32 v49, v54
	v_pk_add_f32 v[46:47], v[46:47], 1.0 op_sel_hi:[1,0]
	v_mul_f32_e32 v40, v40, v49
	s_nop 0
	v_pk_mul_f32 v[32:33], v[32:33], v[50:51] op_sel_hi:[1,0]
	s_nop 0
	v_pk_mul_f32 v[40:41], v[32:33], v[40:41]
	v_rcp_f32_e32 v32, v47
	v_pk_mul_f32 v[42:43], v[42:43], v[50:51] op_sel_hi:[1,0]
	v_mul_f32_e32 v33, v45, v32
	v_mul_f32_e32 v47, 0xbfb8aa3b, v42
	v_exp_f32_e32 v52, v47
	v_mul_f32_e32 v47, 0xbfb8aa3b, v43
	v_exp_f32_e32 v53, v47
	v_rcp_f32_e32 v32, v46
	v_pk_add_f32 v[52:53], v[52:53], 1.0 op_sel_hi:[1,0]
	v_mul_f32_e32 v32, v44, v32
	v_pk_mul_f32 v[38:39], v[38:39], v[50:51] op_sel_hi:[1,0]
	v_pk_mul_f32 v[38:39], v[38:39], v[32:33]
	v_pk_mul_f32 v[34:35], v[34:35], v[50:51] op_sel_hi:[1,0]
	v_rcp_f32_e32 v33, v53
	v_rcp_f32_e32 v32, v52
	v_mul_f32_e32 v33, v43, v33
	v_mul_f32_e32 v32, v42, v32
	v_pk_mul_f32 v[42:43], v[34:35], v[32:33]
	v_cvt_pk_bf16_f32 v32, v36, v37
	v_mad_i64_i32 v[36:37], s[6:7], v48, s62, v[112:113]
	v_cvt_pk_bf16_f32 v33, v38, v39
	v_cvt_pk_bf16_f32 v34, v40, v41
	v_cvt_pk_bf16_f32 v35, v42, v43
	v_lshl_add_u64 v[36:37], v[36:37], 0, v[114:115]
	global_store_dwordx4 v[36:37], v[32:35], off
	s_nop 1
	v_add_u32_e32 v32, 0xa0, v144
	v_ashrrev_i32_e32 v33, 31, v32
	v_lshl_add_u64 v[34:35], v[32:33], 2, s[36:37]
	global_load_dword v33, v[34:35], off
	s_waitcnt vmcnt(0)
; #define PG8_BAR __builtin_amdgcn_s_barrier()
; DI float silu(float x) { return x / (1.f + __expf(-x)); }
; DI bf16x8 pack8(const f32x4& a, const f32x4& b) { v4u w; w.x = pk2(a[0], a[1]); w.y = pk2(a[2], a[3]); w.z = pk2(b[0], b[1]); w.w = pk2(b[2], b[3]); return __builtin_bit_cast(bf16x8, w); }
; template <class Epi, class Sched, bool ALIGN_EPI = false, bool SP2 = false>
; __device__ __forceinline__ void gemm_phase(PG8_LAS unsigned char* lds, const Gemm g, const Sched& S, const Epi& E, const int wid  ) {
;     ...
;         if constexpr (ALIGN_EPI) { if (wr == 0) PG8_BAR; }
;         if constexpr (!Epi::AFTER_DRAIN) { E(acc, cur, wr, wc, fr, fq); S.done(cur); }
;         if (!has_next) break;
; #pragma unroll
;         for (int a = 0; a < 2; ++a)
; #pragma unroll
;             for (int b = 0; b < 2; ++b)
; #pragma unroll
;                 for (int m = 0; m < 4; ++m)
; #pragma unroll
;                     for (int n = 0; n < 2; ++n) acc[a][b][m][n] = (f32x4){0.f, 0.f, 0.f, 0.f};
;         cur = nxt; cA = nA; cB = nB; ++ui;
;         if constexpr (ALIGN_EPI) { if (wr == 1) PG8_BAR; }
;     DI void operator()(const f32x4 (&acc)[2][2][4][2], const pg8::Unit& u, int wr, int wc, int fr, int fq) const {
;     ...
;         EPI_LOOP_BEGIN
;             const float rs = rsqrtf(ssq[row] * (1.f / D) + EPS);
;             f32x4 a = acc[ai][0][m][0], b = acc[ai][0][m][1]; const f32x4 ua = acc[ai][1][m][0], ub = acc[ai][1][m][1];
; #pragma unroll
;             for (int e = 0; e < 4; ++e) { a[e] = silu(a[e] * rs) * (ua[e] * rs); b[e] = silu(b[e] * rs) * (ub[e] * rs); }
;             *(bf16x8*)(hid + (size_t)row * FF + cbase) = pack8(a, b);
;         EPI_LOOP_END
	v_fmamk_f32 v33, v33, 0x3a000000, v156
	v_mul_f32_e32 v34, 0x4b800000, v33
	v_cmp_gt_f32_e32 vcc, s61, v33
	s_nop 1
	v_cndmask_b32_e32 v33, v33, v34, vcc
	v_rsq_f32_e32 v33, v33
	s_nop 0
	v_mul_f32_e32 v34, 0x45800000, v33
	v_cndmask_b32_e32 v34, v33, v34, vcc
	v_pk_mul_f32 v[28:29], v[28:29], v[34:35] op_sel_hi:[1,0]
	s_nop 0
	v_mul_f32_e32 v33, 0xbfb8aa3b, v28
	v_exp_f32_e32 v36, v33
	v_mul_f32_e32 v33, 0xbfb8aa3b, v29
	v_exp_f32_e32 v37, v33
	s_nop 0
	v_pk_add_f32 v[36:37], v[36:37], 1.0 op_sel_hi:[1,0]
	s_nop 0
	s_nop 0
	v_rcp_f32_e32 v33, v37
	v_pk_mul_f32 v[24:25], v[24:25], v[34:35] op_sel_hi:[1,0]
	v_mul_f32_e32 v29, v29, v33
	v_mul_f32_e32 v37, 0xbfb8aa3b, v24
	v_exp_f32_e32 v38, v37
	v_mul_f32_e32 v37, 0xbfb8aa3b, v25
	v_exp_f32_e32 v39, v37
	v_rcp_f32_e32 v33, v36
	v_pk_add_f32 v[38:39], v[38:39], 1.0 op_sel_hi:[1,0]
	v_mul_f32_e32 v28, v28, v33
	s_nop 0
	v_pk_mul_f32 v[20:21], v[20:21], v[34:35] op_sel_hi:[1,0]
	s_nop 0
	v_pk_mul_f32 v[20:21], v[20:21], v[28:29]
	v_rcp_f32_e32 v28, v39
	s_nop 0
	v_mul_f32_e32 v25, v25, v28
	v_pk_mul_f32 v[28:29], v[30:31], v[34:35] op_sel_hi:[1,0]
	v_mul_f32_e32 v30, 0xbfb8aa3b, v28
	v_mul_f32_e32 v31, 0xbfb8aa3b, v29
	v_exp_f32_e32 v30, v30
	v_exp_f32_e32 v31, v31
	v_rcp_f32_e32 v33, v38
	v_pk_add_f32 v[30:31], v[30:31], 1.0 op_sel_hi:[1,0]
	v_mul_f32_e32 v24, v24, v33
	s_nop 0
	v_pk_mul_f32 v[16:17], v[16:17], v[34:35] op_sel_hi:[1,0]
	s_nop 0
	v_pk_mul_f32 v[24:25], v[16:17], v[24:25]
	v_rcp_f32_e32 v16, v31
	v_pk_mul_f32 v[26:27], v[26:27], v[34:35] op_sel_hi:[1,0]
	v_mul_f32_e32 v17, v29, v16
	v_mul_f32_e32 v31, 0xbfb8aa3b, v26
	v_exp_f32_e32 v36, v31
	v_mul_f32_e32 v31, 0xbfb8aa3b, v27
	v_exp_f32_e32 v37, v31
	v_rcp_f32_e32 v16, v30
	v_pk_add_f32 v[36:37], v[36:37], 1.0 op_sel_hi:[1,0]
	v_mul_f32_e32 v16, v28, v16
	v_pk_mul_f32 v[22:23], v[22:23], v[34:35] op_sel_hi:[1,0]
	v_pk_mul_f32 v[22:23], v[22:23], v[16:17]
	v_pk_mul_f32 v[18:19], v[18:19], v[34:35] op_sel_hi:[1,0]
	v_rcp_f32_e32 v17, v37
	v_rcp_f32_e32 v16, v36
	v_mul_f32_e32 v17, v27, v17
	v_mul_f32_e32 v16, v26, v16
	v_pk_mul_f32 v[26:27], v[18:19], v[16:17]
	v_cvt_pk_bf16_f32 v16, v20, v21
	v_mad_i64_i32 v[20:21], s[6:7], v32, s62, v[112:113]
	v_cvt_pk_bf16_f32 v17, v22, v23
	v_cvt_pk_bf16_f32 v18, v24, v25
	v_cvt_pk_bf16_f32 v19, v26, v27
	v_lshl_add_u64 v[20:21], v[20:21], 0, v[114:115]
	global_store_dwordx4 v[20:21], v[16:19], off
	s_nop 1
	v_add_u32_e32 v16, 0xb0, v144
	v_ashrrev_i32_e32 v17, 31, v16
	v_lshl_add_u64 v[18:19], v[16:17], 2, s[36:37]
	global_load_dword v17, v[18:19], off
	s_waitcnt vmcnt(0)
	v_fmamk_f32 v17, v17, 0x3a000000, v156
	v_mul_f32_e32 v18, 0x4b800000, v17
	v_cmp_gt_f32_e32 vcc, s61, v17
	s_nop 1
	v_cndmask_b32_e32 v17, v17, v18, vcc
	v_rsq_f32_e32 v17, v17
	s_nop 0
	v_mul_f32_e32 v18, 0x45800000, v17
	v_cndmask_b32_e32 v18, v17, v18, vcc
	v_pk_mul_f32 v[12:13], v[12:13], v[18:19] op_sel_hi:[1,0]
	s_nop 0
	v_mul_f32_e32 v17, 0xbfb8aa3b, v12
	v_exp_f32_e32 v20, v17
	v_mul_f32_e32 v17, 0xbfb8aa3b, v13
	v_exp_f32_e32 v21, v17
	s_nop 0
	v_pk_add_f32 v[20:21], v[20:21], 1.0 op_sel_hi:[1,0]
	s_nop 0
	s_nop 0
	v_rcp_f32_e32 v17, v21
	v_pk_mul_f32 v[8:9], v[8:9], v[18:19] op_sel_hi:[1,0]
	v_mul_f32_e32 v13, v13, v17
	v_mul_f32_e32 v21, 0xbfb8aa3b, v8
	v_exp_f32_e32 v22, v21
	v_mul_f32_e32 v21, 0xbfb8aa3b, v9
	v_exp_f32_e32 v23, v21
	v_rcp_f32_e32 v17, v20
	v_pk_add_f32 v[22:23], v[22:23], 1.0 op_sel_hi:[1,0]
	v_mul_f32_e32 v12, v12, v17
	s_nop 0
	v_pk_mul_f32 v[4:5], v[4:5], v[18:19] op_sel_hi:[1,0]
	s_nop 0
	v_pk_mul_f32 v[4:5], v[4:5], v[12:13]
	v_rcp_f32_e32 v12, v23
	s_nop 0
	v_mul_f32_e32 v9, v9, v12
	v_pk_mul_f32 v[12:13], v[14:15], v[18:19] op_sel_hi:[1,0]
	v_mul_f32_e32 v14, 0xbfb8aa3b, v12
	v_mul_f32_e32 v15, 0xbfb8aa3b, v13
	v_exp_f32_e32 v14, v14
	v_exp_f32_e32 v15, v15
	v_rcp_f32_e32 v17, v22
	v_pk_add_f32 v[14:15], v[14:15], 1.0 op_sel_hi:[1,0]
	v_mul_f32_e32 v8, v8, v17
	s_nop 0
	v_pk_mul_f32 v[0:1], v[0:1], v[18:19] op_sel_hi:[1,0]
	s_nop 0
	v_pk_mul_f32 v[8:9], v[0:1], v[8:9]
	v_rcp_f32_e32 v0, v15
	v_pk_mul_f32 v[10:11], v[10:11], v[18:19] op_sel_hi:[1,0]
	v_mul_f32_e32 v1, v13, v0
	v_mul_f32_e32 v15, 0xbfb8aa3b, v10
	v_exp_f32_e32 v20, v15
	v_mul_f32_e32 v15, 0xbfb8aa3b, v11
	v_exp_f32_e32 v21, v15
	v_rcp_f32_e32 v0, v14
	v_pk_add_f32 v[20:21], v[20:21], 1.0 op_sel_hi:[1,0]
	v_mul_f32_e32 v0, v12, v0
	v_pk_mul_f32 v[6:7], v[6:7], v[18:19] op_sel_hi:[1,0]
	v_pk_mul_f32 v[6:7], v[6:7], v[0:1]
	v_pk_mul_f32 v[2:3], v[2:3], v[18:19] op_sel_hi:[1,0]
	v_rcp_f32_e32 v1, v21
	v_rcp_f32_e32 v0, v20
	v_mul_f32_e32 v1, v11, v1
	v_mul_f32_e32 v0, v10, v0
	v_pk_mul_f32 v[10:11], v[2:3], v[0:1]
	v_cvt_pk_bf16_f32 v0, v4, v5
	v_mad_i64_i32 v[4:5], s[6:7], v16, s62, v[112:113]
	v_cvt_pk_bf16_f32 v1, v6, v7
	v_cvt_pk_bf16_f32 v2, v8, v9
	v_cvt_pk_bf16_f32 v3, v10, v11
	v_lshl_add_u64 v[4:5], v[4:5], 0, v[114:115]
	s_andn2_b64 vcc, exec, s[4:5]
	s_mov_b64 s[4:5], -1
	global_store_dwordx4 v[4:5], v[0:3], off
	s_cbranch_vccnz .LBB0_5757
	s_andn2_b64 vcc, exec, s[20:21]
	s_cbranch_vccnz .LBB0_5756
	s_barrier
	s_branch .LBB0_5756
